# duplicate s_waitcnt lgkmcnt(0) before each MFMA block removed (on top of no-setprio)
# speedup vs baseline: 1.0104x; 1.0104x over previous
; #define PG8_STAGE(bufoff, gbase, voff) do { _Pragma("unroll") for (int _i = 0; _i < 2; ++_i) \
;         __builtin_amdgcn_global_load_lds((const unsigned*)((const char*)(gbase) + (voff)[_i]), (LAS unsigned*)(lds + (bufoff) + ldsw + _i * 8192), 16, 0, 0); } while (0)
; #define PG8_LDA(dst, b, h) do { _Pragma("unroll") for (int m = 0; m < 4; ++m) _Pragma("unroll") for (int k = 0; k < 2; ++k) dst[m][k] = *(const LAS h8*)(lds + PG8_SA(b, h) + aoff + m * 2048 + k * 1024); } while (0)
; #define PG8_LDB(dst, b, h) do { _Pragma("unroll") for (int n = 0; n < 2; ++n) _Pragma("unroll") for (int k = 0; k < 2; ++k) dst[n][k] = *(const LAS h8*)(lds + PG8_SB(b, h) + boff + n * 2048 + k * 1024); } while (0)
; #define PG8_WAIT_V(n) asm volatile("s_waitcnt vmcnt(" #n ")" ::: "memory")
; #define PG8_WAIT_L(n) asm volatile("s_waitcnt lgkmcnt(" #n ")" ::: "memory")
; #define PG8_BAR __builtin_amdgcn_s_barrier()
; #define PG8_SCHED __builtin_amdgcn_sched_barrier(0)
; template <class Epi>
; __device__ __forceinline__ void gemm_phase(LAS unsigned char* lds, const Gemm g, const StaticOrder& S, const Epi& E, const int tid) {
;     ...
;             const bool last = (t == nt - 2);
;             const char* a1 = cA + (size_t)(t + 1) * kstep;
;             const char* a2 = last ? nA : cA + (size_t)(t + 2) * kstep; const char* b2 = last ? nB : cB + (size_t)(t + 2) * kstep;
;             const char* a3 = a2 + kstep; const char* b3 = b2 + kstep;
;             if constexpr (Epi::HAS_MID) { if (t == (nt >> 1)) E.mid(acc, cur, wr, wc, fr, fq); }
;             PG8_LDB(B0, 0, 0); PG8_SCHED; PG8_LDA(At, 0, 0); PG8_STAGE(PG8_SA(1, 1), a1 + hstep, voffA);
;             PG8_WAIT_L(8); PG8_BAR; PG8_WAIT_L(0); PG8_MMA(0, 0, At, B0); PG8_BAR; PG8_SCHED;
;             PG8_LDB(B1, 0, 1); PG8_STAGE(PG8_SB(0, 0), b2, voffB);
;             PG8_BAR; PG8_WAIT_L(0); PG8_MMA(0, 1, At, B1); PG8_BAR;
;             PG8_LDA(At, 0, 1); PG8_STAGE(PG8_SA(0, 0), a2, voffA);
;             PG8_BAR; PG8_WAIT_L(0); PG8_MMA(1, 0, At, B0); PG8_BAR; PG8_SCHED;
;             PG8_STAGE(PG8_SB(0, 1), b2 + hstepB, voffB);
;             PG8_WAIT_V(6); PG8_BAR; PG8_MMA(1, 1, At, B1); PG8_BAR;
.LBB0_332:
	s_add_u32 s18, s14, 0xfff80080
	s_addc_u32 s19, s15, -1
	s_add_i32 s55, 0, 0x10000
	v_add_u32_e32 v157, s55, v140
	ds_read_b128 v[144:147], v157
	ds_read_b128 v[162:165], v157 offset:1024
	ds_read_b128 v[166:169], v157 offset:2048
	ds_read_b128 v[170:173], v157 offset:3072
	s_cmp_eq_u32 s54, 28
	s_cselect_b32 s23, s9, s19
	s_cselect_b32 s22, s50, s18
	s_cselect_b32 s19, s1, s53
	s_cselect_b32 s18, s51, s52
	v_lshl_add_u64 v[178:179], s[14:15], 0, v[136:137]
	s_add_i32 m0, s39, 0xc000
	ds_read_b128 v[174:177], v143
	ds_read_b128 v[190:193], v143 offset:1024
	ds_read_b128 v[194:197], v143 offset:2048
	ds_read_b128 v[198:201], v143 offset:3072
	ds_read_b128 v[202:205], v143 offset:4096
	ds_read_b128 v[206:209], v143 offset:5120
	ds_read_b128 v[210:213], v143 offset:6144
	ds_read_b128 v[214:217], v143 offset:7168
	global_load_lds_dwordx4 v[178:179], off
	v_lshl_add_u64 v[178:179], s[14:15], 0, v[138:139]
	s_add_i32 m0, s39, 0xe000
	s_nop 0
	global_load_lds_dwordx4 v[178:179], off
	s_waitcnt lgkmcnt(8)
	s_barrier
	s_waitcnt lgkmcnt(0)
	v_mfma_f32_16x16x32_bf16 v[124:127], v[144:147], v[174:177], v[124:127]
	v_mfma_f32_16x16x32_bf16 v[128:131], v[166:169], v[174:177], v[128:131]
	v_mfma_f32_16x16x32_bf16 v[108:111], v[144:147], v[194:197], v[108:111]
	v_mfma_f32_16x16x32_bf16 v[112:115], v[166:169], v[194:197], v[112:115]
	v_mfma_f32_16x16x32_bf16 v[92:95], v[144:147], v[202:205], v[92:95]
	v_mfma_f32_16x16x32_bf16 v[96:99], v[166:169], v[202:205], v[96:99]
	v_mfma_f32_16x16x32_bf16 v[76:79], v[144:147], v[210:213], v[76:79]
	v_mfma_f32_16x16x32_bf16 v[80:83], v[166:169], v[210:213], v[80:83]
	v_mfma_f32_16x16x32_bf16 v[124:127], v[162:165], v[190:193], v[124:127]
	v_mfma_f32_16x16x32_bf16 v[128:131], v[170:173], v[190:193], v[128:131]
	v_mfma_f32_16x16x32_bf16 v[108:111], v[162:165], v[198:201], v[108:111]
	v_mfma_f32_16x16x32_bf16 v[112:115], v[170:173], v[198:201], v[112:115]
	v_mfma_f32_16x16x32_bf16 v[92:95], v[162:165], v[206:209], v[92:95]
	v_mfma_f32_16x16x32_bf16 v[96:99], v[170:173], v[206:209], v[96:99]
	v_mfma_f32_16x16x32_bf16 v[76:79], v[162:165], v[214:217], v[76:79]
	v_mfma_f32_16x16x32_bf16 v[80:83], v[170:173], v[214:217], v[80:83]
	s_barrier
	s_add_i32 s58, 0, 0x14000
	s_add_i32 s55, s55, s38
	v_add_u32_e32 v157, s58, v140
	v_lshl_add_u64 v[178:179], s[18:19], 0, v[2:3]
	s_mov_b32 m0, s55
	ds_read_b128 v[218:221], v157
	ds_read_b128 v[222:225], v157 offset:1024
	ds_read_b128 v[226:229], v157 offset:2048
	ds_read_b128 v[230:233], v157 offset:3072
	global_load_lds_dwordx4 v[178:179], off
	v_lshl_add_u64 v[234:235], s[18:19], 0, v[0:1]
	s_add_i32 m0, s55, 0x2000
	s_nop 0
	global_load_lds_dwordx4 v[234:235], off
	s_barrier
	s_waitcnt lgkmcnt(0)
	v_mfma_f32_16x16x32_bf16 v[116:119], v[218:221], v[174:177], v[116:119]
	v_mfma_f32_16x16x32_bf16 v[120:123], v[226:229], v[174:177], v[120:123]
	v_mfma_f32_16x16x32_bf16 v[100:103], v[218:221], v[194:197], v[100:103]
	v_mfma_f32_16x16x32_bf16 v[104:107], v[226:229], v[194:197], v[104:107]
	v_mfma_f32_16x16x32_bf16 v[84:87], v[218:221], v[202:205], v[84:87]
	v_mfma_f32_16x16x32_bf16 v[88:91], v[226:229], v[202:205], v[88:91]
	v_mfma_f32_16x16x32_bf16 v[68:71], v[218:221], v[210:213], v[68:71]
	v_mfma_f32_16x16x32_bf16 v[72:75], v[226:229], v[210:213], v[72:75]
	v_mfma_f32_16x16x32_bf16 v[116:119], v[222:225], v[190:193], v[116:119]
	v_mfma_f32_16x16x32_bf16 v[120:123], v[230:233], v[190:193], v[120:123]
	v_mfma_f32_16x16x32_bf16 v[100:103], v[222:225], v[198:201], v[100:103]
	v_mfma_f32_16x16x32_bf16 v[104:107], v[230:233], v[198:201], v[104:107]
	v_mfma_f32_16x16x32_bf16 v[84:87], v[222:225], v[206:209], v[84:87]
	v_mfma_f32_16x16x32_bf16 v[88:91], v[230:233], v[206:209], v[88:91]
	v_mfma_f32_16x16x32_bf16 v[68:71], v[222:225], v[214:217], v[68:71]
	v_mfma_f32_16x16x32_bf16 v[72:75], v[230:233], v[214:217], v[72:75]
	s_mov_b32 m0, s39
	v_lshl_add_u64 v[236:237], s[22:23], 0, v[134:135]
	s_barrier
	ds_read_b128 v[174:177], v143 offset:16384
	ds_read_b128 v[190:193], v143 offset:17408
	ds_read_b128 v[194:197], v143 offset:18432
	ds_read_b128 v[198:201], v143 offset:19456
	ds_read_b128 v[202:205], v143 offset:20480
	ds_read_b128 v[206:209], v143 offset:21504
	ds_read_b128 v[210:213], v143 offset:22528
	ds_read_b128 v[214:217], v143 offset:23552
	global_load_lds_dwordx4 v[236:237], off
	v_lshl_add_u64 v[238:239], s[22:23], 0, v[132:133]
	s_mov_b32 m0, s40
	s_nop 0
	global_load_lds_dwordx4 v[238:239], off
	s_barrier
	s_waitcnt lgkmcnt(0)
	v_mfma_f32_16x16x32_bf16 v[60:63], v[144:147], v[174:177], v[60:63]
	v_mfma_f32_16x16x32_bf16 v[64:67], v[166:169], v[174:177], v[64:67]
	v_mfma_f32_16x16x32_bf16 v[44:47], v[144:147], v[194:197], v[44:47]
	v_mfma_f32_16x16x32_bf16 v[48:51], v[166:169], v[194:197], v[48:51]
	v_mfma_f32_16x16x32_bf16 v[28:31], v[144:147], v[202:205], v[28:31]
	v_mfma_f32_16x16x32_bf16 v[32:35], v[166:169], v[202:205], v[32:35]
	v_mfma_f32_16x16x32_bf16 v[12:15], v[144:147], v[210:213], v[12:15]
	v_mfma_f32_16x16x32_bf16 v[16:19], v[166:169], v[210:213], v[16:19]
	v_mfma_f32_16x16x32_bf16 v[60:63], v[162:165], v[190:193], v[60:63]
	v_mfma_f32_16x16x32_bf16 v[64:67], v[170:173], v[190:193], v[64:67]
	v_mfma_f32_16x16x32_bf16 v[44:47], v[162:165], v[198:201], v[44:47]
	v_mfma_f32_16x16x32_bf16 v[48:51], v[170:173], v[198:201], v[48:51]
	v_mfma_f32_16x16x32_bf16 v[28:31], v[162:165], v[206:209], v[28:31]
	v_mfma_f32_16x16x32_bf16 v[32:35], v[170:173], v[206:209], v[32:35]
	v_mfma_f32_16x16x32_bf16 v[12:15], v[162:165], v[214:217], v[12:15]
	v_mfma_f32_16x16x32_bf16 v[16:19], v[170:173], v[214:217], v[16:19]
	s_barrier
; #define PG8_STAGE(bufoff, gbase, voff) do { _Pragma("unroll") for (int _i = 0; _i < 2; ++_i) \
;         __builtin_amdgcn_global_load_lds((const unsigned*)((const char*)(gbase) + (voff)[_i]), (LAS unsigned*)(lds + (bufoff) + ldsw + _i * 8192), 16, 0, 0); } while (0)
; #define PG8_LDA(dst, b, h) do { _Pragma("unroll") for (int m = 0; m < 4; ++m) _Pragma("unroll") for (int k = 0; k < 2; ++k) dst[m][k] = *(const LAS h8*)(lds + PG8_SA(b, h) + aoff + m * 2048 + k * 1024); } while (0)
; #define PG8_LDB(dst, b, h) do { _Pragma("unroll") for (int n = 0; n < 2; ++n) _Pragma("unroll") for (int k = 0; k < 2; ++k) dst[n][k] = *(const LAS h8*)(lds + PG8_SB(b, h) + boff + n * 2048 + k * 1024); } while (0)
; #define PG8_WAIT_V(n) asm volatile("s_waitcnt vmcnt(" #n ")" ::: "memory")
; #define PG8_WAIT_L(n) asm volatile("s_waitcnt lgkmcnt(" #n ")" ::: "memory")
; #define PG8_BAR __builtin_amdgcn_s_barrier()
; #define PG8_SCHED __builtin_amdgcn_sched_barrier(0)
; template <class Epi>
; __device__ __forceinline__ void gemm_phase(LAS unsigned char* lds, const Gemm g, const StaticOrder& S, const Epi& E, const int tid) {
;     ...
;             PG8_STAGE(PG8_SB(0, 1), b2 + hstepB, voffB);
;             PG8_WAIT_V(6); PG8_BAR; PG8_MMA(1, 1, At, B1); PG8_BAR;
;             PG8_LDB(B0, 1, 0); PG8_SCHED; PG8_LDA(At, 1, 0); PG8_STAGE(PG8_SA(0, 1), a2 + hstep, voffA);
;             PG8_WAIT_L(8); PG8_BAR; PG8_WAIT_L(0); PG8_MMA(0, 0, At, B0); PG8_BAR; PG8_SCHED;
;             PG8_LDB(B1, 1, 1); PG8_STAGE(PG8_SB(1, 0), b3, voffB);
;             PG8_BAR; PG8_WAIT_L(0); PG8_MMA(0, 1, At, B1); PG8_BAR;
;             PG8_LDA(At, 1, 1); PG8_STAGE(PG8_SA(1, 0), a3, voffA);
;             PG8_BAR; PG8_WAIT_L(0); PG8_MMA(1, 0, At, B0); PG8_BAR; PG8_SCHED;
;             PG8_STAGE(PG8_SB(1, 1), b3 + hstepB, voffB);
	s_add_u32 s56, s18, 0x20000
	s_addc_u32 s57, s19, 0
	s_add_i32 s55, s58, s38
	v_lshl_add_u64 v[144:145], s[56:57], 0, v[2:3]
	s_mov_b32 m0, s55
	s_nop 0
	global_load_lds_dwordx4 v[144:145], off
	v_lshl_add_u64 v[144:145], s[56:57], 0, v[0:1]
	s_add_i32 m0, s55, 0x2000
	s_nop 0
	global_load_lds_dwordx4 v[144:145], off
	s_waitcnt vmcnt(6)
	s_barrier
	v_mfma_f32_16x16x32_bf16 v[52:55], v[218:221], v[174:177], v[52:55]
	v_mfma_f32_16x16x32_bf16 v[56:59], v[226:229], v[174:177], v[56:59]
	v_mfma_f32_16x16x32_bf16 v[36:39], v[218:221], v[194:197], v[36:39]
	v_mfma_f32_16x16x32_bf16 v[40:43], v[226:229], v[194:197], v[40:43]
	v_mfma_f32_16x16x32_bf16 v[20:23], v[218:221], v[202:205], v[20:23]
	v_mfma_f32_16x16x32_bf16 v[24:27], v[226:229], v[202:205], v[24:27]
	v_mfma_f32_16x16x32_bf16 v[8:11], v[218:221], v[210:213], v[8:11]
	v_mfma_f32_16x16x32_bf16 v[4:7], v[226:229], v[210:213], v[4:7]
	v_mfma_f32_16x16x32_bf16 v[52:55], v[222:225], v[190:193], v[52:55]
	v_mfma_f32_16x16x32_bf16 v[56:59], v[230:233], v[190:193], v[56:59]
	v_mfma_f32_16x16x32_bf16 v[36:39], v[222:225], v[198:201], v[36:39]
	v_mfma_f32_16x16x32_bf16 v[40:43], v[230:233], v[198:201], v[40:43]
	v_mfma_f32_16x16x32_bf16 v[20:23], v[222:225], v[206:209], v[20:23]
	v_mfma_f32_16x16x32_bf16 v[24:27], v[230:233], v[206:209], v[24:27]
	v_mfma_f32_16x16x32_bf16 v[8:11], v[222:225], v[214:217], v[8:11]
	v_mfma_f32_16x16x32_bf16 v[4:7], v[230:233], v[214:217], v[4:7]
	s_add_i32 s55, 0, 0x18000
	v_add_u32_e32 v157, s55, v140
	s_barrier
	ds_read_b128 v[144:147], v157
	ds_read_b128 v[162:165], v157 offset:1024
	ds_read_b128 v[166:169], v157 offset:2048
	ds_read_b128 v[170:173], v157 offset:3072
	s_add_u32 s22, s22, 0x80000
	s_addc_u32 s23, s23, 0
	s_mov_b32 m0, s41
	v_lshl_add_u64 v[218:219], s[22:23], 0, v[134:135]
	ds_read_b128 v[174:177], v143 offset:32768
	ds_read_b128 v[190:193], v143 offset:33792
	ds_read_b128 v[194:197], v143 offset:34816
	ds_read_b128 v[198:201], v143 offset:35840
	ds_read_b128 v[202:205], v143 offset:36864
	ds_read_b128 v[206:209], v143 offset:37888
	ds_read_b128 v[210:213], v143 offset:38912
	ds_read_b128 v[214:217], v143 offset:39936
	global_load_lds_dwordx4 v[218:219], off
	v_lshl_add_u64 v[218:219], s[22:23], 0, v[132:133]
	s_mov_b32 m0, s42
	s_nop 0
	global_load_lds_dwordx4 v[218:219], off
	s_waitcnt lgkmcnt(8)
	s_barrier
	s_waitcnt lgkmcnt(0)
	v_mfma_f32_16x16x32_bf16 v[124:127], v[144:147], v[174:177], v[124:127]
	v_mfma_f32_16x16x32_bf16 v[128:131], v[166:169], v[174:177], v[128:131]
	v_mfma_f32_16x16x32_bf16 v[108:111], v[144:147], v[194:197], v[108:111]
	v_mfma_f32_16x16x32_bf16 v[112:115], v[166:169], v[194:197], v[112:115]
	v_mfma_f32_16x16x32_bf16 v[92:95], v[144:147], v[202:205], v[92:95]
	v_mfma_f32_16x16x32_bf16 v[96:99], v[166:169], v[202:205], v[96:99]
	v_mfma_f32_16x16x32_bf16 v[76:79], v[144:147], v[210:213], v[76:79]
	v_mfma_f32_16x16x32_bf16 v[80:83], v[166:169], v[210:213], v[80:83]
	v_mfma_f32_16x16x32_bf16 v[124:127], v[162:165], v[190:193], v[124:127]
	v_mfma_f32_16x16x32_bf16 v[128:131], v[170:173], v[190:193], v[128:131]
	v_mfma_f32_16x16x32_bf16 v[108:111], v[162:165], v[198:201], v[108:111]
	v_mfma_f32_16x16x32_bf16 v[112:115], v[170:173], v[198:201], v[112:115]
	v_mfma_f32_16x16x32_bf16 v[92:95], v[162:165], v[206:209], v[92:95]
	v_mfma_f32_16x16x32_bf16 v[96:99], v[170:173], v[206:209], v[96:99]
	v_mfma_f32_16x16x32_bf16 v[76:79], v[162:165], v[214:217], v[76:79]
	v_mfma_f32_16x16x32_bf16 v[80:83], v[170:173], v[214:217], v[80:83]
	s_barrier
	s_add_i32 s22, 0, 0x1c000
	s_add_i32 s23, s55, s38
	v_add_u32_e32 v157, s22, v140
	v_lshl_add_u64 v[178:179], v[178:179], 0, s[30:31]
	s_mov_b32 m0, s23
	ds_read_b128 v[218:221], v157
	ds_read_b128 v[222:225], v157 offset:1024
	ds_read_b128 v[226:229], v157 offset:2048
	ds_read_b128 v[230:233], v157 offset:3072
	global_load_lds_dwordx4 v[178:179], off
	v_lshl_add_u64 v[178:179], v[234:235], 0, s[30:31]
	s_add_i32 m0, s23, 0x2000
	s_nop 0
	global_load_lds_dwordx4 v[178:179], off
	s_barrier
	s_waitcnt lgkmcnt(0)
	v_mfma_f32_16x16x32_bf16 v[116:119], v[218:221], v[174:177], v[116:119]
	v_mfma_f32_16x16x32_bf16 v[120:123], v[226:229], v[174:177], v[120:123]
	v_mfma_f32_16x16x32_bf16 v[100:103], v[218:221], v[194:197], v[100:103]
	v_mfma_f32_16x16x32_bf16 v[104:107], v[226:229], v[194:197], v[104:107]
	v_mfma_f32_16x16x32_bf16 v[84:87], v[218:221], v[202:205], v[84:87]
	v_mfma_f32_16x16x32_bf16 v[88:91], v[226:229], v[202:205], v[88:91]
	v_mfma_f32_16x16x32_bf16 v[68:71], v[218:221], v[210:213], v[68:71]
	v_mfma_f32_16x16x32_bf16 v[72:75], v[226:229], v[210:213], v[72:75]
	v_mfma_f32_16x16x32_bf16 v[116:119], v[222:225], v[190:193], v[116:119]
	v_mfma_f32_16x16x32_bf16 v[120:123], v[230:233], v[190:193], v[120:123]
	v_mfma_f32_16x16x32_bf16 v[100:103], v[222:225], v[198:201], v[100:103]
	v_mfma_f32_16x16x32_bf16 v[104:107], v[230:233], v[198:201], v[104:107]
	v_mfma_f32_16x16x32_bf16 v[84:87], v[222:225], v[206:209], v[84:87]
	v_mfma_f32_16x16x32_bf16 v[88:91], v[230:233], v[206:209], v[88:91]
	v_mfma_f32_16x16x32_bf16 v[68:71], v[222:225], v[214:217], v[68:71]
	v_mfma_f32_16x16x32_bf16 v[72:75], v[230:233], v[214:217], v[72:75]
	s_mov_b32 m0, s43
	v_lshl_add_u64 v[178:179], v[236:237], 0, s[30:31]
	s_barrier
	ds_read_b128 v[174:177], v143 offset:49152
	ds_read_b128 v[190:193], v143 offset:50176
	ds_read_b128 v[194:197], v143 offset:51200
	ds_read_b128 v[198:201], v143 offset:52224
	ds_read_b128 v[202:205], v143 offset:53248
	ds_read_b128 v[206:209], v143 offset:54272
	ds_read_b128 v[210:213], v143 offset:55296
	ds_read_b128 v[214:217], v143 offset:56320
	global_load_lds_dwordx4 v[178:179], off
	v_lshl_add_u64 v[178:179], v[238:239], 0, s[30:31]
	s_mov_b32 m0, s46
	s_nop 0
	global_load_lds_dwordx4 v[178:179], off
	s_barrier
; #define PG8_STAGE(bufoff, gbase, voff) do { _Pragma("unroll") for (int _i = 0; _i < 2; ++_i) \
;         __builtin_amdgcn_global_load_lds((const unsigned*)((const char*)(gbase) + (voff)[_i]), (LAS unsigned*)(lds + (bufoff) + ldsw + _i * 8192), 16, 0, 0); } while (0)
; #define PG8_WAIT_V(n) asm volatile("s_waitcnt vmcnt(" #n ")" ::: "memory")
; #define PG8_WAIT_L(n) asm volatile("s_waitcnt lgkmcnt(" #n ")" ::: "memory")
; #define PG8_BAR __builtin_amdgcn_s_barrier()
; #define PG8_SCHED __builtin_amdgcn_sched_barrier(0)
; template <class Epi>
; __device__ __forceinline__ void gemm_phase(LAS unsigned char* lds, const Gemm g, const StaticOrder& S, const Epi& E, const int tid) {
;     ...
;             PG8_BAR; PG8_WAIT_L(0); PG8_MMA(1, 0, At, B0); PG8_BAR; PG8_SCHED;
;             PG8_STAGE(PG8_SB(1, 1), b3 + hstepB, voffB);
;             PG8_WAIT_V(6); PG8_BAR; PG8_MMA(1, 1, At, B1); PG8_BAR;
;     __device__ __forceinline__ void operator()(f32x4 (&acc)[2][2][4][2], const pg8::Unit& u, int wr, int wc, int fr, int fq) const {
;         const bool hi = fr >= 8;
;         const int row0 = u.pm * 256 + wr * 64 + (fr & 7), col = u.pn * 256 + wc * 64 + fq * 8 + (hi ? 32 : 0);
; #pragma unroll
;         for (int ai = 0; ai < 2; ++ai)
; #pragma unroll
;             for (int m = 0; m < 4; ++m) {
;                 const h8 x0 = pack8(acc[ai][0][m][0], acc[ai][0][m][1]), x1 = pack8(acc[ai][1][m][0], acc[ai][1][m][1]);
;                 const i32x4 snd = hi ? __builtin_bit_cast(i32x4, x0) : __builtin_bit_cast(i32x4, x1);
;                 i32x4 rcv;
; #pragma unroll
;                 for (int d = 0; d < 4; ++d) rcv[d] = __builtin_amdgcn_update_dpp(0, snd[d], 0x128  , 0xF, 0xF, false);
;                 const h8 rv = __builtin_bit_cast(h8, rcv);
;                 const h8 vA = hi ? rv : x0;
;                 const h8 vB = hi ? x1 : rv;
;                 half_t* rowp = O + (size_t)(row0 + ai * 128 + m * 16) * NIN + col;
;                 __builtin_nontemporal_store(vA, (h8*)rowp); __builtin_nontemporal_store(vB, (h8*)(rowp + (size_t)8 * NIN)); }
	s_waitcnt lgkmcnt(0)
	v_mfma_f32_16x16x32_bf16 v[60:63], v[144:147], v[174:177], v[60:63]
	v_mfma_f32_16x16x32_bf16 v[64:67], v[166:169], v[174:177], v[64:67]
	v_mfma_f32_16x16x32_bf16 v[44:47], v[144:147], v[194:197], v[44:47]
	v_mfma_f32_16x16x32_bf16 v[48:51], v[166:169], v[194:197], v[48:51]
	v_mfma_f32_16x16x32_bf16 v[28:31], v[144:147], v[202:205], v[28:31]
	v_mfma_f32_16x16x32_bf16 v[32:35], v[166:169], v[202:205], v[32:35]
	v_mfma_f32_16x16x32_bf16 v[12:15], v[144:147], v[210:213], v[12:15]
	v_mfma_f32_16x16x32_bf16 v[16:19], v[166:169], v[210:213], v[16:19]
	v_mfma_f32_16x16x32_bf16 v[60:63], v[162:165], v[190:193], v[60:63]
	v_mfma_f32_16x16x32_bf16 v[64:67], v[170:173], v[190:193], v[64:67]
	v_mfma_f32_16x16x32_bf16 v[44:47], v[162:165], v[198:201], v[44:47]
	v_mfma_f32_16x16x32_bf16 v[48:51], v[170:173], v[198:201], v[48:51]
	v_mfma_f32_16x16x32_bf16 v[28:31], v[162:165], v[206:209], v[28:31]
	v_mfma_f32_16x16x32_bf16 v[32:35], v[170:173], v[206:209], v[32:35]
	v_mfma_f32_16x16x32_bf16 v[12:15], v[162:165], v[214:217], v[12:15]
	v_mfma_f32_16x16x32_bf16 v[16:19], v[170:173], v[214:217], v[16:19]
	s_barrier
	s_add_u32 s18, s18, 0x20080
	s_addc_u32 s19, s19, 0
	s_add_i32 s22, s22, s38
	v_lshl_add_u64 v[144:145], s[18:19], 0, v[2:3]
	s_mov_b32 m0, s22
	s_nop 0
	global_load_lds_dwordx4 v[144:145], off
	v_lshl_add_u64 v[144:145], s[18:19], 0, v[0:1]
	s_add_i32 m0, s22, 0x2000
	s_nop 0
	global_load_lds_dwordx4 v[144:145], off
	s_waitcnt vmcnt(6)
	s_barrier
	v_mfma_f32_16x16x32_bf16 v[52:55], v[218:221], v[174:177], v[52:55]
	v_mfma_f32_16x16x32_bf16 v[56:59], v[226:229], v[174:177], v[56:59]
	v_mfma_f32_16x16x32_bf16 v[36:39], v[218:221], v[194:197], v[36:39]
	v_mfma_f32_16x16x32_bf16 v[40:43], v[226:229], v[194:197], v[40:43]
	v_mfma_f32_16x16x32_bf16 v[20:23], v[218:221], v[202:205], v[20:23]
	v_mfma_f32_16x16x32_bf16 v[24:27], v[226:229], v[202:205], v[24:27]
	v_mfma_f32_16x16x32_bf16 v[8:11], v[218:221], v[210:213], v[8:11]
	v_mfma_f32_16x16x32_bf16 v[4:7], v[226:229], v[210:213], v[4:7]
	v_mfma_f32_16x16x32_bf16 v[52:55], v[222:225], v[190:193], v[52:55]
	v_mfma_f32_16x16x32_bf16 v[56:59], v[230:233], v[190:193], v[56:59]
	v_mfma_f32_16x16x32_bf16 v[36:39], v[222:225], v[198:201], v[36:39]
	v_mfma_f32_16x16x32_bf16 v[40:43], v[230:233], v[198:201], v[40:43]
	v_mfma_f32_16x16x32_bf16 v[20:23], v[222:225], v[206:209], v[20:23]
	v_mfma_f32_16x16x32_bf16 v[24:27], v[230:233], v[206:209], v[24:27]
	v_mfma_f32_16x16x32_bf16 v[8:11], v[222:225], v[214:217], v[8:11]
	v_mfma_f32_16x16x32_bf16 v[4:7], v[230:233], v[214:217], v[4:7]
	s_add_i32 s54, s54, 2
	s_add_u32 s14, s14, 0x100
	s_addc_u32 s15, s15, 0
	s_add_u32 s52, s52, 0x100
	s_addc_u32 s53, s53, 0
	s_cmp_gt_u32 s54, 29
	s_barrier
	s_cbranch_scc0 .LBB0_332
	v_cvt_pk_f16_f32 v124, v124, v125
	v_cvt_pk_f16_f32 v116, v116, v117
	v_cvt_pk_f16_f32 v130, v130, v131
	v_cvt_pk_f16_f32 v131, v122, v123
	v_cvt_pk_f16_f32 v128, v128, v129
	v_cvt_pk_f16_f32 v129, v120, v121
	v_cvt_pk_f16_f32 v121, v126, v127
	v_cvt_pk_f16_f32 v118, v118, v119
	v_cndmask_b32_e64 v117, v116, v124, s[4:5]
	v_mov_b32_e32 v147, v3
	v_cndmask_b32_e64 v122, v131, v130, s[4:5]
	v_cndmask_b32_e64 v119, v118, v121, s[4:5]
	v_mov_b32_dpp v147, v117 row_ror:8 row_mask:0xf bank_mask:0xf
	v_mov_b32_e32 v117, v3
	v_mov_b32_e32 v125, v3
	v_lshl_or_b32 v144, s48, 8, v142
	v_cndmask_b32_e64 v120, v129, v128, s[4:5]
	v_mov_b32_dpp v117, v119 row_ror:8 row_mask:0xf bank_mask:0xf
	v_mov_b32_e32 v119, v3
	v_mov_b32_dpp v125, v122 row_ror:8 row_mask:0xf bank_mask:0xf
	v_lshl_add_u32 v146, s49, 8, v141
	v_ashrrev_i32_e32 v145, 31, v144
	v_mov_b32_dpp v119, v120 row_ror:8 row_mask:0xf bank_mask:0xf
	v_cndmask_b32_e64 v123, v130, v125, s[4:5]
	v_cndmask_b32_e64 v121, v121, v117, s[4:5]
	v_cndmask_b32_e64 v120, v124, v147, s[4:5]
	v_cndmask_b32_e64 v127, v125, v131, s[4:5]
	v_cndmask_b32_e64 v125, v117, v118, s[4:5]
	v_cndmask_b32_e64 v124, v147, v116, s[4:5]
	v_mov_b64_e32 v[116:117], s[36:37]
	v_cndmask_b32_e64 v122, v128, v119, s[4:5]
	v_cndmask_b32_e64 v126, v119, v129, s[4:5]
	v_mad_i64_i32 v[128:129], s[14:15], v146, s35, v[116:117]
	v_lshlrev_b64 v[118:119], 1, v[144:145]
	v_lshl_add_u64 v[128:129], v[128:129], 0, v[118:119]
	s_mov_b32 s1, 0x3c000
	global_store_dwordx4 v[128:129], v[120:123], off nt
	v_cvt_pk_f16_f32 v112, v112, v113
	v_cvt_pk_f16_f32 v104, v104, v105
	v_add_co_u32_e32 v120, vcc, s1, v128
	v_cvt_pk_f16_f32 v108, v108, v109
	s_nop 0
	v_addc_co_u32_e32 v121, vcc, 0, v129, vcc
	v_cvt_pk_f16_f32 v109, v100, v101
	global_store_dwordx4 v[120:121], v[124:127], off nt
	v_cvt_pk_f16_f32 v114, v114, v115
	v_cvt_pk_f16_f32 v106, v106, v107
	v_cndmask_b32_e64 v105, v104, v112, s[4:5]
	v_cndmask_b32_e64 v100, v109, v108, s[4:5]
	v_mov_b32_e32 v113, v3
	v_mov_b32_e32 v120, v3
	v_cndmask_b32_e64 v107, v106, v114, s[4:5]
	v_cvt_pk_f16_f32 v110, v110, v111
	v_cvt_pk_f16_f32 v111, v102, v103
	v_mov_b32_dpp v113, v100 row_ror:8 row_mask:0xf bank_mask:0xf
	v_mov_b32_dpp v120, v105 row_ror:8 row_mask:0xf bank_mask:0xf
	v_mov_b32_e32 v105, v3
	v_cndmask_b32_e64 v102, v111, v110, s[4:5]
	v_mov_b32_e32 v115, v3
	v_mov_b32_dpp v105, v107 row_ror:8 row_mask:0xf bank_mask:0xf
	v_cndmask_b32_e64 v100, v108, v113, s[4:5]
	v_or_b32_e32 v108, 16, v146
	v_mov_b32_dpp v115, v102 row_ror:8 row_mask:0xf bank_mask:0xf
	v_cndmask_b32_e64 v107, v105, v106, s[4:5]
	v_cndmask_b32_e64 v106, v120, v104, s[4:5]
	v_cndmask_b32_e64 v104, v113, v109, s[4:5]
	v_mad_i64_i32 v[108:109], s[14:15], v108, s35, v[116:117]
	v_cndmask_b32_e64 v103, v114, v105, s[4:5]
	v_cndmask_b32_e64 v102, v112, v120, s[4:5]
	v_cndmask_b32_e64 v101, v110, v115, s[4:5]
;     __device__ __forceinline__ void operator()(f32x4 (&acc)[2][2][4][2], const pg8::Unit& u, int wr, int wc, int fr, int fq) const {
;     ...
;         for (int ai = 0; ai < 2; ++ai)
; #pragma unroll
;             for (int m = 0; m < 4; ++m) {
;                 const h8 x0 = pack8(acc[ai][0][m][0], acc[ai][0][m][1]), x1 = pack8(acc[ai][1][m][0], acc[ai][1][m][1]);
;                 const i32x4 snd = hi ? __builtin_bit_cast(i32x4, x0) : __builtin_bit_cast(i32x4, x1);
;                 i32x4 rcv;
; #pragma unroll
;                 for (int d = 0; d < 4; ++d) rcv[d] = __builtin_amdgcn_update_dpp(0, snd[d], 0x128  , 0xF, 0xF, false);
;                 const h8 rv = __builtin_bit_cast(h8, rcv);
;                 const h8 vA = hi ? rv : x0;
;                 const h8 vB = hi ? x1 : rv;
;                 half_t* rowp = O + (size_t)(row0 + ai * 128 + m * 16) * NIN + col;
;                 __builtin_nontemporal_store(vA, (h8*)rowp); __builtin_nontemporal_store(vB, (h8*)(rowp + (size_t)8 * NIN)); }
	v_lshl_add_u64 v[108:109], v[108:109], 0, v[118:119]
	global_store_dwordx4 v[108:109], v[100:103], off nt
	v_cndmask_b32_e64 v105, v115, v111, s[4:5]
	v_cvt_pk_f16_f32 v96, v96, v97
	v_add_co_u32_e32 v100, vcc, s1, v108
	v_cvt_pk_f16_f32 v88, v88, v89
	s_nop 0
	v_addc_co_u32_e32 v101, vcc, 0, v109, vcc
	v_cvt_pk_f16_f32 v92, v92, v93
	v_cvt_pk_f16_f32 v93, v84, v85
	global_store_dwordx4 v[100:101], v[104:107], off nt
	v_cvt_pk_f16_f32 v98, v98, v99
	v_cvt_pk_f16_f32 v90, v90, v91
	v_cndmask_b32_e64 v89, v88, v96, s[4:5]
	v_cndmask_b32_e64 v84, v93, v92, s[4:5]
	v_mov_b32_e32 v97, v3
	v_mov_b32_e32 v100, v3
	v_cndmask_b32_e64 v91, v90, v98, s[4:5]
	v_cvt_pk_f16_f32 v94, v94, v95
	v_cvt_pk_f16_f32 v95, v86, v87
	v_mov_b32_dpp v97, v84 row_ror:8 row_mask:0xf bank_mask:0xf
	v_mov_b32_dpp v100, v89 row_ror:8 row_mask:0xf bank_mask:0xf
	v_mov_b32_e32 v89, v3
	v_cndmask_b32_e64 v86, v95, v94, s[4:5]
	v_mov_b32_e32 v99, v3
	v_mov_b32_dpp v89, v91 row_ror:8 row_mask:0xf bank_mask:0xf
	v_cndmask_b32_e64 v84, v92, v97, s[4:5]
	v_or_b32_e32 v92, 32, v146
	v_mov_b32_dpp v99, v86 row_ror:8 row_mask:0xf bank_mask:0xf
	v_cndmask_b32_e64 v91, v89, v90, s[4:5]
	v_cndmask_b32_e64 v90, v100, v88, s[4:5]
	v_cndmask_b32_e64 v88, v97, v93, s[4:5]
	v_mad_i64_i32 v[92:93], s[14:15], v92, s35, v[116:117]
	v_cndmask_b32_e64 v87, v98, v89, s[4:5]
	v_cndmask_b32_e64 v86, v96, v100, s[4:5]
	v_cndmask_b32_e64 v85, v94, v99, s[4:5]
	v_lshl_add_u64 v[92:93], v[92:93], 0, v[118:119]
	global_store_dwordx4 v[92:93], v[84:87], off nt
	v_cndmask_b32_e64 v89, v99, v95, s[4:5]
	v_cvt_pk_f16_f32 v80, v80, v81
	v_add_co_u32_e32 v84, vcc, s1, v92
	v_cvt_pk_f16_f32 v72, v72, v73
	s_nop 0
	v_addc_co_u32_e32 v85, vcc, 0, v93, vcc
	v_cvt_pk_f16_f32 v76, v76, v77
	v_cvt_pk_f16_f32 v77, v68, v69
	global_store_dwordx4 v[84:85], v[88:91], off nt
	v_cvt_pk_f16_f32 v82, v82, v83
	v_cvt_pk_f16_f32 v74, v74, v75
	v_cndmask_b32_e64 v73, v72, v80, s[4:5]
	v_cndmask_b32_e64 v68, v77, v76, s[4:5]
	v_mov_b32_e32 v81, v3
	v_mov_b32_e32 v84, v3
	v_cndmask_b32_e64 v75, v74, v82, s[4:5]
	v_cvt_pk_f16_f32 v78, v78, v79
	v_cvt_pk_f16_f32 v79, v70, v71
	v_mov_b32_dpp v81, v68 row_ror:8 row_mask:0xf bank_mask:0xf
	v_mov_b32_dpp v84, v73 row_ror:8 row_mask:0xf bank_mask:0xf
	v_mov_b32_e32 v73, v3
	v_cndmask_b32_e64 v70, v79, v78, s[4:5]
	v_mov_b32_e32 v83, v3
	v_mov_b32_dpp v73, v75 row_ror:8 row_mask:0xf bank_mask:0xf
	v_cndmask_b32_e64 v68, v76, v81, s[4:5]
	v_or_b32_e32 v76, 48, v146
	v_mov_b32_dpp v83, v70 row_ror:8 row_mask:0xf bank_mask:0xf
	v_cndmask_b32_e64 v75, v73, v74, s[4:5]
	v_cndmask_b32_e64 v74, v84, v72, s[4:5]
	v_cndmask_b32_e64 v72, v81, v77, s[4:5]
	v_mad_i64_i32 v[76:77], s[14:15], v76, s35, v[116:117]
	v_cndmask_b32_e64 v71, v82, v73, s[4:5]
	v_cndmask_b32_e64 v70, v80, v84, s[4:5]
	v_cndmask_b32_e64 v69, v78, v83, s[4:5]
	v_lshl_add_u64 v[76:77], v[76:77], 0, v[118:119]
	global_store_dwordx4 v[76:77], v[68:71], off nt
	v_cndmask_b32_e64 v73, v83, v79, s[4:5]
	v_cvt_pk_f16_f32 v64, v64, v65
	v_add_co_u32_e32 v68, vcc, s1, v76
	v_cvt_pk_f16_f32 v56, v56, v57
	s_nop 0
	v_addc_co_u32_e32 v69, vcc, 0, v77, vcc
	global_store_dwordx4 v[68:69], v[72:75], off nt
	v_cvt_pk_f16_f32 v66, v66, v67
	v_cvt_pk_f16_f32 v58, v58, v59
	v_cndmask_b32_e64 v57, v56, v64, s[4:5]
	v_cvt_pk_f16_f32 v60, v60, v61
	v_cvt_pk_f16_f32 v61, v52, v53
	v_mov_b32_e32 v69, v3
	v_cndmask_b32_e64 v59, v58, v66, s[4:5]
	v_cvt_pk_f16_f32 v62, v62, v63
	v_cvt_pk_f16_f32 v63, v54, v55
	v_cndmask_b32_e64 v52, v61, v60, s[4:5]
	v_mov_b32_e32 v65, v3
	v_mov_b32_dpp v69, v57 row_ror:8 row_mask:0xf bank_mask:0xf
	v_mov_b32_e32 v57, v3
	v_add_u32_e32 v68, 0x80, v146
	v_cndmask_b32_e64 v54, v63, v62, s[4:5]
	v_mov_b32_dpp v65, v52 row_ror:8 row_mask:0xf bank_mask:0xf
	v_mov_b32_e32 v67, v3
	v_mov_b32_dpp v57, v59 row_ror:8 row_mask:0xf bank_mask:0xf
	v_cndmask_b32_e64 v52, v60, v65, s[4:5]
	v_mov_b32_dpp v67, v54 row_ror:8 row_mask:0xf bank_mask:0xf
	v_cndmask_b32_e64 v59, v57, v58, s[4:5]
	v_cndmask_b32_e64 v58, v69, v56, s[4:5]
	v_cndmask_b32_e64 v56, v65, v61, s[4:5]
	v_mad_i64_i32 v[60:61], s[14:15], v68, s35, v[116:117]
	v_cndmask_b32_e64 v55, v66, v57, s[4:5]
	v_cndmask_b32_e64 v54, v64, v69, s[4:5]
	v_cndmask_b32_e64 v53, v62, v67, s[4:5]
	v_lshl_add_u64 v[60:61], v[60:61], 0, v[118:119]
	global_store_dwordx4 v[60:61], v[52:55], off nt
	v_cndmask_b32_e64 v57, v67, v63, s[4:5]
	v_cvt_pk_f16_f32 v48, v48, v49
	v_add_co_u32_e32 v52, vcc, s1, v60
	v_cvt_pk_f16_f32 v40, v40, v41
	s_nop 0
	v_addc_co_u32_e32 v53, vcc, 0, v61, vcc
	v_cvt_pk_f16_f32 v44, v44, v45
; #define PG8_WAIT_V(n) asm volatile("s_waitcnt vmcnt(" #n ")" ::: "memory")
; #define PG8_BAR __builtin_amdgcn_s_barrier()
; template <class Epi>
; __device__ __forceinline__ void gemm_phase(LAS unsigned char* lds, const Gemm g, const StaticOrder& S, const Epi& E, const int tid) {
;     ...
;     PG8_WAIT_V(0);
;     if (wr == 0) PG8_BAR;
;     PG8_BAR;
;     __device__ __forceinline__ void operator()(f32x4 (&acc)[2][2][4][2], const pg8::Unit& u, int wr, int wc, int fr, int fq) const {
;     ...
;         for (int ai = 0; ai < 2; ++ai)
; #pragma unroll
;             for (int m = 0; m < 4; ++m) {
;                 const h8 x0 = pack8(acc[ai][0][m][0], acc[ai][0][m][1]), x1 = pack8(acc[ai][1][m][0], acc[ai][1][m][1]);
;                 const i32x4 snd = hi ? __builtin_bit_cast(i32x4, x0) : __builtin_bit_cast(i32x4, x1);
;                 i32x4 rcv;
; #pragma unroll
;                 for (int d = 0; d < 4; ++d) rcv[d] = __builtin_amdgcn_update_dpp(0, snd[d], 0x128  , 0xF, 0xF, false);
;                 const h8 rv = __builtin_bit_cast(h8, rcv);
;                 const h8 vA = hi ? rv : x0;
;                 const h8 vB = hi ? x1 : rv;
;                 half_t* rowp = O + (size_t)(row0 + ai * 128 + m * 16) * NIN + col;
;                 __builtin_nontemporal_store(vA, (h8*)rowp); __builtin_nontemporal_store(vB, (h8*)(rowp + (size_t)8 * NIN)); }
	v_cvt_pk_f16_f32 v45, v36, v37
	global_store_dwordx4 v[52:53], v[56:59], off nt
	v_cvt_pk_f16_f32 v50, v50, v51
	v_cvt_pk_f16_f32 v42, v42, v43
	v_cndmask_b32_e64 v41, v40, v48, s[4:5]
	v_cndmask_b32_e64 v36, v45, v44, s[4:5]
	v_mov_b32_e32 v49, v3
	v_mov_b32_e32 v52, v3
	v_cndmask_b32_e64 v43, v42, v50, s[4:5]
	v_cvt_pk_f16_f32 v46, v46, v47
	v_cvt_pk_f16_f32 v47, v38, v39
	v_mov_b32_dpp v49, v36 row_ror:8 row_mask:0xf bank_mask:0xf
	v_mov_b32_dpp v52, v41 row_ror:8 row_mask:0xf bank_mask:0xf
	v_mov_b32_e32 v41, v3
	v_cndmask_b32_e64 v38, v47, v46, s[4:5]
	v_mov_b32_e32 v51, v3
	v_mov_b32_dpp v41, v43 row_ror:8 row_mask:0xf bank_mask:0xf
	v_cndmask_b32_e64 v36, v44, v49, s[4:5]
	v_add_u32_e32 v44, 0x90, v146
	v_mov_b32_dpp v51, v38 row_ror:8 row_mask:0xf bank_mask:0xf
	v_cndmask_b32_e64 v43, v41, v42, s[4:5]
	v_cndmask_b32_e64 v42, v52, v40, s[4:5]
	v_cndmask_b32_e64 v40, v49, v45, s[4:5]
	v_mad_i64_i32 v[44:45], s[14:15], v44, s35, v[116:117]
	v_cndmask_b32_e64 v39, v50, v41, s[4:5]
	v_cndmask_b32_e64 v38, v48, v52, s[4:5]
	v_cndmask_b32_e64 v37, v46, v51, s[4:5]
	v_lshl_add_u64 v[44:45], v[44:45], 0, v[118:119]
	global_store_dwordx4 v[44:45], v[36:39], off nt
	v_cndmask_b32_e64 v41, v51, v47, s[4:5]
	v_cvt_pk_f16_f32 v32, v32, v33
	v_add_co_u32_e32 v36, vcc, s1, v44
	v_cvt_pk_f16_f32 v24, v24, v25
	s_nop 0
	v_addc_co_u32_e32 v37, vcc, 0, v45, vcc
	v_cvt_pk_f16_f32 v28, v28, v29
	v_cvt_pk_f16_f32 v29, v20, v21
	global_store_dwordx4 v[36:37], v[40:43], off nt
	v_cvt_pk_f16_f32 v34, v34, v35
	v_cvt_pk_f16_f32 v26, v26, v27
	v_cndmask_b32_e64 v25, v24, v32, s[4:5]
	v_cndmask_b32_e64 v20, v29, v28, s[4:5]
	v_mov_b32_e32 v33, v3
	v_mov_b32_e32 v36, v3
	v_cndmask_b32_e64 v27, v26, v34, s[4:5]
	v_cvt_pk_f16_f32 v30, v30, v31
	v_cvt_pk_f16_f32 v31, v22, v23
	v_mov_b32_dpp v33, v20 row_ror:8 row_mask:0xf bank_mask:0xf
	v_mov_b32_dpp v36, v25 row_ror:8 row_mask:0xf bank_mask:0xf
	v_mov_b32_e32 v25, v3
	v_cvt_pk_f16_f32 v16, v16, v17
	v_cvt_pk_f16_f32 v17, v4, v5
	v_cvt_pk_f16_f32 v5, v14, v15
	v_cvt_pk_f16_f32 v14, v10, v11
	v_cvt_pk_f16_f32 v10, v12, v13
	v_cvt_pk_f16_f32 v8, v8, v9
	v_cndmask_b32_e64 v22, v31, v30, s[4:5]
	v_mov_b32_e32 v35, v3
	v_mov_b32_dpp v25, v27 row_ror:8 row_mask:0xf bank_mask:0xf
	v_cndmask_b32_e64 v20, v28, v33, s[4:5]
	v_add_u32_e32 v28, 0xa0, v146
	v_cndmask_b32_e64 v9, v8, v10, s[4:5]
	v_mov_b32_e32 v12, v3
	v_mov_b32_dpp v35, v22 row_ror:8 row_mask:0xf bank_mask:0xf
	v_cndmask_b32_e64 v27, v25, v26, s[4:5]
	v_cndmask_b32_e64 v26, v36, v24, s[4:5]
	v_cndmask_b32_e64 v24, v33, v29, s[4:5]
	v_mad_i64_i32 v[28:29], s[14:15], v28, s35, v[116:117]
	v_cvt_pk_f16_f32 v18, v18, v19
	v_cvt_pk_f16_f32 v19, v6, v7
	v_cndmask_b32_e64 v4, v17, v16, s[4:5]
	v_mov_b32_dpp v12, v9 row_ror:8 row_mask:0xf bank_mask:0xf
	v_mov_b32_e32 v13, v3
	v_cndmask_b32_e64 v23, v34, v25, s[4:5]
	v_cndmask_b32_e64 v22, v32, v36, s[4:5]
	v_cndmask_b32_e64 v21, v30, v35, s[4:5]
	v_lshl_add_u64 v[28:29], v[28:29], 0, v[118:119]
	v_cndmask_b32_e64 v6, v19, v18, s[4:5]
	v_cndmask_b32_e64 v7, v14, v5, s[4:5]
	v_mov_b32_e32 v9, v3
	v_mov_b32_dpp v13, v4 row_ror:8 row_mask:0xf bank_mask:0xf
	v_mov_b32_e32 v11, v3
	v_cndmask_b32_e64 v4, v10, v12, s[4:5]
	v_cndmask_b32_e64 v8, v12, v8, s[4:5]
	v_add_u32_e32 v12, 0xb0, v146
	global_store_dwordx4 v[28:29], v[20:23], off nt
	v_mov_b32_dpp v9, v7 row_ror:8 row_mask:0xf bank_mask:0xf
	v_mov_b32_dpp v11, v6 row_ror:8 row_mask:0xf bank_mask:0xf
	v_add_co_u32_e32 v20, vcc, s1, v28
	v_cndmask_b32_e64 v6, v16, v13, s[4:5]
	v_cndmask_b32_e64 v10, v13, v17, s[4:5]
	v_mad_i64_i32 v[12:13], s[14:15], v12, s35, v[116:117]
	v_addc_co_u32_e32 v21, vcc, 0, v29, vcc
	v_cndmask_b32_e64 v7, v18, v11, s[4:5]
	v_cndmask_b32_e64 v5, v5, v9, s[4:5]
	v_lshl_add_u64 v[12:13], v[12:13], 0, v[118:119]
	global_store_dwordx4 v[12:13], v[4:7], off nt
	v_cndmask_b32_e64 v25, v35, v31, s[4:5]
	v_cndmask_b32_e64 v11, v11, v19, s[4:5]
	v_add_co_u32_e32 v4, vcc, 0x3c000, v12
	v_cndmask_b32_e64 v9, v9, v14, s[4:5]
	s_nop 0
	v_addc_co_u32_e32 v5, vcc, 0, v13, vcc
	s_and_b64 vcc, exec, s[6:7]
	s_mov_b32 s48, s0
	s_mov_b32 s49, s8
	s_mov_b64 s[18:19], s[12:13]
	s_mov_b64 s[14:15], s[10:11]
	global_store_dwordx4 v[20:21], v[24:27], off nt
	global_store_dwordx4 v[4:5], v[8:11], off nt
	s_cbranch_vccz .LBB0_329
	s_waitcnt vmcnt(0)
	v_readlane_b32 s42, v251, 7
	v_readlane_b32 s46, v251, 9
	v_readlane_b32 s48, v251, 13
	s_cmpk_gt_u32 s20, 0xff
	v_readlane_b32 s43, v251, 8
	v_readlane_b32 s47, v251, 10
	v_readlane_b32 s49, v251, 14
	s_cbranch_scc1 .LBB0_336
	s_barrier

; #define PG8_STAGE(bufoff, gbase, voff) do { _Pragma("unroll") for (int _i = 0; _i < 2; ++_i) \
;         __builtin_amdgcn_global_load_lds((const unsigned*)((const char*)(gbase) + (voff)[_i]), (LAS unsigned*)(lds + (bufoff) + ldsw + _i * 8192), 16, 0, 0); } while (0)
; #define PG8_LDA(dst, b, h) do { _Pragma("unroll") for (int m = 0; m < 4; ++m) _Pragma("unroll") for (int k = 0; k < 2; ++k) dst[m][k] = *(const LAS h8*)(lds + PG8_SA(b, h) + aoff + m * 2048 + k * 1024); } while (0)
; #define PG8_LDB(dst, b, h) do { _Pragma("unroll") for (int n = 0; n < 2; ++n) _Pragma("unroll") for (int k = 0; k < 2; ++k) dst[n][k] = *(const LAS h8*)(lds + PG8_SB(b, h) + boff + n * 2048 + k * 1024); } while (0)
; #define PG8_WAIT_V(n) asm volatile("s_waitcnt vmcnt(" #n ")" ::: "memory")
; #define PG8_WAIT_L(n) asm volatile("s_waitcnt lgkmcnt(" #n ")" ::: "memory")
; #define PG8_BAR __builtin_amdgcn_s_barrier()
; #define PG8_SCHED __builtin_amdgcn_sched_barrier(0)
; template <class Epi>
; __device__ __forceinline__ void gemm_phase(LAS unsigned char* lds, const Gemm g, const StaticOrder& S, const Epi& E, const int tid) {
;     ...
;             const bool last = (t == nt - 2);
;             const char* a1 = cA + (size_t)(t + 1) * kstep;
;             const char* a2 = last ? nA : cA + (size_t)(t + 2) * kstep; const char* b2 = last ? nB : cB + (size_t)(t + 2) * kstep;
;             const char* a3 = a2 + kstep; const char* b3 = b2 + kstep;
;             if constexpr (Epi::HAS_MID) { if (t == (nt >> 1)) E.mid(acc, cur, wr, wc, fr, fq); }
;             PG8_LDB(B0, 0, 0); PG8_SCHED; PG8_LDA(At, 0, 0); PG8_STAGE(PG8_SA(1, 1), a1 + hstep, voffA);
;             PG8_WAIT_L(8); PG8_BAR; PG8_WAIT_L(0); PG8_MMA(0, 0, At, B0); PG8_BAR; PG8_SCHED;
;             PG8_LDB(B1, 0, 1); PG8_STAGE(PG8_SB(0, 0), b2, voffB);
;             PG8_BAR; PG8_WAIT_L(0); PG8_MMA(0, 1, At, B1); PG8_BAR;
;             PG8_LDA(At, 0, 1); PG8_STAGE(PG8_SA(0, 0), a2, voffA);
;             PG8_BAR; PG8_WAIT_L(0); PG8_MMA(1, 0, At, B0); PG8_BAR; PG8_SCHED;
;             PG8_STAGE(PG8_SB(0, 1), b2 + hstepB, voffB);
;             PG8_WAIT_V(6); PG8_BAR; PG8_MMA(1, 1, At, B1); PG8_BAR;
.LBB0_594:
	s_add_u32 s14, s10, s12
	s_addc_u32 s15, s11, s13
	s_add_u32 s14, s14, 0x100
	s_addc_u32 s15, s15, 0
	s_add_u32 s55, s52, s12
	s_addc_u32 s56, s53, s13
	s_cmpk_eq_i32 s12, 0x1f00
	s_cselect_b32 s19, s5, s15
	s_cselect_b32 s18, s50, s14
	s_cselect_b32 s15, s1, s56
	s_cselect_b32 s14, s51, s55
	s_add_i32 s55, 0, 0x10000
	v_add_u32_e32 v0, s55, v189
	ds_read_b128 v[132:135], v0
	ds_read_b128 v[136:139], v0 offset:1024
	ds_read_b128 v[176:179], v0 offset:2048
	ds_read_b128 v[192:195], v0 offset:3072
	v_lshl_add_u64 v[0:1], v[172:173], 0, s[12:13]
	s_add_i32 m0, s25, 0xc000
	ds_read_b128 v[196:199], v191
	ds_read_b128 v[200:203], v191 offset:1024
	ds_read_b128 v[204:207], v191 offset:2048
	ds_read_b128 v[208:211], v191 offset:3072
	ds_read_b128 v[212:215], v191 offset:4096
	ds_read_b128 v[216:219], v191 offset:5120
	ds_read_b128 v[220:223], v191 offset:6144
	ds_read_b128 v[224:227], v191 offset:7168
	global_load_lds_dwordx4 v[0:1], off
	v_lshl_add_u64 v[0:1], v[174:175], 0, s[12:13]
	s_add_i32 m0, s25, 0xe000
	s_nop 0
	global_load_lds_dwordx4 v[0:1], off
	s_waitcnt lgkmcnt(8)
	s_barrier
	s_waitcnt lgkmcnt(0)
	v_mfma_f32_16x16x32_bf16 v[128:131], v[132:135], v[196:199], v[128:131]
	v_mfma_f32_16x16x32_bf16 v[124:127], v[176:179], v[196:199], v[124:127]
	v_mfma_f32_16x16x32_bf16 v[112:115], v[132:135], v[204:207], v[112:115]
	v_mfma_f32_16x16x32_bf16 v[108:111], v[176:179], v[204:207], v[108:111]
	v_mfma_f32_16x16x32_bf16 v[96:99], v[132:135], v[212:215], v[96:99]
	v_mfma_f32_16x16x32_bf16 v[92:95], v[176:179], v[212:215], v[92:95]
	v_mfma_f32_16x16x32_bf16 v[80:83], v[132:135], v[220:223], v[80:83]
	v_mfma_f32_16x16x32_bf16 v[76:79], v[176:179], v[220:223], v[76:79]
	v_mfma_f32_16x16x32_bf16 v[128:131], v[136:139], v[200:203], v[128:131]
	v_mfma_f32_16x16x32_bf16 v[124:127], v[192:195], v[200:203], v[124:127]
	v_mfma_f32_16x16x32_bf16 v[112:115], v[136:139], v[208:211], v[112:115]
	v_mfma_f32_16x16x32_bf16 v[108:111], v[192:195], v[208:211], v[108:111]
	v_mfma_f32_16x16x32_bf16 v[96:99], v[136:139], v[216:219], v[96:99]
	v_mfma_f32_16x16x32_bf16 v[92:95], v[192:195], v[216:219], v[92:95]
	v_mfma_f32_16x16x32_bf16 v[80:83], v[136:139], v[224:227], v[80:83]
	v_mfma_f32_16x16x32_bf16 v[76:79], v[192:195], v[224:227], v[76:79]
	s_barrier
	s_add_i32 s58, 0, 0x14000
	v_add_u32_e32 v0, s58, v189
	s_add_i32 s55, s55, s24
	ds_read_b128 v[228:231], v0
	ds_read_b128 v[232:235], v0 offset:1024
	ds_read_b128 v[236:239], v0 offset:2048
	ds_read_b128 v[240:243], v0 offset:3072
	v_lshl_add_u64 v[0:1], s[14:15], 0, v[144:145]
	s_mov_b32 m0, s55
	v_lshl_add_u64 v[244:245], s[14:15], 0, v[140:141]
	global_load_lds_dwordx4 v[0:1], off
	s_add_i32 m0, s55, 0x2000
	s_nop 0
	global_load_lds_dwordx4 v[244:245], off
	s_barrier
	s_waitcnt lgkmcnt(0)
	v_mfma_f32_16x16x32_bf16 v[120:123], v[228:231], v[196:199], v[120:123]
	v_mfma_f32_16x16x32_bf16 v[116:119], v[236:239], v[196:199], v[116:119]
	v_mfma_f32_16x16x32_bf16 v[104:107], v[228:231], v[204:207], v[104:107]
	v_mfma_f32_16x16x32_bf16 v[100:103], v[236:239], v[204:207], v[100:103]
	v_mfma_f32_16x16x32_bf16 v[88:91], v[228:231], v[212:215], v[88:91]
	v_mfma_f32_16x16x32_bf16 v[84:87], v[236:239], v[212:215], v[84:87]
	v_mfma_f32_16x16x32_bf16 v[72:75], v[228:231], v[220:223], v[72:75]
	v_mfma_f32_16x16x32_bf16 v[68:71], v[236:239], v[220:223], v[68:71]
	v_mfma_f32_16x16x32_bf16 v[120:123], v[232:235], v[200:203], v[120:123]
	v_mfma_f32_16x16x32_bf16 v[116:119], v[240:243], v[200:203], v[116:119]
	v_mfma_f32_16x16x32_bf16 v[104:107], v[232:235], v[208:211], v[104:107]
	v_mfma_f32_16x16x32_bf16 v[100:103], v[240:243], v[208:211], v[100:103]
	v_mfma_f32_16x16x32_bf16 v[88:91], v[232:235], v[216:219], v[88:91]
	v_mfma_f32_16x16x32_bf16 v[84:87], v[240:243], v[216:219], v[84:87]
	v_mfma_f32_16x16x32_bf16 v[72:75], v[232:235], v[224:227], v[72:75]
	v_mfma_f32_16x16x32_bf16 v[68:71], v[240:243], v[224:227], v[68:71]
	s_mov_b32 m0, s25
	v_lshl_add_u64 v[246:247], s[18:19], 0, v[146:147]
	s_barrier
	ds_read_b128 v[196:199], v191 offset:16384
	ds_read_b128 v[200:203], v191 offset:17408
	ds_read_b128 v[204:207], v191 offset:18432
	ds_read_b128 v[208:211], v191 offset:19456
	ds_read_b128 v[212:215], v191 offset:20480
	ds_read_b128 v[216:219], v191 offset:21504
	ds_read_b128 v[220:223], v191 offset:22528
	ds_read_b128 v[224:227], v191 offset:23552
	global_load_lds_dwordx4 v[246:247], off
	v_lshl_add_u64 v[248:249], s[18:19], 0, v[142:143]
	s_mov_b32 m0, s42
	s_nop 0
	global_load_lds_dwordx4 v[248:249], off
	s_barrier
	s_waitcnt lgkmcnt(0)
	v_mfma_f32_16x16x32_bf16 v[64:67], v[132:135], v[196:199], v[64:67]
	v_mfma_f32_16x16x32_bf16 v[60:63], v[176:179], v[196:199], v[60:63]
	v_mfma_f32_16x16x32_bf16 v[48:51], v[132:135], v[204:207], v[48:51]
	v_mfma_f32_16x16x32_bf16 v[44:47], v[176:179], v[204:207], v[44:47]
	v_mfma_f32_16x16x32_bf16 v[32:35], v[132:135], v[212:215], v[32:35]
	v_mfma_f32_16x16x32_bf16 v[28:31], v[176:179], v[212:215], v[28:31]
	v_mfma_f32_16x16x32_bf16 v[16:19], v[132:135], v[220:223], v[16:19]
	v_mfma_f32_16x16x32_bf16 v[12:15], v[176:179], v[220:223], v[12:15]
	v_mfma_f32_16x16x32_bf16 v[64:67], v[136:139], v[200:203], v[64:67]
	v_mfma_f32_16x16x32_bf16 v[60:63], v[192:195], v[200:203], v[60:63]
	v_mfma_f32_16x16x32_bf16 v[48:51], v[136:139], v[208:211], v[48:51]
	v_mfma_f32_16x16x32_bf16 v[44:47], v[192:195], v[208:211], v[44:47]
	v_mfma_f32_16x16x32_bf16 v[32:35], v[136:139], v[216:219], v[32:35]
	v_mfma_f32_16x16x32_bf16 v[28:31], v[192:195], v[216:219], v[28:31]
	v_mfma_f32_16x16x32_bf16 v[16:19], v[136:139], v[224:227], v[16:19]
	v_mfma_f32_16x16x32_bf16 v[12:15], v[192:195], v[224:227], v[12:15]
	s_barrier
; #define PG8_STAGE(bufoff, gbase, voff) do { _Pragma("unroll") for (int _i = 0; _i < 2; ++_i) \
;         __builtin_amdgcn_global_load_lds((const unsigned*)((const char*)(gbase) + (voff)[_i]), (LAS unsigned*)(lds + (bufoff) + ldsw + _i * 8192), 16, 0, 0); } while (0)
; #define PG8_LDA(dst, b, h) do { _Pragma("unroll") for (int m = 0; m < 4; ++m) _Pragma("unroll") for (int k = 0; k < 2; ++k) dst[m][k] = *(const LAS h8*)(lds + PG8_SA(b, h) + aoff + m * 2048 + k * 1024); } while (0)
; #define PG8_LDB(dst, b, h) do { _Pragma("unroll") for (int n = 0; n < 2; ++n) _Pragma("unroll") for (int k = 0; k < 2; ++k) dst[n][k] = *(const LAS h8*)(lds + PG8_SB(b, h) + boff + n * 2048 + k * 1024); } while (0)
; #define PG8_WAIT_V(n) asm volatile("s_waitcnt vmcnt(" #n ")" ::: "memory")
; #define PG8_WAIT_L(n) asm volatile("s_waitcnt lgkmcnt(" #n ")" ::: "memory")
; #define PG8_BAR __builtin_amdgcn_s_barrier()
; #define PG8_SCHED __builtin_amdgcn_sched_barrier(0)
; template <class Epi>
; __device__ __forceinline__ void gemm_phase(LAS unsigned char* lds, const Gemm g, const StaticOrder& S, const Epi& E, const int tid) {
;     ...
;             PG8_STAGE(PG8_SB(0, 1), b2 + hstepB, voffB);
;             PG8_WAIT_V(6); PG8_BAR; PG8_MMA(1, 1, At, B1); PG8_BAR;
;             PG8_LDB(B0, 1, 0); PG8_SCHED; PG8_LDA(At, 1, 0); PG8_STAGE(PG8_SA(0, 1), a2 + hstep, voffA);
;             PG8_WAIT_L(8); PG8_BAR; PG8_WAIT_L(0); PG8_MMA(0, 0, At, B0); PG8_BAR; PG8_SCHED;
;             PG8_LDB(B1, 1, 1); PG8_STAGE(PG8_SB(1, 0), b3, voffB);
;             PG8_BAR; PG8_WAIT_L(0); PG8_MMA(0, 1, At, B1); PG8_BAR;
;             PG8_LDA(At, 1, 1); PG8_STAGE(PG8_SA(1, 0), a3, voffA);
	s_add_u32 s56, s14, 0x100000
	s_addc_u32 s57, s15, 0
	s_add_i32 s55, s58, s24
	v_lshl_add_u64 v[132:133], s[56:57], 0, v[144:145]
	s_mov_b32 m0, s55
	s_nop 0
	global_load_lds_dwordx4 v[132:133], off
	v_lshl_add_u64 v[132:133], s[56:57], 0, v[140:141]
	s_add_i32 m0, s55, 0x2000
	s_nop 0
	global_load_lds_dwordx4 v[132:133], off
	s_waitcnt vmcnt(6)
	s_barrier
	v_mfma_f32_16x16x32_bf16 v[56:59], v[228:231], v[196:199], v[56:59]
	v_mfma_f32_16x16x32_bf16 v[52:55], v[236:239], v[196:199], v[52:55]
	v_mfma_f32_16x16x32_bf16 v[40:43], v[228:231], v[204:207], v[40:43]
	v_mfma_f32_16x16x32_bf16 v[36:39], v[236:239], v[204:207], v[36:39]
	v_mfma_f32_16x16x32_bf16 v[24:27], v[228:231], v[212:215], v[24:27]
	v_mfma_f32_16x16x32_bf16 v[20:23], v[236:239], v[212:215], v[20:23]
	v_mfma_f32_16x16x32_bf16 v[8:11], v[228:231], v[220:223], v[8:11]
	v_mfma_f32_16x16x32_bf16 v[4:7], v[236:239], v[220:223], v[4:7]
	v_mfma_f32_16x16x32_bf16 v[56:59], v[232:235], v[200:203], v[56:59]
	v_mfma_f32_16x16x32_bf16 v[52:55], v[240:243], v[200:203], v[52:55]
	v_mfma_f32_16x16x32_bf16 v[40:43], v[232:235], v[208:211], v[40:43]
	v_mfma_f32_16x16x32_bf16 v[36:39], v[240:243], v[208:211], v[36:39]
	v_mfma_f32_16x16x32_bf16 v[24:27], v[232:235], v[216:219], v[24:27]
	v_mfma_f32_16x16x32_bf16 v[20:23], v[240:243], v[216:219], v[20:23]
	v_mfma_f32_16x16x32_bf16 v[8:11], v[232:235], v[224:227], v[8:11]
	v_mfma_f32_16x16x32_bf16 v[4:7], v[240:243], v[224:227], v[4:7]
	s_add_i32 s55, 0, 0x18000
	v_add_u32_e32 v2, s55, v189
	s_barrier
	ds_read_b128 v[132:135], v2
	ds_read_b128 v[136:139], v2 offset:1024
	ds_read_b128 v[176:179], v2 offset:2048
	ds_read_b128 v[192:195], v2 offset:3072
	s_add_u32 s18, s18, 0x100000
	s_addc_u32 s19, s19, 0
	s_mov_b32 m0, s43
	v_lshl_add_u64 v[228:229], s[18:19], 0, v[146:147]
	ds_read_b128 v[196:199], v191 offset:32768
	ds_read_b128 v[200:203], v191 offset:33792
	ds_read_b128 v[204:207], v191 offset:34816
	ds_read_b128 v[208:211], v191 offset:35840
	ds_read_b128 v[212:215], v191 offset:36864
	ds_read_b128 v[216:219], v191 offset:37888
	ds_read_b128 v[220:223], v191 offset:38912
	ds_read_b128 v[224:227], v191 offset:39936
	global_load_lds_dwordx4 v[228:229], off
	v_lshl_add_u64 v[228:229], s[18:19], 0, v[142:143]
	s_mov_b32 m0, s46
	s_nop 0
	global_load_lds_dwordx4 v[228:229], off
	s_waitcnt lgkmcnt(8)
	s_barrier
	s_waitcnt lgkmcnt(0)
	v_mfma_f32_16x16x32_bf16 v[128:131], v[132:135], v[196:199], v[128:131]
	v_mfma_f32_16x16x32_bf16 v[124:127], v[176:179], v[196:199], v[124:127]
	v_mfma_f32_16x16x32_bf16 v[112:115], v[132:135], v[204:207], v[112:115]
	v_mfma_f32_16x16x32_bf16 v[108:111], v[176:179], v[204:207], v[108:111]
	v_mfma_f32_16x16x32_bf16 v[96:99], v[132:135], v[212:215], v[96:99]
	v_mfma_f32_16x16x32_bf16 v[92:95], v[176:179], v[212:215], v[92:95]
	v_mfma_f32_16x16x32_bf16 v[80:83], v[132:135], v[220:223], v[80:83]
	v_mfma_f32_16x16x32_bf16 v[76:79], v[176:179], v[220:223], v[76:79]
	v_mfma_f32_16x16x32_bf16 v[128:131], v[136:139], v[200:203], v[128:131]
	v_mfma_f32_16x16x32_bf16 v[124:127], v[192:195], v[200:203], v[124:127]
	v_mfma_f32_16x16x32_bf16 v[112:115], v[136:139], v[208:211], v[112:115]
	v_mfma_f32_16x16x32_bf16 v[108:111], v[192:195], v[208:211], v[108:111]
	v_mfma_f32_16x16x32_bf16 v[96:99], v[136:139], v[216:219], v[96:99]
	v_mfma_f32_16x16x32_bf16 v[92:95], v[192:195], v[216:219], v[92:95]
	v_mfma_f32_16x16x32_bf16 v[80:83], v[136:139], v[224:227], v[80:83]
	v_mfma_f32_16x16x32_bf16 v[76:79], v[192:195], v[224:227], v[76:79]
	s_barrier
	s_add_i32 s18, 0, 0x1c000
	s_add_i32 s19, s55, s24
	v_add_u32_e32 v2, s18, v189
	v_lshl_add_u64 v[0:1], v[0:1], 0, s[30:31]
	s_mov_b32 m0, s19
	ds_read_b128 v[228:231], v2
	ds_read_b128 v[232:235], v2 offset:1024
	ds_read_b128 v[236:239], v2 offset:2048
	ds_read_b128 v[240:243], v2 offset:3072
	global_load_lds_dwordx4 v[0:1], off
	v_lshl_add_u64 v[0:1], v[244:245], 0, s[30:31]
	s_add_i32 m0, s19, 0x2000
	s_nop 0
	global_load_lds_dwordx4 v[0:1], off
	s_barrier
; #define PG8_STAGE(bufoff, gbase, voff) do { _Pragma("unroll") for (int _i = 0; _i < 2; ++_i) \
;         __builtin_amdgcn_global_load_lds((const unsigned*)((const char*)(gbase) + (voff)[_i]), (LAS unsigned*)(lds + (bufoff) + ldsw + _i * 8192), 16, 0, 0); } while (0)
; #define PG8_LDA(dst, b, h) do { _Pragma("unroll") for (int m = 0; m < 4; ++m) _Pragma("unroll") for (int k = 0; k < 2; ++k) dst[m][k] = *(const LAS h8*)(lds + PG8_SA(b, h) + aoff + m * 2048 + k * 1024); } while (0)
; #define PG8_WAIT_V(n) asm volatile("s_waitcnt vmcnt(" #n ")" ::: "memory")
; #define PG8_WAIT_L(n) asm volatile("s_waitcnt lgkmcnt(" #n ")" ::: "memory")
; #define PG8_BAR __builtin_amdgcn_s_barrier()
; #define PG8_SCHED __builtin_amdgcn_sched_barrier(0)
; template <class Epi>
; __device__ __forceinline__ void gemm_phase(LAS unsigned char* lds, const Gemm g, const StaticOrder& S, const Epi& E, const int tid) {
;     ...
;             PG8_LDA(At, 1, 1); PG8_STAGE(PG8_SA(1, 0), a3, voffA);
;             PG8_BAR; PG8_WAIT_L(0); PG8_MMA(1, 0, At, B0); PG8_BAR; PG8_SCHED;
;             PG8_STAGE(PG8_SB(1, 1), b3 + hstepB, voffB);
;             PG8_WAIT_V(6); PG8_BAR; PG8_MMA(1, 1, At, B1); PG8_BAR;
	s_waitcnt lgkmcnt(0)
	v_mfma_f32_16x16x32_bf16 v[120:123], v[228:231], v[196:199], v[120:123]
	v_mfma_f32_16x16x32_bf16 v[116:119], v[236:239], v[196:199], v[116:119]
	v_mfma_f32_16x16x32_bf16 v[104:107], v[228:231], v[204:207], v[104:107]
	v_mfma_f32_16x16x32_bf16 v[100:103], v[236:239], v[204:207], v[100:103]
	v_mfma_f32_16x16x32_bf16 v[88:91], v[228:231], v[212:215], v[88:91]
	v_mfma_f32_16x16x32_bf16 v[84:87], v[236:239], v[212:215], v[84:87]
	v_mfma_f32_16x16x32_bf16 v[72:75], v[228:231], v[220:223], v[72:75]
	v_mfma_f32_16x16x32_bf16 v[68:71], v[236:239], v[220:223], v[68:71]
	v_mfma_f32_16x16x32_bf16 v[120:123], v[232:235], v[200:203], v[120:123]
	v_mfma_f32_16x16x32_bf16 v[116:119], v[240:243], v[200:203], v[116:119]
	v_mfma_f32_16x16x32_bf16 v[104:107], v[232:235], v[208:211], v[104:107]
	v_mfma_f32_16x16x32_bf16 v[100:103], v[240:243], v[208:211], v[100:103]
	v_mfma_f32_16x16x32_bf16 v[88:91], v[232:235], v[216:219], v[88:91]
	v_mfma_f32_16x16x32_bf16 v[84:87], v[240:243], v[216:219], v[84:87]
	v_mfma_f32_16x16x32_bf16 v[72:75], v[232:235], v[224:227], v[72:75]
	v_mfma_f32_16x16x32_bf16 v[68:71], v[240:243], v[224:227], v[68:71]
	s_mov_b32 m0, s47
	v_lshl_add_u64 v[0:1], v[246:247], 0, s[30:31]
	s_barrier
	ds_read_b128 v[196:199], v191 offset:49152
	ds_read_b128 v[200:203], v191 offset:50176
	ds_read_b128 v[204:207], v191 offset:51200
	ds_read_b128 v[208:211], v191 offset:52224
	ds_read_b128 v[212:215], v191 offset:53248
	ds_read_b128 v[216:219], v191 offset:54272
	ds_read_b128 v[220:223], v191 offset:55296
	ds_read_b128 v[224:227], v191 offset:56320
	global_load_lds_dwordx4 v[0:1], off
	v_lshl_add_u64 v[0:1], v[248:249], 0, s[30:31]
	s_mov_b32 m0, s48
	s_nop 0
	global_load_lds_dwordx4 v[0:1], off
	s_barrier
	s_waitcnt lgkmcnt(0)
	v_mfma_f32_16x16x32_bf16 v[64:67], v[132:135], v[196:199], v[64:67]
	v_mfma_f32_16x16x32_bf16 v[60:63], v[176:179], v[196:199], v[60:63]
	v_mfma_f32_16x16x32_bf16 v[48:51], v[132:135], v[204:207], v[48:51]
	v_mfma_f32_16x16x32_bf16 v[44:47], v[176:179], v[204:207], v[44:47]
	v_mfma_f32_16x16x32_bf16 v[32:35], v[132:135], v[212:215], v[32:35]
	v_mfma_f32_16x16x32_bf16 v[28:31], v[176:179], v[212:215], v[28:31]
	v_mfma_f32_16x16x32_bf16 v[16:19], v[132:135], v[220:223], v[16:19]
	v_mfma_f32_16x16x32_bf16 v[12:15], v[176:179], v[220:223], v[12:15]
	v_mfma_f32_16x16x32_bf16 v[64:67], v[136:139], v[200:203], v[64:67]
	v_mfma_f32_16x16x32_bf16 v[60:63], v[192:195], v[200:203], v[60:63]
	v_mfma_f32_16x16x32_bf16 v[48:51], v[136:139], v[208:211], v[48:51]
	v_mfma_f32_16x16x32_bf16 v[44:47], v[192:195], v[208:211], v[44:47]
	v_mfma_f32_16x16x32_bf16 v[32:35], v[136:139], v[216:219], v[32:35]
	v_mfma_f32_16x16x32_bf16 v[28:31], v[192:195], v[216:219], v[28:31]
	v_mfma_f32_16x16x32_bf16 v[16:19], v[136:139], v[224:227], v[16:19]
	v_mfma_f32_16x16x32_bf16 v[12:15], v[192:195], v[224:227], v[12:15]
	s_barrier
	s_add_u32 s14, s14, 0x100080
	s_addc_u32 s15, s15, 0
	s_add_i32 s18, s18, s24
	v_lshl_add_u64 v[0:1], s[14:15], 0, v[144:145]
	s_mov_b32 m0, s18
	s_nop 0
	global_load_lds_dwordx4 v[0:1], off
	v_lshl_add_u64 v[0:1], s[14:15], 0, v[140:141]
	s_add_i32 m0, s18, 0x2000
	s_nop 0
	global_load_lds_dwordx4 v[0:1], off
	s_waitcnt vmcnt(6)
	s_barrier
	v_mfma_f32_16x16x32_bf16 v[56:59], v[228:231], v[196:199], v[56:59]
	v_mfma_f32_16x16x32_bf16 v[52:55], v[236:239], v[196:199], v[52:55]
	v_mfma_f32_16x16x32_bf16 v[40:43], v[228:231], v[204:207], v[40:43]
	v_mfma_f32_16x16x32_bf16 v[36:39], v[236:239], v[204:207], v[36:39]
	v_mfma_f32_16x16x32_bf16 v[24:27], v[228:231], v[212:215], v[24:27]
	v_mfma_f32_16x16x32_bf16 v[20:23], v[236:239], v[212:215], v[20:23]
	v_mfma_f32_16x16x32_bf16 v[8:11], v[228:231], v[220:223], v[8:11]
	v_mfma_f32_16x16x32_bf16 v[4:7], v[236:239], v[220:223], v[4:7]
	v_mfma_f32_16x16x32_bf16 v[56:59], v[232:235], v[200:203], v[56:59]
	v_mfma_f32_16x16x32_bf16 v[52:55], v[240:243], v[200:203], v[52:55]
	v_mfma_f32_16x16x32_bf16 v[40:43], v[232:235], v[208:211], v[40:43]
	v_mfma_f32_16x16x32_bf16 v[36:39], v[240:243], v[208:211], v[36:39]
	v_mfma_f32_16x16x32_bf16 v[24:27], v[232:235], v[216:219], v[24:27]
	v_mfma_f32_16x16x32_bf16 v[20:23], v[240:243], v[216:219], v[20:23]
	v_mfma_f32_16x16x32_bf16 v[8:11], v[232:235], v[224:227], v[8:11]
	v_mfma_f32_16x16x32_bf16 v[4:7], v[240:243], v[224:227], v[4:7]
	s_add_i32 s54, s54, 2
	s_add_u32 s12, s12, 0x100
	s_addc_u32 s13, s13, 0
	s_cmp_gt_u32 s54, 61
	s_barrier
	s_cbranch_scc1 .LBB0_586

; #define PG8_STAGE(bufoff, gbase, voff) do { _Pragma("unroll") for (int _i = 0; _i < 2; ++_i) \
;         __builtin_amdgcn_global_load_lds((const unsigned*)((const char*)(gbase) + (voff)[_i]), (LAS unsigned*)(lds + (bufoff) + ldsw + _i * 8192), 16, 0, 0); } while (0)
; #define PG8_LDA(dst, b, h) do { _Pragma("unroll") for (int m = 0; m < 4; ++m) _Pragma("unroll") for (int k = 0; k < 2; ++k) dst[m][k] = *(const LAS h8*)(lds + PG8_SA(b, h) + aoff + m * 2048 + k * 1024); } while (0)
; #define PG8_LDB(dst, b, h) do { _Pragma("unroll") for (int n = 0; n < 2; ++n) _Pragma("unroll") for (int k = 0; k < 2; ++k) dst[n][k] = *(const LAS h8*)(lds + PG8_SB(b, h) + boff + n * 2048 + k * 1024); } while (0)
; #define PG8_WAIT_V(n) asm volatile("s_waitcnt vmcnt(" #n ")" ::: "memory")
; #define PG8_WAIT_L(n) asm volatile("s_waitcnt lgkmcnt(" #n ")" ::: "memory")
; #define PG8_BAR __builtin_amdgcn_s_barrier()
; #define PG8_SCHED __builtin_amdgcn_sched_barrier(0)
; template <class Epi>
; __device__ __forceinline__ void gemm_phase(LAS unsigned char* lds, const Gemm g, const StaticOrder& S, const Epi& E, const int tid) {
;     ...
;             const bool last = (t == nt - 2);
;             const char* a1 = cA + (size_t)(t + 1) * kstep;
;             const char* a2 = last ? nA : cA + (size_t)(t + 2) * kstep; const char* b2 = last ? nB : cB + (size_t)(t + 2) * kstep;
;             const char* a3 = a2 + kstep; const char* b3 = b2 + kstep;
;             if constexpr (Epi::HAS_MID) { if (t == (nt >> 1)) E.mid(acc, cur, wr, wc, fr, fq); }
;             PG8_LDB(B0, 0, 0); PG8_SCHED; PG8_LDA(At, 0, 0); PG8_STAGE(PG8_SA(1, 1), a1 + hstep, voffA);
;             PG8_WAIT_L(8); PG8_BAR; PG8_WAIT_L(0); PG8_MMA(0, 0, At, B0); PG8_BAR; PG8_SCHED;
;             PG8_LDB(B1, 0, 1); PG8_STAGE(PG8_SB(0, 0), b2, voffB);
;             PG8_BAR; PG8_WAIT_L(0); PG8_MMA(0, 1, At, B1); PG8_BAR;
;             PG8_LDA(At, 0, 1); PG8_STAGE(PG8_SA(0, 0), a2, voffA);
;             PG8_BAR; PG8_WAIT_L(0); PG8_MMA(1, 0, At, B0); PG8_BAR; PG8_SCHED;
;             PG8_STAGE(PG8_SB(0, 1), b2 + hstepB, voffB);
;             PG8_WAIT_V(6); PG8_BAR; PG8_MMA(1, 1, At, B1); PG8_BAR;
.LBB0_660:
	s_add_u32 s14, s12, 0xfff80080
	s_addc_u32 s15, s13, -1
	s_add_i32 s57, 0, 0x10000
	v_add_u32_e32 v64, s57, v190
	ds_read_b128 v[28:31], v64
	ds_read_b128 v[32:35], v64 offset:1024
	ds_read_b128 v[60:63], v64 offset:2048
	ds_read_b128 v[64:67], v64 offset:3072
	s_cmp_eq_u32 s56, 28
	s_cselect_b32 s19, s7, s15
	s_cselect_b32 s18, s52, s14
	s_cselect_b32 s15, s1, s55
	s_cselect_b32 s14, s53, s54
	v_lshl_add_u64 v[174:175], s[12:13], 0, v[166:167]
	s_add_i32 m0, s41, 0xc000
	ds_read_b128 v[170:173], v192
	ds_read_b128 v[194:197], v192 offset:1024
	ds_read_b128 v[198:201], v192 offset:2048
	ds_read_b128 v[202:205], v192 offset:3072
	ds_read_b128 v[206:209], v192 offset:4096
	ds_read_b128 v[210:213], v192 offset:5120
	ds_read_b128 v[214:217], v192 offset:6144
	ds_read_b128 v[218:221], v192 offset:7168
	global_load_lds_dwordx4 v[174:175], off
	v_lshl_add_u64 v[174:175], s[12:13], 0, v[168:169]
	s_add_i32 m0, s41, 0xe000
	s_nop 0
	global_load_lds_dwordx4 v[174:175], off
	s_waitcnt lgkmcnt(8)
	s_barrier
	s_waitcnt lgkmcnt(0)
	v_mfma_f32_16x16x32_bf16 v[144:147], v[28:31], v[170:173], v[144:147]
	v_mfma_f32_16x16x32_bf16 v[140:143], v[60:63], v[170:173], v[140:143]
	v_mfma_f32_16x16x32_bf16 v[128:131], v[28:31], v[198:201], v[128:131]
	v_mfma_f32_16x16x32_bf16 v[124:127], v[60:63], v[198:201], v[124:127]
	v_mfma_f32_16x16x32_bf16 v[112:115], v[28:31], v[206:209], v[112:115]
	v_mfma_f32_16x16x32_bf16 v[108:111], v[60:63], v[206:209], v[108:111]
	v_mfma_f32_16x16x32_bf16 v[96:99], v[28:31], v[214:217], v[96:99]
	v_mfma_f32_16x16x32_bf16 v[92:95], v[60:63], v[214:217], v[92:95]
	v_mfma_f32_16x16x32_bf16 v[144:147], v[32:35], v[194:197], v[144:147]
	v_mfma_f32_16x16x32_bf16 v[140:143], v[64:67], v[194:197], v[140:143]
	v_mfma_f32_16x16x32_bf16 v[128:131], v[32:35], v[202:205], v[128:131]
	v_mfma_f32_16x16x32_bf16 v[124:127], v[64:67], v[202:205], v[124:127]
	v_mfma_f32_16x16x32_bf16 v[112:115], v[32:35], v[210:213], v[112:115]
	v_mfma_f32_16x16x32_bf16 v[108:111], v[64:67], v[210:213], v[108:111]
	v_mfma_f32_16x16x32_bf16 v[96:99], v[32:35], v[218:221], v[96:99]
	v_mfma_f32_16x16x32_bf16 v[92:95], v[64:67], v[218:221], v[92:95]
	s_barrier
	s_add_i32 s60, 0, 0x14000
	v_add_u32_e32 v174, s60, v190
	s_add_i32 s57, s57, s40
	ds_read_b128 v[222:225], v174
	ds_read_b128 v[226:229], v174 offset:1024
	ds_read_b128 v[230:233], v174 offset:2048
	ds_read_b128 v[234:237], v174 offset:3072
	v_lshl_add_u64 v[174:175], s[14:15], 0, v[2:3]
	s_mov_b32 m0, s57
	v_lshl_add_u64 v[238:239], s[14:15], 0, v[0:1]
	global_load_lds_dwordx4 v[174:175], off
	s_add_i32 m0, s57, 0x2000
	s_nop 0
	global_load_lds_dwordx4 v[238:239], off
	s_barrier
	s_waitcnt lgkmcnt(0)
	v_mfma_f32_16x16x32_bf16 v[136:139], v[222:225], v[170:173], v[136:139]
	v_mfma_f32_16x16x32_bf16 v[132:135], v[230:233], v[170:173], v[132:135]
	v_mfma_f32_16x16x32_bf16 v[120:123], v[222:225], v[198:201], v[120:123]
	v_mfma_f32_16x16x32_bf16 v[116:119], v[230:233], v[198:201], v[116:119]
	v_mfma_f32_16x16x32_bf16 v[104:107], v[222:225], v[206:209], v[104:107]
	v_mfma_f32_16x16x32_bf16 v[100:103], v[230:233], v[206:209], v[100:103]
	v_mfma_f32_16x16x32_bf16 v[88:91], v[222:225], v[214:217], v[88:91]
	v_mfma_f32_16x16x32_bf16 v[84:87], v[230:233], v[214:217], v[84:87]
	v_mfma_f32_16x16x32_bf16 v[136:139], v[226:229], v[194:197], v[136:139]
	v_mfma_f32_16x16x32_bf16 v[132:135], v[234:237], v[194:197], v[132:135]
	v_mfma_f32_16x16x32_bf16 v[120:123], v[226:229], v[202:205], v[120:123]
	v_mfma_f32_16x16x32_bf16 v[116:119], v[234:237], v[202:205], v[116:119]
	v_mfma_f32_16x16x32_bf16 v[104:107], v[226:229], v[210:213], v[104:107]
	v_mfma_f32_16x16x32_bf16 v[100:103], v[234:237], v[210:213], v[100:103]
	v_mfma_f32_16x16x32_bf16 v[88:91], v[226:229], v[218:221], v[88:91]
	v_mfma_f32_16x16x32_bf16 v[84:87], v[234:237], v[218:221], v[84:87]
	s_mov_b32 m0, s41
	v_lshl_add_u64 v[240:241], s[18:19], 0, v[164:165]
	s_barrier
	ds_read_b128 v[170:173], v192 offset:16384
	ds_read_b128 v[194:197], v192 offset:17408
	ds_read_b128 v[198:201], v192 offset:18432
	ds_read_b128 v[202:205], v192 offset:19456
	ds_read_b128 v[206:209], v192 offset:20480
	ds_read_b128 v[210:213], v192 offset:21504
	ds_read_b128 v[214:217], v192 offset:22528
	ds_read_b128 v[218:221], v192 offset:23552
	global_load_lds_dwordx4 v[240:241], off
	v_lshl_add_u64 v[242:243], s[18:19], 0, v[162:163]
	s_mov_b32 m0, s42
	s_nop 0
	global_load_lds_dwordx4 v[242:243], off
	s_barrier
	s_waitcnt lgkmcnt(0)
	v_mfma_f32_16x16x32_bf16 v[80:83], v[28:31], v[170:173], v[80:83]
	v_mfma_f32_16x16x32_bf16 v[76:79], v[60:63], v[170:173], v[76:79]
	v_mfma_f32_16x16x32_bf16 v[56:59], v[28:31], v[198:201], v[56:59]
	v_mfma_f32_16x16x32_bf16 v[52:55], v[60:63], v[198:201], v[52:55]
	v_mfma_f32_16x16x32_bf16 v[40:43], v[28:31], v[206:209], v[40:43]
	v_mfma_f32_16x16x32_bf16 v[36:39], v[60:63], v[206:209], v[36:39]
	v_mfma_f32_16x16x32_bf16 v[16:19], v[28:31], v[214:217], v[16:19]
	v_mfma_f32_16x16x32_bf16 v[12:15], v[60:63], v[214:217], v[12:15]
	v_mfma_f32_16x16x32_bf16 v[80:83], v[32:35], v[194:197], v[80:83]
	v_mfma_f32_16x16x32_bf16 v[76:79], v[64:67], v[194:197], v[76:79]
	v_mfma_f32_16x16x32_bf16 v[56:59], v[32:35], v[202:205], v[56:59]
	v_mfma_f32_16x16x32_bf16 v[52:55], v[64:67], v[202:205], v[52:55]
	v_mfma_f32_16x16x32_bf16 v[40:43], v[32:35], v[210:213], v[40:43]
	v_mfma_f32_16x16x32_bf16 v[36:39], v[64:67], v[210:213], v[36:39]
	v_mfma_f32_16x16x32_bf16 v[16:19], v[32:35], v[218:221], v[16:19]
	v_mfma_f32_16x16x32_bf16 v[12:15], v[64:67], v[218:221], v[12:15]
	s_barrier
; #define PG8_STAGE(bufoff, gbase, voff) do { _Pragma("unroll") for (int _i = 0; _i < 2; ++_i) \
;         __builtin_amdgcn_global_load_lds((const unsigned*)((const char*)(gbase) + (voff)[_i]), (LAS unsigned*)(lds + (bufoff) + ldsw + _i * 8192), 16, 0, 0); } while (0)
; #define PG8_LDA(dst, b, h) do { _Pragma("unroll") for (int m = 0; m < 4; ++m) _Pragma("unroll") for (int k = 0; k < 2; ++k) dst[m][k] = *(const LAS h8*)(lds + PG8_SA(b, h) + aoff + m * 2048 + k * 1024); } while (0)
; #define PG8_LDB(dst, b, h) do { _Pragma("unroll") for (int n = 0; n < 2; ++n) _Pragma("unroll") for (int k = 0; k < 2; ++k) dst[n][k] = *(const LAS h8*)(lds + PG8_SB(b, h) + boff + n * 2048 + k * 1024); } while (0)
; #define PG8_WAIT_V(n) asm volatile("s_waitcnt vmcnt(" #n ")" ::: "memory")
; #define PG8_WAIT_L(n) asm volatile("s_waitcnt lgkmcnt(" #n ")" ::: "memory")
; #define PG8_BAR __builtin_amdgcn_s_barrier()
; #define PG8_SCHED __builtin_amdgcn_sched_barrier(0)
; template <class Epi>
; __device__ __forceinline__ void gemm_phase(LAS unsigned char* lds, const Gemm g, const StaticOrder& S, const Epi& E, const int tid) {
;     ...
;             PG8_STAGE(PG8_SB(0, 1), b2 + hstepB, voffB);
;             PG8_WAIT_V(6); PG8_BAR; PG8_MMA(1, 1, At, B1); PG8_BAR;
;             PG8_LDB(B0, 1, 0); PG8_SCHED; PG8_LDA(At, 1, 0); PG8_STAGE(PG8_SA(0, 1), a2 + hstep, voffA);
;             PG8_WAIT_L(8); PG8_BAR; PG8_WAIT_L(0); PG8_MMA(0, 0, At, B0); PG8_BAR; PG8_SCHED;
;             PG8_LDB(B1, 1, 1); PG8_STAGE(PG8_SB(1, 0), b3, voffB);
;             PG8_BAR; PG8_WAIT_L(0); PG8_MMA(0, 1, At, B1); PG8_BAR;
;             PG8_LDA(At, 1, 1); PG8_STAGE(PG8_SA(1, 0), a3, voffA);
;             PG8_BAR; PG8_WAIT_L(0); PG8_MMA(1, 0, At, B0); PG8_BAR; PG8_SCHED;
;             PG8_STAGE(PG8_SB(1, 1), b3 + hstepB, voffB);
	s_add_u32 s58, s14, 0x80000
	s_addc_u32 s59, s15, 0
	s_add_i32 s57, s60, s40
	v_lshl_add_u64 v[28:29], s[58:59], 0, v[2:3]
	s_mov_b32 m0, s57
	s_nop 0
	global_load_lds_dwordx4 v[28:29], off
	v_lshl_add_u64 v[28:29], s[58:59], 0, v[0:1]
	s_add_i32 m0, s57, 0x2000
	s_nop 0
	global_load_lds_dwordx4 v[28:29], off
	s_waitcnt vmcnt(6)
	s_barrier
	v_mfma_f32_16x16x32_bf16 v[48:51], v[222:225], v[198:201], v[48:51]
	v_mfma_f32_16x16x32_bf16 v[44:47], v[230:233], v[198:201], v[44:47]
	v_mfma_f32_16x16x32_bf16 v[24:27], v[222:225], v[206:209], v[24:27]
	v_mfma_f32_16x16x32_bf16 v[20:23], v[230:233], v[206:209], v[20:23]
	v_mfma_f32_16x16x32_bf16 v[8:11], v[222:225], v[214:217], v[8:11]
	v_mfma_f32_16x16x32_bf16 v[4:7], v[230:233], v[214:217], v[4:7]
	v_mfma_f32_16x16x32_bf16 v[28:31], v[222:225], v[170:173], v[72:75]
	v_mfma_f32_16x16x32_bf16 v[32:35], v[230:233], v[170:173], v[68:71]
	v_mfma_f32_16x16x32_bf16 v[48:51], v[226:229], v[202:205], v[48:51]
	v_mfma_f32_16x16x32_bf16 v[44:47], v[234:237], v[202:205], v[44:47]
	v_mfma_f32_16x16x32_bf16 v[24:27], v[226:229], v[210:213], v[24:27]
	v_mfma_f32_16x16x32_bf16 v[20:23], v[234:237], v[210:213], v[20:23]
	v_mfma_f32_16x16x32_bf16 v[8:11], v[226:229], v[218:221], v[8:11]
	v_mfma_f32_16x16x32_bf16 v[4:7], v[234:237], v[218:221], v[4:7]
	v_mfma_f32_16x16x32_bf16 v[28:31], v[226:229], v[194:197], v[28:31]
	v_mfma_f32_16x16x32_bf16 v[32:35], v[234:237], v[194:197], v[32:35]
	s_add_i32 s57, 0, 0x18000
	v_add_u32_e32 v72, s57, v190
	s_barrier
	ds_read_b128 v[60:63], v72
	ds_read_b128 v[64:67], v72 offset:1024
	ds_read_b128 v[68:71], v72 offset:2048
	ds_read_b128 v[72:75], v72 offset:3072
	s_add_u32 s18, s18, 0x80000
	s_addc_u32 s19, s19, 0
	s_mov_b32 m0, s43
	v_lshl_add_u64 v[222:223], s[18:19], 0, v[164:165]
	ds_read_b128 v[170:173], v192 offset:32768
	ds_read_b128 v[194:197], v192 offset:33792
	ds_read_b128 v[198:201], v192 offset:34816
	ds_read_b128 v[202:205], v192 offset:35840
	ds_read_b128 v[206:209], v192 offset:36864
	ds_read_b128 v[210:213], v192 offset:37888
	ds_read_b128 v[214:217], v192 offset:38912
	ds_read_b128 v[218:221], v192 offset:39936
	global_load_lds_dwordx4 v[222:223], off
	v_lshl_add_u64 v[222:223], s[18:19], 0, v[162:163]
	s_mov_b32 m0, s46
	s_nop 0
	global_load_lds_dwordx4 v[222:223], off
	s_waitcnt lgkmcnt(8)
	s_barrier
	s_waitcnt lgkmcnt(0)
	v_mfma_f32_16x16x32_bf16 v[144:147], v[60:63], v[170:173], v[144:147]
	v_mfma_f32_16x16x32_bf16 v[140:143], v[68:71], v[170:173], v[140:143]
	v_mfma_f32_16x16x32_bf16 v[128:131], v[60:63], v[198:201], v[128:131]
	v_mfma_f32_16x16x32_bf16 v[124:127], v[68:71], v[198:201], v[124:127]
	v_mfma_f32_16x16x32_bf16 v[112:115], v[60:63], v[206:209], v[112:115]
	v_mfma_f32_16x16x32_bf16 v[108:111], v[68:71], v[206:209], v[108:111]
	v_mfma_f32_16x16x32_bf16 v[96:99], v[60:63], v[214:217], v[96:99]
	v_mfma_f32_16x16x32_bf16 v[92:95], v[68:71], v[214:217], v[92:95]
	v_mfma_f32_16x16x32_bf16 v[144:147], v[64:67], v[194:197], v[144:147]
	v_mfma_f32_16x16x32_bf16 v[140:143], v[72:75], v[194:197], v[140:143]
	v_mfma_f32_16x16x32_bf16 v[128:131], v[64:67], v[202:205], v[128:131]
	v_mfma_f32_16x16x32_bf16 v[124:127], v[72:75], v[202:205], v[124:127]
	v_mfma_f32_16x16x32_bf16 v[112:115], v[64:67], v[210:213], v[112:115]
	v_mfma_f32_16x16x32_bf16 v[108:111], v[72:75], v[210:213], v[108:111]
	v_mfma_f32_16x16x32_bf16 v[96:99], v[64:67], v[218:221], v[96:99]
	v_mfma_f32_16x16x32_bf16 v[92:95], v[72:75], v[218:221], v[92:95]
	s_barrier
	s_add_i32 s18, 0, 0x1c000
	s_add_i32 s19, s57, s40
	v_add_u32_e32 v193, s18, v190
	v_lshl_add_u64 v[174:175], v[174:175], 0, s[30:31]
	s_mov_b32 m0, s19
	ds_read_b128 v[222:225], v193
	ds_read_b128 v[226:229], v193 offset:1024
	ds_read_b128 v[230:233], v193 offset:2048
	ds_read_b128 v[234:237], v193 offset:3072
	global_load_lds_dwordx4 v[174:175], off
	v_lshl_add_u64 v[174:175], v[238:239], 0, s[30:31]
	s_add_i32 m0, s19, 0x2000
	s_nop 0
	global_load_lds_dwordx4 v[174:175], off
	s_barrier
	s_waitcnt lgkmcnt(0)
	v_mfma_f32_16x16x32_bf16 v[136:139], v[222:225], v[170:173], v[136:139]
	v_mfma_f32_16x16x32_bf16 v[132:135], v[230:233], v[170:173], v[132:135]
	v_mfma_f32_16x16x32_bf16 v[120:123], v[222:225], v[198:201], v[120:123]
	v_mfma_f32_16x16x32_bf16 v[116:119], v[230:233], v[198:201], v[116:119]
	v_mfma_f32_16x16x32_bf16 v[104:107], v[222:225], v[206:209], v[104:107]
	v_mfma_f32_16x16x32_bf16 v[100:103], v[230:233], v[206:209], v[100:103]
	v_mfma_f32_16x16x32_bf16 v[88:91], v[222:225], v[214:217], v[88:91]
	v_mfma_f32_16x16x32_bf16 v[84:87], v[230:233], v[214:217], v[84:87]
	v_mfma_f32_16x16x32_bf16 v[136:139], v[226:229], v[194:197], v[136:139]
	v_mfma_f32_16x16x32_bf16 v[132:135], v[234:237], v[194:197], v[132:135]
	v_mfma_f32_16x16x32_bf16 v[120:123], v[226:229], v[202:205], v[120:123]
	v_mfma_f32_16x16x32_bf16 v[116:119], v[234:237], v[202:205], v[116:119]
	v_mfma_f32_16x16x32_bf16 v[104:107], v[226:229], v[210:213], v[104:107]
	v_mfma_f32_16x16x32_bf16 v[100:103], v[234:237], v[210:213], v[100:103]
	v_mfma_f32_16x16x32_bf16 v[88:91], v[226:229], v[218:221], v[88:91]
	v_mfma_f32_16x16x32_bf16 v[84:87], v[234:237], v[218:221], v[84:87]
	s_mov_b32 m0, s47
	v_lshl_add_u64 v[174:175], v[240:241], 0, s[30:31]
	s_barrier
	ds_read_b128 v[170:173], v192 offset:49152
	ds_read_b128 v[194:197], v192 offset:50176
	ds_read_b128 v[198:201], v192 offset:51200
	ds_read_b128 v[202:205], v192 offset:52224
	ds_read_b128 v[206:209], v192 offset:53248
	ds_read_b128 v[210:213], v192 offset:54272
	ds_read_b128 v[214:217], v192 offset:55296
	ds_read_b128 v[218:221], v192 offset:56320
	global_load_lds_dwordx4 v[174:175], off
	v_lshl_add_u64 v[174:175], v[242:243], 0, s[30:31]
	s_mov_b32 m0, s48
	s_nop 0
	global_load_lds_dwordx4 v[174:175], off
	s_barrier
; #define PG8_STAGE(bufoff, gbase, voff) do { _Pragma("unroll") for (int _i = 0; _i < 2; ++_i) \
;         __builtin_amdgcn_global_load_lds((const unsigned*)((const char*)(gbase) + (voff)[_i]), (LAS unsigned*)(lds + (bufoff) + ldsw + _i * 8192), 16, 0, 0); } while (0)
; #define PG8_WAIT_V(n) asm volatile("s_waitcnt vmcnt(" #n ")" ::: "memory")
; #define PG8_WAIT_L(n) asm volatile("s_waitcnt lgkmcnt(" #n ")" ::: "memory")
; #define PG8_BAR __builtin_amdgcn_s_barrier()
; #define PG8_SCHED __builtin_amdgcn_sched_barrier(0)
; template <class Epi>
; __device__ __forceinline__ void gemm_phase(LAS unsigned char* lds, const Gemm g, const StaticOrder& S, const Epi& E, const int tid) {
;     ...
;             PG8_BAR; PG8_WAIT_L(0); PG8_MMA(1, 0, At, B0); PG8_BAR; PG8_SCHED;
;             PG8_STAGE(PG8_SB(1, 1), b3 + hstepB, voffB);
;             PG8_WAIT_V(6); PG8_BAR; PG8_MMA(1, 1, At, B1); PG8_BAR;
;     __device__ __forceinline__ void operator()(const f32x4 (&acc)[2][2][4][2], const pg8::Unit& u, int wr, int wc, int fr, int fq) const {
;         const int row0 = u.pm * 256 + wr * 64 + fr, col0 = u.pn * 256 + wc * 32 + 8 * fq;
;         const float* gp = gate + (size_t)((u.pm * 256) >> 12) * 6144 + col0;
;         f32x4 gv[2][2];
; #pragma unroll
;         for (int bj = 0; bj < 2; ++bj)
; #pragma unroll
;             for (int n = 0; n < 2; ++n) gv[bj][n] = *(const f32x4*)(gp + bj * 128 + 4 * n);
; #pragma unroll
;         for (int ai = 0; ai < 2; ++ai)
; #pragma unroll
;             for (int m = 0; m < 4; ++m) { const size_t ro = (size_t)(row0 + ai * 128 + m * 16) * DM + col0;
; #pragma unroll
;                 for (int bj = 0; bj < 2; ++bj) {
;                     f32x4 x0, x1;
;                     if (XF32) { x0 = *(const f32x4*)(xin + ro + bj * 128); x1 = *(const f32x4*)(xin + ro + bj * 128 + 4); }
;                     else { const h8 xh = *(const h8*)(H + ro + bj * 128); x0 = (f32x4){(float)xh[0], (float)xh[1], (float)xh[2], (float)xh[3]}; x1 = (f32x4){(float)xh[4], (float)xh[5], (float)xh[6], (float)xh[7]}; }
	s_waitcnt lgkmcnt(0)
	v_mfma_f32_16x16x32_bf16 v[80:83], v[60:63], v[170:173], v[80:83]
	v_mfma_f32_16x16x32_bf16 v[76:79], v[68:71], v[170:173], v[76:79]
	v_mfma_f32_16x16x32_bf16 v[56:59], v[60:63], v[198:201], v[56:59]
	v_mfma_f32_16x16x32_bf16 v[52:55], v[68:71], v[198:201], v[52:55]
	v_mfma_f32_16x16x32_bf16 v[40:43], v[60:63], v[206:209], v[40:43]
	v_mfma_f32_16x16x32_bf16 v[36:39], v[68:71], v[206:209], v[36:39]
	v_mfma_f32_16x16x32_bf16 v[16:19], v[60:63], v[214:217], v[16:19]
	v_mfma_f32_16x16x32_bf16 v[12:15], v[68:71], v[214:217], v[12:15]
	v_mfma_f32_16x16x32_bf16 v[80:83], v[64:67], v[194:197], v[80:83]
	v_mfma_f32_16x16x32_bf16 v[76:79], v[72:75], v[194:197], v[76:79]
	v_mfma_f32_16x16x32_bf16 v[56:59], v[64:67], v[202:205], v[56:59]
	v_mfma_f32_16x16x32_bf16 v[52:55], v[72:75], v[202:205], v[52:55]
	v_mfma_f32_16x16x32_bf16 v[40:43], v[64:67], v[210:213], v[40:43]
	v_mfma_f32_16x16x32_bf16 v[36:39], v[72:75], v[210:213], v[36:39]
	v_mfma_f32_16x16x32_bf16 v[16:19], v[64:67], v[218:221], v[16:19]
	v_mfma_f32_16x16x32_bf16 v[12:15], v[72:75], v[218:221], v[12:15]
	s_barrier
	s_add_u32 s14, s14, 0x80080
	s_addc_u32 s15, s15, 0
	s_add_i32 s18, s18, s40
	v_lshl_add_u64 v[60:61], s[14:15], 0, v[2:3]
	s_mov_b32 m0, s18
	s_nop 0
	global_load_lds_dwordx4 v[60:61], off
	v_lshl_add_u64 v[60:61], s[14:15], 0, v[0:1]
	s_add_i32 m0, s18, 0x2000
	s_nop 0
	global_load_lds_dwordx4 v[60:61], off
	s_waitcnt vmcnt(6)
	s_barrier
	v_mfma_f32_16x16x32_bf16 v[28:31], v[222:225], v[170:173], v[28:31]
	v_mfma_f32_16x16x32_bf16 v[72:75], v[226:229], v[194:197], v[28:31]
	v_mfma_f32_16x16x32_bf16 v[28:31], v[230:233], v[170:173], v[32:35]
	v_mfma_f32_16x16x32_bf16 v[68:71], v[234:237], v[194:197], v[28:31]
	v_mfma_f32_16x16x32_bf16 v[28:31], v[222:225], v[198:201], v[48:51]
	v_mfma_f32_16x16x32_bf16 v[48:51], v[226:229], v[202:205], v[28:31]
	v_mfma_f32_16x16x32_bf16 v[28:31], v[230:233], v[198:201], v[44:47]
	v_mfma_f32_16x16x32_bf16 v[24:27], v[222:225], v[206:209], v[24:27]
	v_mfma_f32_16x16x32_bf16 v[20:23], v[230:233], v[206:209], v[20:23]
	v_mfma_f32_16x16x32_bf16 v[8:11], v[222:225], v[214:217], v[8:11]
	v_mfma_f32_16x16x32_bf16 v[4:7], v[230:233], v[214:217], v[4:7]
	v_mfma_f32_16x16x32_bf16 v[44:47], v[234:237], v[202:205], v[28:31]
	v_mfma_f32_16x16x32_bf16 v[24:27], v[226:229], v[210:213], v[24:27]
	v_mfma_f32_16x16x32_bf16 v[20:23], v[234:237], v[210:213], v[20:23]
	v_mfma_f32_16x16x32_bf16 v[8:11], v[226:229], v[218:221], v[8:11]
	v_mfma_f32_16x16x32_bf16 v[4:7], v[234:237], v[218:221], v[4:7]
	s_add_i32 s56, s56, 2
	s_add_u32 s12, s12, 0x100
	s_addc_u32 s13, s13, 0
	s_add_u32 s54, s54, 0x100
	s_addc_u32 s55, s55, 0
	s_cmp_gt_u32 s56, 29
	s_barrier
	s_cbranch_scc0 .LBB0_660
	s_ashr_i32 s1, s50, 4
	v_lshl_add_u32 v172, s50, 8, v189
	v_lshl_or_b32 v170, s51, 8, v191
	s_mul_hi_i32 s7, s1, 0x6000
	s_mulk_i32 s1, 0x6000
	v_ashrrev_i32_e32 v173, 31, v172
	s_add_u32 s12, s23, s1
	v_ashrrev_i32_e32 v171, 31, v170
	v_lshlrev_b64 v[174:175], 12, v[172:173]
	s_addc_u32 s13, s24, s7
	v_lshl_add_u64 v[194:195], s[16:17], 0, v[174:175]
	v_lshlrev_b64 v[174:175], 1, v[170:171]
	v_lshl_add_u64 v[32:33], v[170:171], 2, s[12:13]
	v_lshl_add_u64 v[170:171], v[194:195], 0, v[174:175]
	global_load_dwordx4 v[60:63], v[32:33], off offset:16
	global_load_dwordx4 v[64:67], v[32:33], off
	global_load_dwordx4 v[28:31], v[32:33], off offset:528
	s_nop 0
	global_load_dwordx4 v[32:35], v[32:33], off offset:512
	v_add_co_u32_e32 v242, vcc, 0, v170
	s_nop 1
	v_addc_co_u32_e32 v243, vcc, 0, v171, vcc
	global_load_dwordx4 v[202:205], v[242:243], off
	v_add_co_u32_e32 v242, vcc, 0, v170
	s_nop 1
	v_addc_co_u32_e32 v243, vcc, 0, v171, vcc
	global_load_dwordx4 v[206:209], v[242:243], off offset:256
	v_add_co_u32_e32 v242, vcc, 0x10000, v170
	s_nop 1
	v_addc_co_u32_e32 v243, vcc, 0, v171, vcc
	global_load_dwordx4 v[210:213], v[242:243], off
	v_add_co_u32_e32 v242, vcc, 0x10000, v170
	s_nop 1
	v_addc_co_u32_e32 v243, vcc, 0, v171, vcc
	global_load_dwordx4 v[214:217], v[242:243], off offset:256
	v_add_co_u32_e32 v242, vcc, 0x20000, v170
	s_nop 1
	v_addc_co_u32_e32 v243, vcc, 0, v171, vcc
	global_load_dwordx4 v[218:221], v[242:243], off
	v_add_co_u32_e32 v242, vcc, 0x20000, v170
	s_nop 1
	v_addc_co_u32_e32 v243, vcc, 0, v171, vcc
	global_load_dwordx4 v[222:225], v[242:243], off offset:256
	v_add_co_u32_e32 v242, vcc, 0x30000, v170
	s_nop 1
	v_addc_co_u32_e32 v243, vcc, 0, v171, vcc
	global_load_dwordx4 v[226:229], v[242:243], off
	v_add_co_u32_e32 v242, vcc, 0x30000, v170
	s_nop 1
	v_addc_co_u32_e32 v243, vcc, 0, v171, vcc
	global_load_dwordx4 v[230:233], v[242:243], off offset:256
	v_add_co_u32_e32 v242, vcc, 0x80000, v170
	s_nop 1
	v_addc_co_u32_e32 v243, vcc, 0, v171, vcc
	global_load_dwordx4 v[234:237], v[242:243], off
	v_add_co_u32_e32 v242, vcc, 0x80000, v170
	s_nop 1
	v_addc_co_u32_e32 v243, vcc, 0, v171, vcc
	global_load_dwordx4 v[238:241], v[242:243], off offset:256
	v_add_co_u32_e32 v242, vcc, 0x90000, v170
	s_nop 1
	v_addc_co_u32_e32 v243, vcc, 0, v171, vcc
	global_load_dwordx4 v[244:247], v[242:243], off
	s_mov_b32 s1, 0x80000
	s_nop 1
	s_waitcnt vmcnt(10)
;     __device__ __forceinline__ void operator()(const f32x4 (&acc)[2][2][4][2], const pg8::Unit& u, int wr, int wc, int fr, int fq) const {
;     ...
;             for (int m = 0; m < 4; ++m) { const size_t ro = (size_t)(row0 + ai * 128 + m * 16) * DM + col0;
; #pragma unroll
;                 for (int bj = 0; bj < 2; ++bj) {
;                     f32x4 x0, x1;
;                     if (XF32) { x0 = *(const f32x4*)(xin + ro + bj * 128); x1 = *(const f32x4*)(xin + ro + bj * 128 + 4); }
;                     else { const h8 xh = *(const h8*)(H + ro + bj * 128); x0 = (f32x4){(float)xh[0], (float)xh[1], (float)xh[2], (float)xh[3]}; x1 = (f32x4){(float)xh[4], (float)xh[5], (float)xh[6], (float)xh[7]}; }
;                     const f32x4 y0 = x0 + gv[bj][0] * acc[ai][bj][m][0], y1 = x1 + gv[bj][1] * acc[ai][bj][m][1];
;                     h8 o; o[0] = (half_t)y0[0]; o[1] = (half_t)y0[1]; o[2] = (half_t)y0[2]; o[3] = (half_t)y0[3]; o[4] = (half_t)y1[0]; o[5] = (half_t)y1[1]; o[6] = (half_t)y1[2]; o[7] = (half_t)y1[3];
;                     *(h8*)(H + ro + bj * 128) = o; } }
	v_mov_b32_e32 v194, v202
	v_mov_b32_e32 v195, v203
	v_mov_b32_e32 v196, v204
	v_mov_b32_e32 v197, v205
	v_add_co_u32_e32 v242, vcc, 0x90000, v170
	s_nop 1
	v_addc_co_u32_e32 v243, vcc, 0, v171, vcc
	global_load_dwordx4 v[202:205], v[242:243], off offset:256
	s_mov_b64 s[12:13], 0x80000
	s_mov_b32 s51, s0
	s_mov_b32 s50, s6
	s_mov_b64 s[14:15], s[10:11]
	v_readlane_b32 s59, v251, 43
	s_nop 0
	v_cvt_f32_f16_e32 v198, v194
	v_cvt_f32_f16_sdwa v199, v194 dst_sel:DWORD dst_unused:UNUSED_PAD src0_sel:WORD_1
	v_cvt_f32_f16_e32 v194, v195
	v_cvt_f32_f16_sdwa v195, v195 dst_sel:DWORD dst_unused:UNUSED_PAD src0_sel:WORD_1
	v_cvt_f32_f16_e32 v200, v196
	v_cvt_f32_f16_sdwa v201, v196 dst_sel:DWORD dst_unused:UNUSED_PAD src0_sel:WORD_1
	v_cvt_f32_f16_e32 v196, v197
	v_cvt_f32_f16_sdwa v197, v197 dst_sel:DWORD dst_unused:UNUSED_PAD src0_sel:WORD_1
	v_pk_fma_f32 v[146:147], v[146:147], v[66:67], v[194:195]
	v_pk_fma_f32 v[144:145], v[144:145], v[64:65], v[198:199]
	v_pk_fma_f32 v[140:141], v[140:141], v[60:61], v[200:201]
	v_pk_fma_f32 v[142:143], v[142:143], v[62:63], v[196:197]
	s_nop 0
	v_cvt_pk_f16_f32 v143, v142, v143
	v_cvt_pk_f16_f32 v142, v140, v141
	v_cvt_pk_f16_f32 v141, v146, v147
	v_cvt_pk_f16_f32 v140, v144, v145
	global_store_dwordx4 v[170:171], v[140:143], off
	s_nop 1
	s_waitcnt vmcnt(10)
	v_mov_b32_e32 v140, v206
	v_mov_b32_e32 v141, v207
	v_mov_b32_e32 v142, v208
	v_mov_b32_e32 v143, v209
	v_add_co_u32_e32 v242, vcc, 0xa0000, v170
	s_nop 1
	v_addc_co_u32_e32 v243, vcc, 0, v171, vcc
	global_load_dwordx4 v[206:209], v[242:243], off
	s_nop 0
	v_cvt_f32_f16_e32 v144, v140
	v_cvt_f32_f16_sdwa v145, v140 dst_sel:DWORD dst_unused:UNUSED_PAD src0_sel:WORD_1
	v_cvt_f32_f16_e32 v140, v141
	v_cvt_f32_f16_sdwa v141, v141 dst_sel:DWORD dst_unused:UNUSED_PAD src0_sel:WORD_1
	v_cvt_f32_f16_e32 v146, v142
	v_cvt_f32_f16_sdwa v147, v142 dst_sel:DWORD dst_unused:UNUSED_PAD src0_sel:WORD_1
	v_cvt_f32_f16_e32 v142, v143
	v_cvt_f32_f16_sdwa v143, v143 dst_sel:DWORD dst_unused:UNUSED_PAD src0_sel:WORD_1
	v_pk_fma_f32 v[138:139], v[138:139], v[34:35], v[140:141]
	v_pk_fma_f32 v[136:137], v[136:137], v[32:33], v[144:145]
	v_pk_fma_f32 v[132:133], v[132:133], v[28:29], v[146:147]
	v_pk_fma_f32 v[134:135], v[134:135], v[30:31], v[142:143]
	s_nop 0
	v_cvt_pk_f16_f32 v135, v134, v135
	v_cvt_pk_f16_f32 v134, v132, v133
	v_cvt_pk_f16_f32 v133, v138, v139
	v_cvt_pk_f16_f32 v132, v136, v137
	global_store_dwordx4 v[170:171], v[132:135], off offset:256
	s_nop 1
	v_or_b32_e32 v132, 16, v172
	v_ashrrev_i32_e32 v133, 31, v132
	v_lshlrev_b64 v[132:133], 12, v[132:133]
	v_lshl_add_u64 v[132:133], s[16:17], 0, v[132:133]
	v_lshl_add_u64 v[136:137], v[132:133], 0, v[174:175]
	s_nop 1
	s_waitcnt vmcnt(10)
	v_mov_b32_e32 v132, v210
	v_mov_b32_e32 v133, v211
	v_mov_b32_e32 v134, v212
	v_mov_b32_e32 v135, v213
	v_add_co_u32_e32 v242, vcc, 0xa0000, v170
	s_nop 1
	v_addc_co_u32_e32 v243, vcc, 0, v171, vcc
	global_load_dwordx4 v[210:213], v[242:243], off offset:256
	s_nop 0
	v_cvt_f32_f16_e32 v138, v132
	v_cvt_f32_f16_sdwa v139, v132 dst_sel:DWORD dst_unused:UNUSED_PAD src0_sel:WORD_1
	v_cvt_f32_f16_e32 v132, v133
	v_cvt_f32_f16_sdwa v133, v133 dst_sel:DWORD dst_unused:UNUSED_PAD src0_sel:WORD_1
	v_cvt_f32_f16_e32 v140, v134
	v_cvt_f32_f16_sdwa v141, v134 dst_sel:DWORD dst_unused:UNUSED_PAD src0_sel:WORD_1
	v_cvt_f32_f16_e32 v134, v135
	v_cvt_f32_f16_sdwa v135, v135 dst_sel:DWORD dst_unused:UNUSED_PAD src0_sel:WORD_1
	v_pk_fma_f32 v[130:131], v[130:131], v[66:67], v[132:133]
	v_pk_fma_f32 v[128:129], v[128:129], v[64:65], v[138:139]
	v_pk_fma_f32 v[124:125], v[124:125], v[60:61], v[140:141]
	v_pk_fma_f32 v[126:127], v[126:127], v[62:63], v[134:135]
	s_nop 0
	v_cvt_pk_f16_f32 v127, v126, v127
	v_cvt_pk_f16_f32 v126, v124, v125
	v_cvt_pk_f16_f32 v125, v130, v131
	v_cvt_pk_f16_f32 v124, v128, v129
	global_store_dwordx4 v[136:137], v[124:127], off
	s_nop 1
	s_waitcnt vmcnt(10)
	v_mov_b32_e32 v124, v214
	v_mov_b32_e32 v125, v215
	v_mov_b32_e32 v126, v216
	v_mov_b32_e32 v127, v217
	v_add_co_u32_e32 v242, vcc, 0xb0000, v170
	s_nop 1
	v_addc_co_u32_e32 v243, vcc, 0, v171, vcc
	global_load_dwordx4 v[214:217], v[242:243], off
	s_nop 0
	v_cvt_f32_f16_e32 v128, v124
	v_cvt_f32_f16_sdwa v129, v124 dst_sel:DWORD dst_unused:UNUSED_PAD src0_sel:WORD_1
	v_cvt_f32_f16_e32 v124, v125
	v_cvt_f32_f16_sdwa v125, v125 dst_sel:DWORD dst_unused:UNUSED_PAD src0_sel:WORD_1
	v_cvt_f32_f16_e32 v130, v126
	v_cvt_f32_f16_sdwa v131, v126 dst_sel:DWORD dst_unused:UNUSED_PAD src0_sel:WORD_1
	v_cvt_f32_f16_e32 v126, v127
	v_cvt_f32_f16_sdwa v127, v127 dst_sel:DWORD dst_unused:UNUSED_PAD src0_sel:WORD_1
	v_pk_fma_f32 v[122:123], v[122:123], v[34:35], v[124:125]
	v_pk_fma_f32 v[120:121], v[120:121], v[32:33], v[128:129]
	v_pk_fma_f32 v[116:117], v[116:117], v[28:29], v[130:131]
	v_pk_fma_f32 v[118:119], v[118:119], v[30:31], v[126:127]
	s_nop 0
	v_cvt_pk_f16_f32 v119, v118, v119
	v_cvt_pk_f16_f32 v118, v116, v117
	v_cvt_pk_f16_f32 v117, v122, v123
	v_cvt_pk_f16_f32 v116, v120, v121
	global_store_dwordx4 v[136:137], v[116:119], off offset:256
	s_nop 1
	v_or_b32_e32 v116, 32, v172
	v_ashrrev_i32_e32 v117, 31, v116
	v_lshlrev_b64 v[116:117], 12, v[116:117]
	v_lshl_add_u64 v[116:117], s[16:17], 0, v[116:117]
	v_lshl_add_u64 v[120:121], v[116:117], 0, v[174:175]
	s_nop 1
	s_waitcnt vmcnt(10)
;     __device__ __forceinline__ void operator()(const f32x4 (&acc)[2][2][4][2], const pg8::Unit& u, int wr, int wc, int fr, int fq) const {
;     ...
;             for (int m = 0; m < 4; ++m) { const size_t ro = (size_t)(row0 + ai * 128 + m * 16) * DM + col0;
; #pragma unroll
;                 for (int bj = 0; bj < 2; ++bj) {
;                     f32x4 x0, x1;
;                     if (XF32) { x0 = *(const f32x4*)(xin + ro + bj * 128); x1 = *(const f32x4*)(xin + ro + bj * 128 + 4); }
;                     else { const h8 xh = *(const h8*)(H + ro + bj * 128); x0 = (f32x4){(float)xh[0], (float)xh[1], (float)xh[2], (float)xh[3]}; x1 = (f32x4){(float)xh[4], (float)xh[5], (float)xh[6], (float)xh[7]}; }
;                     const f32x4 y0 = x0 + gv[bj][0] * acc[ai][bj][m][0], y1 = x1 + gv[bj][1] * acc[ai][bj][m][1];
;                     h8 o; o[0] = (half_t)y0[0]; o[1] = (half_t)y0[1]; o[2] = (half_t)y0[2]; o[3] = (half_t)y0[3]; o[4] = (half_t)y1[0]; o[5] = (half_t)y1[1]; o[6] = (half_t)y1[2]; o[7] = (half_t)y1[3];
;                     *(h8*)(H + ro + bj * 128) = o; } }
	v_mov_b32_e32 v116, v218
	v_mov_b32_e32 v117, v219
	v_mov_b32_e32 v118, v220
	v_mov_b32_e32 v119, v221
	v_add_co_u32_e32 v242, vcc, 0xb0000, v170
	s_nop 1
	v_addc_co_u32_e32 v243, vcc, 0, v171, vcc
	global_load_dwordx4 v[218:221], v[242:243], off offset:256
	s_nop 0
	v_cvt_f32_f16_e32 v122, v116
	v_cvt_f32_f16_sdwa v123, v116 dst_sel:DWORD dst_unused:UNUSED_PAD src0_sel:WORD_1
	v_cvt_f32_f16_e32 v116, v117
	v_cvt_f32_f16_sdwa v117, v117 dst_sel:DWORD dst_unused:UNUSED_PAD src0_sel:WORD_1
	v_cvt_f32_f16_e32 v124, v118
	v_cvt_f32_f16_sdwa v125, v118 dst_sel:DWORD dst_unused:UNUSED_PAD src0_sel:WORD_1
	v_cvt_f32_f16_e32 v118, v119
	v_cvt_f32_f16_sdwa v119, v119 dst_sel:DWORD dst_unused:UNUSED_PAD src0_sel:WORD_1
	v_pk_fma_f32 v[114:115], v[114:115], v[66:67], v[116:117]
	v_pk_fma_f32 v[112:113], v[112:113], v[64:65], v[122:123]
	v_pk_fma_f32 v[108:109], v[108:109], v[60:61], v[124:125]
	v_pk_fma_f32 v[110:111], v[110:111], v[62:63], v[118:119]
	s_nop 0
	v_cvt_pk_f16_f32 v111, v110, v111
	v_cvt_pk_f16_f32 v110, v108, v109
	v_cvt_pk_f16_f32 v109, v114, v115
	v_cvt_pk_f16_f32 v108, v112, v113
	global_store_dwordx4 v[120:121], v[108:111], off
	s_nop 1
	s_waitcnt vmcnt(10)
	v_mov_b32_e32 v108, v222
	v_mov_b32_e32 v109, v223
	v_mov_b32_e32 v110, v224
	v_mov_b32_e32 v111, v225
	s_nop 0
	v_cvt_f32_f16_e32 v112, v108
	v_cvt_f32_f16_sdwa v113, v108 dst_sel:DWORD dst_unused:UNUSED_PAD src0_sel:WORD_1
	v_cvt_f32_f16_e32 v108, v109
	v_cvt_f32_f16_sdwa v109, v109 dst_sel:DWORD dst_unused:UNUSED_PAD src0_sel:WORD_1
	v_cvt_f32_f16_e32 v114, v110
	v_cvt_f32_f16_sdwa v115, v110 dst_sel:DWORD dst_unused:UNUSED_PAD src0_sel:WORD_1
	v_cvt_f32_f16_e32 v110, v111
	v_cvt_f32_f16_sdwa v111, v111 dst_sel:DWORD dst_unused:UNUSED_PAD src0_sel:WORD_1
	v_pk_fma_f32 v[106:107], v[106:107], v[34:35], v[108:109]
	v_pk_fma_f32 v[104:105], v[104:105], v[32:33], v[112:113]
	v_pk_fma_f32 v[100:101], v[100:101], v[28:29], v[114:115]
	v_pk_fma_f32 v[102:103], v[102:103], v[30:31], v[110:111]
	s_nop 0
	v_cvt_pk_f16_f32 v103, v102, v103
	v_cvt_pk_f16_f32 v102, v100, v101
	v_cvt_pk_f16_f32 v101, v106, v107
	v_cvt_pk_f16_f32 v100, v104, v105
	global_store_dwordx4 v[120:121], v[100:103], off offset:256
	s_nop 1
	v_or_b32_e32 v100, 48, v172
	v_ashrrev_i32_e32 v101, 31, v100
	v_lshlrev_b64 v[100:101], 12, v[100:101]
	v_lshl_add_u64 v[100:101], s[16:17], 0, v[100:101]
	v_lshl_add_u64 v[104:105], v[100:101], 0, v[174:175]
	s_nop 1
	s_waitcnt vmcnt(9)
	v_mov_b32_e32 v100, v226
	v_mov_b32_e32 v101, v227
	v_mov_b32_e32 v102, v228
	v_mov_b32_e32 v103, v229
	s_nop 0
	v_cvt_f32_f16_e32 v106, v100
	v_cvt_f32_f16_sdwa v107, v100 dst_sel:DWORD dst_unused:UNUSED_PAD src0_sel:WORD_1
	v_cvt_f32_f16_e32 v100, v101
	v_cvt_f32_f16_sdwa v101, v101 dst_sel:DWORD dst_unused:UNUSED_PAD src0_sel:WORD_1
	v_cvt_f32_f16_e32 v108, v102
	v_cvt_f32_f16_sdwa v109, v102 dst_sel:DWORD dst_unused:UNUSED_PAD src0_sel:WORD_1
	v_cvt_f32_f16_e32 v102, v103
	v_cvt_f32_f16_sdwa v103, v103 dst_sel:DWORD dst_unused:UNUSED_PAD src0_sel:WORD_1
	v_pk_fma_f32 v[98:99], v[98:99], v[66:67], v[100:101]
	v_pk_fma_f32 v[96:97], v[96:97], v[64:65], v[106:107]
	v_pk_fma_f32 v[92:93], v[92:93], v[60:61], v[108:109]
	v_pk_fma_f32 v[94:95], v[94:95], v[62:63], v[102:103]
	s_nop 0
	v_cvt_pk_f16_f32 v95, v94, v95
	v_cvt_pk_f16_f32 v94, v92, v93
	v_cvt_pk_f16_f32 v93, v98, v99
	v_cvt_pk_f16_f32 v92, v96, v97
	global_store_dwordx4 v[104:105], v[92:95], off
	s_nop 1
	s_waitcnt vmcnt(8)
	v_mov_b32_e32 v92, v230
	v_mov_b32_e32 v93, v231
	v_mov_b32_e32 v94, v232
	v_mov_b32_e32 v95, v233
	s_nop 0
	v_cvt_f32_f16_e32 v96, v92
	v_cvt_f32_f16_sdwa v97, v92 dst_sel:DWORD dst_unused:UNUSED_PAD src0_sel:WORD_1
	v_cvt_f32_f16_e32 v92, v93
	v_cvt_f32_f16_sdwa v93, v93 dst_sel:DWORD dst_unused:UNUSED_PAD src0_sel:WORD_1
	v_cvt_f32_f16_e32 v98, v94
	v_cvt_f32_f16_sdwa v99, v94 dst_sel:DWORD dst_unused:UNUSED_PAD src0_sel:WORD_1
	v_cvt_f32_f16_e32 v94, v95
	v_cvt_f32_f16_sdwa v95, v95 dst_sel:DWORD dst_unused:UNUSED_PAD src0_sel:WORD_1
	v_pk_fma_f32 v[90:91], v[90:91], v[34:35], v[92:93]
	v_pk_fma_f32 v[84:85], v[84:85], v[28:29], v[98:99]
	v_pk_fma_f32 v[88:89], v[88:89], v[32:33], v[96:97]
	v_pk_fma_f32 v[86:87], v[86:87], v[30:31], v[94:95]
	s_nop 0
	v_cvt_pk_f16_f32 v87, v86, v87
	v_cvt_pk_f16_f32 v86, v84, v85
	v_cvt_pk_f16_f32 v85, v90, v91
	v_add_co_u32_e32 v90, vcc, s1, v170
	v_cvt_pk_f16_f32 v84, v88, v89
	s_nop 0
	v_addc_co_u32_e32 v91, vcc, 0, v171, vcc
	global_store_dwordx4 v[104:105], v[84:87], off offset:256
	s_nop 1
	s_waitcnt vmcnt(7)
	v_mov_b32_e32 v86, v234
	v_mov_b32_e32 v87, v235
	v_mov_b32_e32 v88, v236
	v_mov_b32_e32 v89, v237
	s_mov_b32 s1, 0x90000
	v_lshl_add_u64 v[84:85], v[170:171], 0, s[12:13]
	s_mov_b64 s[12:13], 0x90000
	s_nop 0
	v_cvt_f32_f16_e32 v92, v86
	v_cvt_f32_f16_sdwa v93, v86 dst_sel:DWORD dst_unused:UNUSED_PAD src0_sel:WORD_1
	v_cvt_f32_f16_e32 v86, v87
	v_cvt_f32_f16_sdwa v87, v87 dst_sel:DWORD dst_unused:UNUSED_PAD src0_sel:WORD_1
	v_cvt_f32_f16_e32 v94, v88
	v_cvt_f32_f16_sdwa v95, v88 dst_sel:DWORD dst_unused:UNUSED_PAD src0_sel:WORD_1
	v_cvt_f32_f16_e32 v88, v89
	v_cvt_f32_f16_sdwa v89, v89 dst_sel:DWORD dst_unused:UNUSED_PAD src0_sel:WORD_1
	v_pk_fma_f32 v[82:83], v[82:83], v[66:67], v[86:87]
	v_pk_fma_f32 v[80:81], v[80:81], v[64:65], v[92:93]
	v_pk_fma_f32 v[76:77], v[76:77], v[60:61], v[94:95]
	v_pk_fma_f32 v[78:79], v[78:79], v[62:63], v[88:89]
	s_nop 0
	v_cvt_pk_f16_f32 v79, v78, v79
	v_cvt_pk_f16_f32 v78, v76, v77
	v_cvt_pk_f16_f32 v77, v82, v83
	v_cvt_pk_f16_f32 v76, v80, v81
	global_store_dwordx4 v[90:91], v[76:79], off
	s_nop 1
	s_waitcnt vmcnt(6)
;     __device__ __forceinline__ void operator()(const f32x4 (&acc)[2][2][4][2], const pg8::Unit& u, int wr, int wc, int fr, int fq) const {
;     ...
;             for (int m = 0; m < 4; ++m) { const size_t ro = (size_t)(row0 + ai * 128 + m * 16) * DM + col0;
; #pragma unroll
;                 for (int bj = 0; bj < 2; ++bj) {
;                     f32x4 x0, x1;
;                     if (XF32) { x0 = *(const f32x4*)(xin + ro + bj * 128); x1 = *(const f32x4*)(xin + ro + bj * 128 + 4); }
;                     else { const h8 xh = *(const h8*)(H + ro + bj * 128); x0 = (f32x4){(float)xh[0], (float)xh[1], (float)xh[2], (float)xh[3]}; x1 = (f32x4){(float)xh[4], (float)xh[5], (float)xh[6], (float)xh[7]}; }
;                     const f32x4 y0 = x0 + gv[bj][0] * acc[ai][bj][m][0], y1 = x1 + gv[bj][1] * acc[ai][bj][m][1];
;                     h8 o; o[0] = (half_t)y0[0]; o[1] = (half_t)y0[1]; o[2] = (half_t)y0[2]; o[3] = (half_t)y0[3]; o[4] = (half_t)y1[0]; o[5] = (half_t)y1[1]; o[6] = (half_t)y1[2]; o[7] = (half_t)y1[3];
;                     *(h8*)(H + ro + bj * 128) = o; } }
	v_mov_b32_e32 v76, v238
	v_mov_b32_e32 v77, v239
	v_mov_b32_e32 v78, v240
	v_mov_b32_e32 v79, v241
	s_nop 0
	v_cvt_f32_f16_e32 v80, v76
	v_cvt_f32_f16_sdwa v81, v76 dst_sel:DWORD dst_unused:UNUSED_PAD src0_sel:WORD_1
	v_cvt_f32_f16_e32 v76, v77
	v_cvt_f32_f16_sdwa v77, v77 dst_sel:DWORD dst_unused:UNUSED_PAD src0_sel:WORD_1
	v_cvt_f32_f16_e32 v82, v78
	v_cvt_f32_f16_sdwa v83, v78 dst_sel:DWORD dst_unused:UNUSED_PAD src0_sel:WORD_1
	v_cvt_f32_f16_e32 v78, v79
	v_cvt_f32_f16_sdwa v79, v79 dst_sel:DWORD dst_unused:UNUSED_PAD src0_sel:WORD_1
	v_pk_fma_f32 v[74:75], v[74:75], v[34:35], v[76:77]
	v_pk_fma_f32 v[68:69], v[68:69], v[28:29], v[82:83]
	v_pk_fma_f32 v[72:73], v[72:73], v[32:33], v[80:81]
	v_pk_fma_f32 v[70:71], v[70:71], v[30:31], v[78:79]
	s_nop 0
	v_cvt_pk_f16_f32 v71, v70, v71
	v_cvt_pk_f16_f32 v70, v68, v69
	v_cvt_pk_f16_f32 v69, v74, v75
	v_add_co_u32_e32 v74, vcc, s1, v170
	v_cvt_pk_f16_f32 v68, v72, v73
	s_nop 0
	v_addc_co_u32_e32 v75, vcc, 0, v171, vcc
	global_store_dwordx4 v[84:85], v[68:71], off offset:256
	s_nop 1
	s_waitcnt vmcnt(5)
	v_mov_b32_e32 v70, v244
	v_mov_b32_e32 v71, v245
	v_mov_b32_e32 v72, v246
	v_mov_b32_e32 v73, v247
	s_mov_b32 s1, 0xa0000
	v_lshl_add_u64 v[68:69], v[170:171], 0, s[12:13]
	s_mov_b64 s[12:13], 0xa0000
	s_nop 0
	v_cvt_f32_f16_e32 v76, v70
	v_cvt_f32_f16_sdwa v77, v70 dst_sel:DWORD dst_unused:UNUSED_PAD src0_sel:WORD_1
	v_cvt_f32_f16_e32 v70, v71
	v_cvt_f32_f16_sdwa v71, v71 dst_sel:DWORD dst_unused:UNUSED_PAD src0_sel:WORD_1
	v_cvt_f32_f16_e32 v78, v72
	v_cvt_f32_f16_sdwa v79, v72 dst_sel:DWORD dst_unused:UNUSED_PAD src0_sel:WORD_1
	v_cvt_f32_f16_e32 v72, v73
	v_cvt_f32_f16_sdwa v73, v73 dst_sel:DWORD dst_unused:UNUSED_PAD src0_sel:WORD_1
	v_pk_fma_f32 v[58:59], v[58:59], v[66:67], v[70:71]
	v_pk_fma_f32 v[56:57], v[56:57], v[64:65], v[76:77]
	v_pk_fma_f32 v[52:53], v[52:53], v[60:61], v[78:79]
	v_pk_fma_f32 v[54:55], v[54:55], v[62:63], v[72:73]
	s_nop 0
	v_cvt_pk_f16_f32 v55, v54, v55
	v_cvt_pk_f16_f32 v54, v52, v53
	v_cvt_pk_f16_f32 v53, v58, v59
	v_cvt_pk_f16_f32 v52, v56, v57
	global_store_dwordx4 v[74:75], v[52:55], off
	s_nop 1
	s_waitcnt vmcnt(4)
	v_mov_b32_e32 v52, v202
	v_mov_b32_e32 v53, v203
	v_mov_b32_e32 v54, v204
	v_mov_b32_e32 v55, v205
	s_nop 0
	v_cvt_f32_f16_e32 v56, v52
	v_cvt_f32_f16_sdwa v57, v52 dst_sel:DWORD dst_unused:UNUSED_PAD src0_sel:WORD_1
	v_cvt_f32_f16_e32 v52, v53
	v_cvt_f32_f16_sdwa v53, v53 dst_sel:DWORD dst_unused:UNUSED_PAD src0_sel:WORD_1
	v_cvt_f32_f16_e32 v58, v54
	v_cvt_f32_f16_sdwa v59, v54 dst_sel:DWORD dst_unused:UNUSED_PAD src0_sel:WORD_1
	v_cvt_f32_f16_e32 v54, v55
	v_cvt_f32_f16_sdwa v55, v55 dst_sel:DWORD dst_unused:UNUSED_PAD src0_sel:WORD_1
	v_pk_fma_f32 v[50:51], v[50:51], v[34:35], v[52:53]
	v_pk_fma_f32 v[44:45], v[44:45], v[28:29], v[58:59]
	v_pk_fma_f32 v[48:49], v[48:49], v[32:33], v[56:57]
	v_pk_fma_f32 v[46:47], v[46:47], v[30:31], v[54:55]
	s_nop 0
	v_cvt_pk_f16_f32 v47, v46, v47
	v_cvt_pk_f16_f32 v46, v44, v45
	v_cvt_pk_f16_f32 v45, v50, v51
	v_add_co_u32_e32 v50, vcc, s1, v170
	v_cvt_pk_f16_f32 v44, v48, v49
	s_nop 0
	v_addc_co_u32_e32 v51, vcc, 0, v171, vcc
	global_store_dwordx4 v[68:69], v[44:47], off offset:256
	s_nop 1
	s_waitcnt vmcnt(3)
	v_mov_b32_e32 v46, v206
	v_mov_b32_e32 v47, v207
	v_mov_b32_e32 v48, v208
	v_mov_b32_e32 v49, v209
	s_mov_b32 s1, 0xb0000
	v_lshl_add_u64 v[44:45], v[170:171], 0, s[12:13]
	s_mov_b64 s[12:13], 0xb0000
	s_nop 0
	v_cvt_f32_f16_e32 v52, v46
	v_cvt_f32_f16_sdwa v53, v46 dst_sel:DWORD dst_unused:UNUSED_PAD src0_sel:WORD_1
	v_cvt_f32_f16_e32 v46, v47
	v_cvt_f32_f16_sdwa v47, v47 dst_sel:DWORD dst_unused:UNUSED_PAD src0_sel:WORD_1
	v_cvt_f32_f16_e32 v54, v48
	v_cvt_f32_f16_sdwa v55, v48 dst_sel:DWORD dst_unused:UNUSED_PAD src0_sel:WORD_1
	v_cvt_f32_f16_e32 v48, v49
	v_cvt_f32_f16_sdwa v49, v49 dst_sel:DWORD dst_unused:UNUSED_PAD src0_sel:WORD_1
	v_pk_fma_f32 v[42:43], v[42:43], v[66:67], v[46:47]
	v_pk_fma_f32 v[40:41], v[40:41], v[64:65], v[52:53]
	v_pk_fma_f32 v[36:37], v[36:37], v[60:61], v[54:55]
	v_pk_fma_f32 v[38:39], v[38:39], v[62:63], v[48:49]
	s_nop 0
	v_cvt_pk_f16_f32 v39, v38, v39
	v_cvt_pk_f16_f32 v38, v36, v37
	v_cvt_pk_f16_f32 v37, v42, v43
	v_cvt_pk_f16_f32 v36, v40, v41
	global_store_dwordx4 v[50:51], v[36:39], off
	s_nop 1
	s_waitcnt vmcnt(2)
; #define PG8_WAIT_V(n) asm volatile("s_waitcnt vmcnt(" #n ")" ::: "memory")
; #define PG8_BAR __builtin_amdgcn_s_barrier()
; template <class Epi>
; __device__ __forceinline__ void gemm_phase(LAS unsigned char* lds, const Gemm g, const StaticOrder& S, const Epi& E, const int tid) {
;     ...
;         if (!has_next) break;
; #pragma unroll
;         for (int a = 0; a < 2; ++a)
; #pragma unroll
;             for (int b = 0; b < 2; ++b)
; #pragma unroll
;                 for (int m = 0; m < 4; ++m)
; #pragma unroll
;                     for (int n = 0; n < 2; ++n) acc[a][b][m][n] = (f32x4){0.f, 0.f, 0.f, 0.f};
;         cur = nxt; cA = nA; cB = nB; ++ui;
;     }
;     PG8_WAIT_V(0);
;     if (wr == 0) PG8_BAR;
;     PG8_BAR;
;     __device__ __forceinline__ void operator()(const f32x4 (&acc)[2][2][4][2], const pg8::Unit& u, int wr, int wc, int fr, int fq) const {
;     ...
;             for (int m = 0; m < 4; ++m) { const size_t ro = (size_t)(row0 + ai * 128 + m * 16) * DM + col0;
; #pragma unroll
;                 for (int bj = 0; bj < 2; ++bj) {
;                     f32x4 x0, x1;
;                     if (XF32) { x0 = *(const f32x4*)(xin + ro + bj * 128); x1 = *(const f32x4*)(xin + ro + bj * 128 + 4); }
;                     else { const h8 xh = *(const h8*)(H + ro + bj * 128); x0 = (f32x4){(float)xh[0], (float)xh[1], (float)xh[2], (float)xh[3]}; x1 = (f32x4){(float)xh[4], (float)xh[5], (float)xh[6], (float)xh[7]}; }
;                     const f32x4 y0 = x0 + gv[bj][0] * acc[ai][bj][m][0], y1 = x1 + gv[bj][1] * acc[ai][bj][m][1];
;                     h8 o; o[0] = (half_t)y0[0]; o[1] = (half_t)y0[1]; o[2] = (half_t)y0[2]; o[3] = (half_t)y0[3]; o[4] = (half_t)y1[0]; o[5] = (half_t)y1[1]; o[6] = (half_t)y1[2]; o[7] = (half_t)y1[3];
;                     *(h8*)(H + ro + bj * 128) = o; } }
	v_mov_b32_e32 v36, v210
	v_mov_b32_e32 v37, v211
	v_mov_b32_e32 v38, v212
	v_mov_b32_e32 v39, v213
	s_nop 0
	v_cvt_f32_f16_e32 v40, v36
	v_cvt_f32_f16_sdwa v41, v36 dst_sel:DWORD dst_unused:UNUSED_PAD src0_sel:WORD_1
	v_cvt_f32_f16_e32 v36, v37
	v_cvt_f32_f16_sdwa v37, v37 dst_sel:DWORD dst_unused:UNUSED_PAD src0_sel:WORD_1
	v_cvt_f32_f16_e32 v42, v38
	v_cvt_f32_f16_sdwa v43, v38 dst_sel:DWORD dst_unused:UNUSED_PAD src0_sel:WORD_1
	v_cvt_f32_f16_e32 v38, v39
	v_cvt_f32_f16_sdwa v39, v39 dst_sel:DWORD dst_unused:UNUSED_PAD src0_sel:WORD_1
	v_pk_fma_f32 v[26:27], v[26:27], v[34:35], v[36:37]
	v_pk_fma_f32 v[20:21], v[20:21], v[28:29], v[42:43]
	v_pk_fma_f32 v[24:25], v[24:25], v[32:33], v[40:41]
	v_pk_fma_f32 v[22:23], v[22:23], v[30:31], v[38:39]
	s_nop 0
	v_cvt_pk_f16_f32 v23, v22, v23
	v_cvt_pk_f16_f32 v22, v20, v21
	v_cvt_pk_f16_f32 v21, v26, v27
	v_add_co_u32_e32 v26, vcc, s1, v170
	v_cvt_pk_f16_f32 v20, v24, v25
	s_nop 0
	v_addc_co_u32_e32 v27, vcc, 0, v171, vcc
	global_store_dwordx4 v[44:45], v[20:23], off offset:256
	s_nop 1
	s_waitcnt vmcnt(1)
	v_mov_b32_e32 v22, v214
	v_mov_b32_e32 v23, v215
	v_mov_b32_e32 v24, v216
	v_mov_b32_e32 v25, v217
	s_and_b64 vcc, exec, s[4:5]
	v_lshl_add_u64 v[20:21], v[170:171], 0, s[12:13]
	s_mov_b64 s[12:13], s[8:9]
	s_nop 0
	v_cvt_f32_f16_e32 v36, v22
	v_cvt_f32_f16_sdwa v37, v22 dst_sel:DWORD dst_unused:UNUSED_PAD src0_sel:WORD_1
	v_cvt_f32_f16_e32 v22, v23
	v_cvt_f32_f16_sdwa v23, v23 dst_sel:DWORD dst_unused:UNUSED_PAD src0_sel:WORD_1
	v_cvt_f32_f16_e32 v38, v24
	v_cvt_f32_f16_sdwa v39, v24 dst_sel:DWORD dst_unused:UNUSED_PAD src0_sel:WORD_1
	v_cvt_f32_f16_e32 v24, v25
	v_cvt_f32_f16_sdwa v25, v25 dst_sel:DWORD dst_unused:UNUSED_PAD src0_sel:WORD_1
	v_pk_fma_f32 v[18:19], v[18:19], v[66:67], v[22:23]
	v_pk_fma_f32 v[16:17], v[16:17], v[64:65], v[36:37]
	v_pk_fma_f32 v[12:13], v[12:13], v[60:61], v[38:39]
	v_pk_fma_f32 v[14:15], v[14:15], v[62:63], v[24:25]
	s_nop 0
	v_cvt_pk_f16_f32 v15, v14, v15
	v_cvt_pk_f16_f32 v14, v12, v13
	v_cvt_pk_f16_f32 v13, v18, v19
	v_cvt_pk_f16_f32 v12, v16, v17
	global_store_dwordx4 v[26:27], v[12:15], off
	s_nop 1
	s_waitcnt vmcnt(0)
	v_mov_b32_e32 v12, v218
	v_mov_b32_e32 v13, v219
	v_mov_b32_e32 v14, v220
	v_mov_b32_e32 v15, v221
	s_nop 0
	v_cvt_f32_f16_e32 v16, v12
	v_cvt_f32_f16_sdwa v17, v12 dst_sel:DWORD dst_unused:UNUSED_PAD src0_sel:WORD_1
	v_cvt_f32_f16_e32 v12, v13
	v_cvt_f32_f16_sdwa v13, v13 dst_sel:DWORD dst_unused:UNUSED_PAD src0_sel:WORD_1
	v_cvt_f32_f16_e32 v18, v14
	v_cvt_f32_f16_sdwa v19, v14 dst_sel:DWORD dst_unused:UNUSED_PAD src0_sel:WORD_1
	v_cvt_f32_f16_e32 v14, v15
	v_cvt_f32_f16_sdwa v15, v15 dst_sel:DWORD dst_unused:UNUSED_PAD src0_sel:WORD_1
	v_pk_fma_f32 v[10:11], v[10:11], v[34:35], v[12:13]
	v_pk_fma_f32 v[8:9], v[8:9], v[32:33], v[16:17]
	v_pk_fma_f32 v[4:5], v[4:5], v[28:29], v[18:19]
	v_pk_fma_f32 v[6:7], v[6:7], v[30:31], v[14:15]
	s_nop 0
	v_cvt_pk_f16_f32 v7, v6, v7
	v_cvt_pk_f16_f32 v6, v4, v5
	v_cvt_pk_f16_f32 v5, v10, v11
	v_cvt_pk_f16_f32 v4, v8, v9
	global_store_dwordx4 v[20:21], v[4:7], off offset:256
	s_cbranch_vccz .LBB0_653
	s_waitcnt vmcnt(0)
	v_readlane_b32 s48, v251, 13
	s_cmpk_gt_u32 s25, 0xff
	v_readlane_b32 s49, v251, 14
	s_cbranch_scc1 .LBB0_664
	s_barrier

; #define PG8_STAGE(bufoff, gbase, voff) do { _Pragma("unroll") for (int _i = 0; _i < 2; ++_i) \
;         __builtin_amdgcn_global_load_lds((const unsigned*)((const char*)(gbase) + (voff)[_i]), (LAS unsigned*)(lds + (bufoff) + ldsw + _i * 8192), 16, 0, 0); } while (0)
; #define PG8_LDA(dst, b, h) do { _Pragma("unroll") for (int m = 0; m < 4; ++m) _Pragma("unroll") for (int k = 0; k < 2; ++k) dst[m][k] = *(const LAS h8*)(lds + PG8_SA(b, h) + aoff + m * 2048 + k * 1024); } while (0)
; #define PG8_LDB(dst, b, h) do { _Pragma("unroll") for (int n = 0; n < 2; ++n) _Pragma("unroll") for (int k = 0; k < 2; ++k) dst[n][k] = *(const LAS h8*)(lds + PG8_SB(b, h) + boff + n * 2048 + k * 1024); } while (0)
; #define PG8_WAIT_L(n) asm volatile("s_waitcnt lgkmcnt(" #n ")" ::: "memory")
; #define PG8_BAR __builtin_amdgcn_s_barrier()
; #define PG8_SCHED __builtin_amdgcn_sched_barrier(0)
; template <class Epi>
; __device__ __forceinline__ void gemm_phase(LAS unsigned char* lds, const Gemm g, const StaticOrder& S, const Epi& E, const int tid) {
;     ...
;         const bool has_next = S.next(ui + 1, nxt);
;         const char* nA = has_next ? (const char*)g.A + (size_t)nxt.pm * tstep : cA; const char* nB = has_next ? (const char*)g.Bt + (size_t)nxt.pn * tstep : cB;
;         for (int t = 0; t < nt; t += 2) {
;             const bool last = (t == nt - 2);
;             const char* a1 = cA + (size_t)(t + 1) * kstep;
;             const char* a2 = last ? nA : cA + (size_t)(t + 2) * kstep; const char* b2 = last ? nB : cB + (size_t)(t + 2) * kstep;
;             const char* a3 = a2 + kstep; const char* b3 = b2 + kstep;
;             if constexpr (Epi::HAS_MID) { if (t == (nt >> 1)) E.mid(acc, cur, wr, wc, fr, fq); }
;             PG8_LDB(B0, 0, 0); PG8_SCHED; PG8_LDA(At, 0, 0); PG8_STAGE(PG8_SA(1, 1), a1 + hstep, voffA);
;             PG8_WAIT_L(8); PG8_BAR; PG8_WAIT_L(0); PG8_MMA(0, 0, At, B0); PG8_BAR; PG8_SCHED;
;             PG8_LDB(B1, 0, 1); PG8_STAGE(PG8_SB(0, 0), b2, voffB);
;             PG8_BAR; PG8_WAIT_L(0); PG8_MMA(0, 1, At, B1); PG8_BAR;
;             PG8_LDA(At, 0, 1); PG8_STAGE(PG8_SA(0, 0), a2, voffA);
;             PG8_BAR; PG8_WAIT_L(0); PG8_MMA(1, 0, At, B0); PG8_BAR; PG8_SCHED;
.LBB0_678:
	s_add_u32 s14, s12, 0xfff80080
	s_addc_u32 s15, s13, -1
	s_add_i32 s55, 0, 0x10000
	v_add_u32_e32 v88, s55, v176
	ds_read_b128 v[68:71], v88
	ds_read_b128 v[72:75], v88 offset:1024
	ds_read_b128 v[84:87], v88 offset:2048
	ds_read_b128 v[88:91], v88 offset:3072
	s_cmp_eq_u32 s54, 28
	s_cselect_b32 s19, s7, s15
	s_cselect_b32 s18, s50, s14
	s_cselect_b32 s15, s1, s53
	s_cselect_b32 s14, s51, s52
	v_lshl_add_u64 v[174:175], s[12:13], 0, v[166:167]
	s_add_i32 m0, s39, 0xc000
	ds_read_b128 v[170:173], v177
	ds_read_b128 v[190:193], v177 offset:1024
	ds_read_b128 v[194:197], v177 offset:2048
	ds_read_b128 v[198:201], v177 offset:3072
	ds_read_b128 v[202:205], v177 offset:4096
	ds_read_b128 v[206:209], v177 offset:5120
	ds_read_b128 v[210:213], v177 offset:6144
	ds_read_b128 v[214:217], v177 offset:7168
	global_load_lds_dwordx4 v[174:175], off
	v_lshl_add_u64 v[174:175], s[12:13], 0, v[168:169]
	s_add_i32 m0, s39, 0xe000
	s_nop 0
	global_load_lds_dwordx4 v[174:175], off
	s_waitcnt lgkmcnt(8)
	s_barrier
	s_waitcnt lgkmcnt(0)
	v_mfma_f32_16x16x32_bf16 v[144:147], v[68:71], v[170:173], v[144:147]
	v_mfma_f32_16x16x32_bf16 v[140:143], v[84:87], v[170:173], v[140:143]
	v_mfma_f32_16x16x32_bf16 v[128:131], v[68:71], v[194:197], v[128:131]
	v_mfma_f32_16x16x32_bf16 v[124:127], v[84:87], v[194:197], v[124:127]
	v_mfma_f32_16x16x32_bf16 v[112:115], v[68:71], v[202:205], v[112:115]
	v_mfma_f32_16x16x32_bf16 v[108:111], v[84:87], v[202:205], v[108:111]
	v_mfma_f32_16x16x32_bf16 v[96:99], v[68:71], v[210:213], v[96:99]
	v_mfma_f32_16x16x32_bf16 v[92:95], v[84:87], v[210:213], v[92:95]
	v_mfma_f32_16x16x32_bf16 v[144:147], v[72:75], v[190:193], v[144:147]
	v_mfma_f32_16x16x32_bf16 v[140:143], v[88:91], v[190:193], v[140:143]
	v_mfma_f32_16x16x32_bf16 v[128:131], v[72:75], v[198:201], v[128:131]
	v_mfma_f32_16x16x32_bf16 v[124:127], v[88:91], v[198:201], v[124:127]
	v_mfma_f32_16x16x32_bf16 v[112:115], v[72:75], v[206:209], v[112:115]
	v_mfma_f32_16x16x32_bf16 v[108:111], v[88:91], v[206:209], v[108:111]
	v_mfma_f32_16x16x32_bf16 v[96:99], v[72:75], v[214:217], v[96:99]
	v_mfma_f32_16x16x32_bf16 v[92:95], v[88:91], v[214:217], v[92:95]
	s_barrier
	s_add_i32 s58, 0, 0x14000
	v_add_u32_e32 v174, s58, v176
	s_add_i32 s55, s55, s38
	ds_read_b128 v[218:221], v174
	ds_read_b128 v[222:225], v174 offset:1024
	ds_read_b128 v[226:229], v174 offset:2048
	ds_read_b128 v[230:233], v174 offset:3072
	v_lshl_add_u64 v[174:175], s[14:15], 0, v[2:3]
	s_mov_b32 m0, s55
	v_lshl_add_u64 v[234:235], s[14:15], 0, v[0:1]
	global_load_lds_dwordx4 v[174:175], off
	s_add_i32 m0, s55, 0x2000
	s_nop 0
	global_load_lds_dwordx4 v[234:235], off
	s_barrier
	s_waitcnt lgkmcnt(0)
	v_mfma_f32_16x16x32_bf16 v[136:139], v[218:221], v[170:173], v[136:139]
	v_mfma_f32_16x16x32_bf16 v[132:135], v[226:229], v[170:173], v[132:135]
	v_mfma_f32_16x16x32_bf16 v[120:123], v[218:221], v[194:197], v[120:123]
	v_mfma_f32_16x16x32_bf16 v[116:119], v[226:229], v[194:197], v[116:119]
	v_mfma_f32_16x16x32_bf16 v[104:107], v[218:221], v[202:205], v[104:107]
	v_mfma_f32_16x16x32_bf16 v[100:103], v[226:229], v[202:205], v[100:103]
	v_mfma_f32_16x16x32_bf16 v[80:83], v[218:221], v[210:213], v[80:83]
	v_mfma_f32_16x16x32_bf16 v[76:79], v[226:229], v[210:213], v[76:79]
	v_mfma_f32_16x16x32_bf16 v[136:139], v[222:225], v[190:193], v[136:139]
	v_mfma_f32_16x16x32_bf16 v[132:135], v[230:233], v[190:193], v[132:135]
	v_mfma_f32_16x16x32_bf16 v[120:123], v[222:225], v[198:201], v[120:123]
	v_mfma_f32_16x16x32_bf16 v[116:119], v[230:233], v[198:201], v[116:119]
	v_mfma_f32_16x16x32_bf16 v[104:107], v[222:225], v[206:209], v[104:107]
	v_mfma_f32_16x16x32_bf16 v[100:103], v[230:233], v[206:209], v[100:103]
	v_mfma_f32_16x16x32_bf16 v[80:83], v[222:225], v[214:217], v[80:83]
	v_mfma_f32_16x16x32_bf16 v[76:79], v[230:233], v[214:217], v[76:79]
	s_mov_b32 m0, s39
	v_lshl_add_u64 v[236:237], s[18:19], 0, v[164:165]
	s_barrier
	ds_read_b128 v[170:173], v177 offset:16384
	ds_read_b128 v[190:193], v177 offset:17408
	ds_read_b128 v[194:197], v177 offset:18432
	ds_read_b128 v[198:201], v177 offset:19456
	ds_read_b128 v[202:205], v177 offset:20480
	ds_read_b128 v[206:209], v177 offset:21504
	ds_read_b128 v[210:213], v177 offset:22528
	ds_read_b128 v[214:217], v177 offset:23552
	global_load_lds_dwordx4 v[236:237], off
	v_lshl_add_u64 v[238:239], s[18:19], 0, v[162:163]
	s_mov_b32 m0, s40
	s_nop 0
	global_load_lds_dwordx4 v[238:239], off
	s_barrier
	s_waitcnt lgkmcnt(0)
	v_mfma_f32_16x16x32_bf16 v[64:67], v[68:71], v[170:173], v[64:67]
	v_mfma_f32_16x16x32_bf16 v[60:63], v[84:87], v[170:173], v[60:63]
	v_mfma_f32_16x16x32_bf16 v[48:51], v[68:71], v[194:197], v[48:51]
	v_mfma_f32_16x16x32_bf16 v[44:47], v[84:87], v[194:197], v[44:47]
	v_mfma_f32_16x16x32_bf16 v[32:35], v[68:71], v[202:205], v[32:35]
	v_mfma_f32_16x16x32_bf16 v[28:31], v[84:87], v[202:205], v[28:31]
	v_mfma_f32_16x16x32_bf16 v[16:19], v[68:71], v[210:213], v[16:19]
	v_mfma_f32_16x16x32_bf16 v[12:15], v[84:87], v[210:213], v[12:15]
	v_mfma_f32_16x16x32_bf16 v[64:67], v[72:75], v[190:193], v[64:67]
	v_mfma_f32_16x16x32_bf16 v[60:63], v[88:91], v[190:193], v[60:63]
	v_mfma_f32_16x16x32_bf16 v[48:51], v[72:75], v[198:201], v[48:51]
	v_mfma_f32_16x16x32_bf16 v[44:47], v[88:91], v[198:201], v[44:47]
	v_mfma_f32_16x16x32_bf16 v[32:35], v[72:75], v[206:209], v[32:35]
	v_mfma_f32_16x16x32_bf16 v[28:31], v[88:91], v[206:209], v[28:31]
	v_mfma_f32_16x16x32_bf16 v[16:19], v[72:75], v[214:217], v[16:19]
	v_mfma_f32_16x16x32_bf16 v[12:15], v[88:91], v[214:217], v[12:15]
	s_barrier
; #define PG8_STAGE(bufoff, gbase, voff) do { _Pragma("unroll") for (int _i = 0; _i < 2; ++_i) \
;         __builtin_amdgcn_global_load_lds((const unsigned*)((const char*)(gbase) + (voff)[_i]), (LAS unsigned*)(lds + (bufoff) + ldsw + _i * 8192), 16, 0, 0); } while (0)
; #define PG8_LDA(dst, b, h) do { _Pragma("unroll") for (int m = 0; m < 4; ++m) _Pragma("unroll") for (int k = 0; k < 2; ++k) dst[m][k] = *(const LAS h8*)(lds + PG8_SA(b, h) + aoff + m * 2048 + k * 1024); } while (0)
; #define PG8_LDB(dst, b, h) do { _Pragma("unroll") for (int n = 0; n < 2; ++n) _Pragma("unroll") for (int k = 0; k < 2; ++k) dst[n][k] = *(const LAS h8*)(lds + PG8_SB(b, h) + boff + n * 2048 + k * 1024); } while (0)
; #define PG8_WAIT_V(n) asm volatile("s_waitcnt vmcnt(" #n ")" ::: "memory")
; #define PG8_WAIT_L(n) asm volatile("s_waitcnt lgkmcnt(" #n ")" ::: "memory")
; #define PG8_BAR __builtin_amdgcn_s_barrier()
; #define PG8_SCHED __builtin_amdgcn_sched_barrier(0)
; template <class Epi>
; __device__ __forceinline__ void gemm_phase(LAS unsigned char* lds, const Gemm g, const StaticOrder& S, const Epi& E, const int tid) {
;     ...
;             PG8_STAGE(PG8_SB(0, 1), b2 + hstepB, voffB);
;             PG8_WAIT_V(6); PG8_BAR; PG8_MMA(1, 1, At, B1); PG8_BAR;
;             PG8_LDB(B0, 1, 0); PG8_SCHED; PG8_LDA(At, 1, 0); PG8_STAGE(PG8_SA(0, 1), a2 + hstep, voffA);
;             PG8_WAIT_L(8); PG8_BAR; PG8_WAIT_L(0); PG8_MMA(0, 0, At, B0); PG8_BAR; PG8_SCHED;
;             PG8_LDB(B1, 1, 1); PG8_STAGE(PG8_SB(1, 0), b3, voffB);
;             PG8_BAR; PG8_WAIT_L(0); PG8_MMA(0, 1, At, B1); PG8_BAR;
;             PG8_LDA(At, 1, 1); PG8_STAGE(PG8_SA(1, 0), a3, voffA);
	s_add_u32 s56, s14, 0x80000
	s_addc_u32 s57, s15, 0
	s_add_i32 s55, s58, s38
	v_lshl_add_u64 v[68:69], s[56:57], 0, v[2:3]
	s_mov_b32 m0, s55
	s_nop 0
	global_load_lds_dwordx4 v[68:69], off
	v_lshl_add_u64 v[68:69], s[56:57], 0, v[0:1]
	s_add_i32 m0, s55, 0x2000
	s_nop 0
	global_load_lds_dwordx4 v[68:69], off
	s_waitcnt vmcnt(6)
	s_barrier
	v_mfma_f32_16x16x32_bf16 v[56:59], v[218:221], v[170:173], v[56:59]
	v_mfma_f32_16x16x32_bf16 v[52:55], v[226:229], v[170:173], v[52:55]
	v_mfma_f32_16x16x32_bf16 v[40:43], v[218:221], v[194:197], v[40:43]
	v_mfma_f32_16x16x32_bf16 v[36:39], v[226:229], v[194:197], v[36:39]
	v_mfma_f32_16x16x32_bf16 v[24:27], v[218:221], v[202:205], v[24:27]
	v_mfma_f32_16x16x32_bf16 v[20:23], v[226:229], v[202:205], v[20:23]
	v_mfma_f32_16x16x32_bf16 v[8:11], v[218:221], v[210:213], v[8:11]
	v_mfma_f32_16x16x32_bf16 v[4:7], v[226:229], v[210:213], v[4:7]
	v_mfma_f32_16x16x32_bf16 v[56:59], v[222:225], v[190:193], v[56:59]
	v_mfma_f32_16x16x32_bf16 v[52:55], v[230:233], v[190:193], v[52:55]
	v_mfma_f32_16x16x32_bf16 v[40:43], v[222:225], v[198:201], v[40:43]
	v_mfma_f32_16x16x32_bf16 v[36:39], v[230:233], v[198:201], v[36:39]
	v_mfma_f32_16x16x32_bf16 v[24:27], v[222:225], v[206:209], v[24:27]
	v_mfma_f32_16x16x32_bf16 v[20:23], v[230:233], v[206:209], v[20:23]
	v_mfma_f32_16x16x32_bf16 v[8:11], v[222:225], v[214:217], v[8:11]
	v_mfma_f32_16x16x32_bf16 v[4:7], v[230:233], v[214:217], v[4:7]
	s_add_i32 s55, 0, 0x18000
	v_add_u32_e32 v88, s55, v176
	s_barrier
	ds_read_b128 v[68:71], v88
	ds_read_b128 v[72:75], v88 offset:1024
	ds_read_b128 v[84:87], v88 offset:2048
	ds_read_b128 v[88:91], v88 offset:3072
	s_add_u32 s18, s18, 0x80000
	s_addc_u32 s19, s19, 0
	s_mov_b32 m0, s41
	v_lshl_add_u64 v[218:219], s[18:19], 0, v[164:165]
	ds_read_b128 v[170:173], v177 offset:32768
	ds_read_b128 v[190:193], v177 offset:33792
	ds_read_b128 v[194:197], v177 offset:34816
	ds_read_b128 v[198:201], v177 offset:35840
	ds_read_b128 v[202:205], v177 offset:36864
	ds_read_b128 v[206:209], v177 offset:37888
	ds_read_b128 v[210:213], v177 offset:38912
	ds_read_b128 v[214:217], v177 offset:39936
	global_load_lds_dwordx4 v[218:219], off
	v_lshl_add_u64 v[218:219], s[18:19], 0, v[162:163]
	s_mov_b32 m0, s42
	s_nop 0
	global_load_lds_dwordx4 v[218:219], off
	s_waitcnt lgkmcnt(8)
	s_barrier
	s_waitcnt lgkmcnt(0)
	v_mfma_f32_16x16x32_bf16 v[144:147], v[68:71], v[170:173], v[144:147]
	v_mfma_f32_16x16x32_bf16 v[140:143], v[84:87], v[170:173], v[140:143]
	v_mfma_f32_16x16x32_bf16 v[128:131], v[68:71], v[194:197], v[128:131]
	v_mfma_f32_16x16x32_bf16 v[124:127], v[84:87], v[194:197], v[124:127]
	v_mfma_f32_16x16x32_bf16 v[112:115], v[68:71], v[202:205], v[112:115]
	v_mfma_f32_16x16x32_bf16 v[108:111], v[84:87], v[202:205], v[108:111]
	v_mfma_f32_16x16x32_bf16 v[96:99], v[68:71], v[210:213], v[96:99]
	v_mfma_f32_16x16x32_bf16 v[92:95], v[84:87], v[210:213], v[92:95]
	v_mfma_f32_16x16x32_bf16 v[144:147], v[72:75], v[190:193], v[144:147]
	v_mfma_f32_16x16x32_bf16 v[140:143], v[88:91], v[190:193], v[140:143]
	v_mfma_f32_16x16x32_bf16 v[128:131], v[72:75], v[198:201], v[128:131]
	v_mfma_f32_16x16x32_bf16 v[124:127], v[88:91], v[198:201], v[124:127]
	v_mfma_f32_16x16x32_bf16 v[112:115], v[72:75], v[206:209], v[112:115]
	v_mfma_f32_16x16x32_bf16 v[108:111], v[88:91], v[206:209], v[108:111]
	v_mfma_f32_16x16x32_bf16 v[96:99], v[72:75], v[214:217], v[96:99]
	v_mfma_f32_16x16x32_bf16 v[92:95], v[88:91], v[214:217], v[92:95]
	s_barrier
	s_add_i32 s18, 0, 0x1c000
	s_add_i32 s19, s55, s38
	v_add_u32_e32 v178, s18, v176
	v_lshl_add_u64 v[174:175], v[174:175], 0, s[30:31]
	s_mov_b32 m0, s19
	ds_read_b128 v[218:221], v178
	ds_read_b128 v[222:225], v178 offset:1024
	ds_read_b128 v[226:229], v178 offset:2048
	ds_read_b128 v[230:233], v178 offset:3072
	global_load_lds_dwordx4 v[174:175], off
	v_lshl_add_u64 v[174:175], v[234:235], 0, s[30:31]
	s_add_i32 m0, s19, 0x2000
	s_nop 0
	global_load_lds_dwordx4 v[174:175], off
	s_barrier
	s_waitcnt lgkmcnt(0)
	v_mfma_f32_16x16x32_bf16 v[136:139], v[218:221], v[170:173], v[136:139]
	v_mfma_f32_16x16x32_bf16 v[132:135], v[226:229], v[170:173], v[132:135]
	v_mfma_f32_16x16x32_bf16 v[120:123], v[218:221], v[194:197], v[120:123]
	v_mfma_f32_16x16x32_bf16 v[116:119], v[226:229], v[194:197], v[116:119]
	v_mfma_f32_16x16x32_bf16 v[104:107], v[218:221], v[202:205], v[104:107]
	v_mfma_f32_16x16x32_bf16 v[100:103], v[226:229], v[202:205], v[100:103]
	v_mfma_f32_16x16x32_bf16 v[80:83], v[218:221], v[210:213], v[80:83]
	v_mfma_f32_16x16x32_bf16 v[76:79], v[226:229], v[210:213], v[76:79]
	v_mfma_f32_16x16x32_bf16 v[136:139], v[222:225], v[190:193], v[136:139]
	v_mfma_f32_16x16x32_bf16 v[132:135], v[230:233], v[190:193], v[132:135]
	v_mfma_f32_16x16x32_bf16 v[120:123], v[222:225], v[198:201], v[120:123]
	v_mfma_f32_16x16x32_bf16 v[116:119], v[230:233], v[198:201], v[116:119]
	v_mfma_f32_16x16x32_bf16 v[104:107], v[222:225], v[206:209], v[104:107]
	v_mfma_f32_16x16x32_bf16 v[100:103], v[230:233], v[206:209], v[100:103]
	v_mfma_f32_16x16x32_bf16 v[80:83], v[222:225], v[214:217], v[80:83]
	v_mfma_f32_16x16x32_bf16 v[76:79], v[230:233], v[214:217], v[76:79]
	s_mov_b32 m0, s43
	v_lshl_add_u64 v[174:175], v[236:237], 0, s[30:31]
	s_barrier
	ds_read_b128 v[170:173], v177 offset:49152
	ds_read_b128 v[190:193], v177 offset:50176
	ds_read_b128 v[194:197], v177 offset:51200
	ds_read_b128 v[198:201], v177 offset:52224
	ds_read_b128 v[202:205], v177 offset:53248
	ds_read_b128 v[206:209], v177 offset:54272
	ds_read_b128 v[210:213], v177 offset:55296
	ds_read_b128 v[214:217], v177 offset:56320
	global_load_lds_dwordx4 v[174:175], off
	v_lshl_add_u64 v[174:175], v[238:239], 0, s[30:31]
	s_mov_b32 m0, s46
	s_nop 0
	global_load_lds_dwordx4 v[174:175], off
	s_barrier
; #define PG8_STAGE(bufoff, gbase, voff) do { _Pragma("unroll") for (int _i = 0; _i < 2; ++_i) \
;         __builtin_amdgcn_global_load_lds((const unsigned*)((const char*)(gbase) + (voff)[_i]), (LAS unsigned*)(lds + (bufoff) + ldsw + _i * 8192), 16, 0, 0); } while (0)
; #define PG8_WAIT_V(n) asm volatile("s_waitcnt vmcnt(" #n ")" ::: "memory")
; #define PG8_WAIT_L(n) asm volatile("s_waitcnt lgkmcnt(" #n ")" ::: "memory")
; template <class Epi>
; __device__ __forceinline__ void gemm_phase(LAS unsigned char* lds, const Gemm g, const StaticOrder& S, const Epi& E, const int tid) {
;     ...
;             PG8_BAR; PG8_WAIT_L(0); PG8_MMA(1, 0, At, B0); PG8_BAR; PG8_SCHED;
;             PG8_STAGE(PG8_SB(1, 1), b3 + hstepB, voffB);
;             PG8_WAIT_V(6); PG8_BAR; PG8_MMA(1, 1, At, B1); PG8_BAR;
;         }
;         E(acc, cur, wr, wc, fr, fq);
;     __device__ __forceinline__ void operator()(const f32x4 (&acc)[2][2][4][2], const pg8::Unit& u, int wr, int wc, int fr, int fq) const {
;         const int row0 = u.pm * 256 + wr * 64 + fr, col0 = u.pn * 256 + wc * 32 + 8 * fq;
;         const float* gp = gate + (size_t)((u.pm * 256) >> 12) * 6144 + col0;
;         f32x4 gv[2][2];
; #pragma unroll
;         for (int bj = 0; bj < 2; ++bj)
; #pragma unroll
;             for (int n = 0; n < 2; ++n) gv[bj][n] = *(const f32x4*)(gp + bj * 128 + 4 * n);
; #pragma unroll
;         for (int ai = 0; ai < 2; ++ai)
; #pragma unroll
;             for (int m = 0; m < 4; ++m) { const size_t ro = (size_t)(row0 + ai * 128 + m * 16) * DM + col0;
; #pragma unroll
;                 for (int bj = 0; bj < 2; ++bj) {
;                     f32x4 x0, x1;
;                     if (XF32) { x0 = *(const f32x4*)(xin + ro + bj * 128); x1 = *(const f32x4*)(xin + ro + bj * 128 + 4); }
;                     else { const h8 xh = *(const h8*)(H + ro + bj * 128); x0 = (f32x4){(float)xh[0], (float)xh[1], (float)xh[2], (float)xh[3]}; x1 = (f32x4){(float)xh[4], (float)xh[5], (float)xh[6], (float)xh[7]}; }
;                     const f32x4 y0 = x0 + gv[bj][0] * acc[ai][bj][m][0], y1 = x1 + gv[bj][1] * acc[ai][bj][m][1];
;                     h8 o; o[0] = (half_t)y0[0]; o[1] = (half_t)y0[1]; o[2] = (half_t)y0[2]; o[3] = (half_t)y0[3]; o[4] = (half_t)y1[0]; o[5] = (half_t)y1[1]; o[6] = (half_t)y1[2]; o[7] = (half_t)y1[3];
;                     *(h8*)(H + ro + bj * 128) = o; } }
	s_waitcnt lgkmcnt(0)
	v_mfma_f32_16x16x32_bf16 v[64:67], v[68:71], v[170:173], v[64:67]
	v_mfma_f32_16x16x32_bf16 v[60:63], v[84:87], v[170:173], v[60:63]
	v_mfma_f32_16x16x32_bf16 v[48:51], v[68:71], v[194:197], v[48:51]
	v_mfma_f32_16x16x32_bf16 v[44:47], v[84:87], v[194:197], v[44:47]
	v_mfma_f32_16x16x32_bf16 v[32:35], v[68:71], v[202:205], v[32:35]
	v_mfma_f32_16x16x32_bf16 v[28:31], v[84:87], v[202:205], v[28:31]
	v_mfma_f32_16x16x32_bf16 v[16:19], v[68:71], v[210:213], v[16:19]
	v_mfma_f32_16x16x32_bf16 v[12:15], v[84:87], v[210:213], v[12:15]
	v_mfma_f32_16x16x32_bf16 v[64:67], v[72:75], v[190:193], v[64:67]
	v_mfma_f32_16x16x32_bf16 v[60:63], v[88:91], v[190:193], v[60:63]
	v_mfma_f32_16x16x32_bf16 v[48:51], v[72:75], v[198:201], v[48:51]
	v_mfma_f32_16x16x32_bf16 v[44:47], v[88:91], v[198:201], v[44:47]
	v_mfma_f32_16x16x32_bf16 v[32:35], v[72:75], v[206:209], v[32:35]
	v_mfma_f32_16x16x32_bf16 v[28:31], v[88:91], v[206:209], v[28:31]
	v_mfma_f32_16x16x32_bf16 v[16:19], v[72:75], v[214:217], v[16:19]
	v_mfma_f32_16x16x32_bf16 v[12:15], v[88:91], v[214:217], v[12:15]
	s_barrier
	s_add_u32 s14, s14, 0x80080
	s_addc_u32 s15, s15, 0
	s_add_i32 s18, s18, s38
	v_lshl_add_u64 v[68:69], s[14:15], 0, v[2:3]
	s_mov_b32 m0, s18
	s_nop 0
	global_load_lds_dwordx4 v[68:69], off
	v_lshl_add_u64 v[68:69], s[14:15], 0, v[0:1]
	s_add_i32 m0, s18, 0x2000
	s_nop 0
	global_load_lds_dwordx4 v[68:69], off
	s_waitcnt vmcnt(6)
	s_barrier
	v_mfma_f32_16x16x32_bf16 v[56:59], v[218:221], v[170:173], v[56:59]
	v_mfma_f32_16x16x32_bf16 v[52:55], v[226:229], v[170:173], v[52:55]
	v_mfma_f32_16x16x32_bf16 v[40:43], v[218:221], v[194:197], v[40:43]
	v_mfma_f32_16x16x32_bf16 v[36:39], v[226:229], v[194:197], v[36:39]
	v_mfma_f32_16x16x32_bf16 v[24:27], v[218:221], v[202:205], v[24:27]
	v_mfma_f32_16x16x32_bf16 v[20:23], v[226:229], v[202:205], v[20:23]
	v_mfma_f32_16x16x32_bf16 v[8:11], v[218:221], v[210:213], v[8:11]
	v_mfma_f32_16x16x32_bf16 v[4:7], v[226:229], v[210:213], v[4:7]
	v_mfma_f32_16x16x32_bf16 v[56:59], v[222:225], v[190:193], v[56:59]
	v_mfma_f32_16x16x32_bf16 v[52:55], v[230:233], v[190:193], v[52:55]
	v_mfma_f32_16x16x32_bf16 v[40:43], v[222:225], v[198:201], v[40:43]
	v_mfma_f32_16x16x32_bf16 v[36:39], v[230:233], v[198:201], v[36:39]
	v_mfma_f32_16x16x32_bf16 v[24:27], v[222:225], v[206:209], v[24:27]
	v_mfma_f32_16x16x32_bf16 v[20:23], v[230:233], v[206:209], v[20:23]
	v_mfma_f32_16x16x32_bf16 v[8:11], v[222:225], v[214:217], v[8:11]
	v_mfma_f32_16x16x32_bf16 v[4:7], v[230:233], v[214:217], v[4:7]
	s_add_i32 s54, s54, 2
	s_add_u32 s12, s12, 0x100
	s_addc_u32 s13, s13, 0
	s_add_u32 s52, s52, 0x100
	s_addc_u32 s53, s53, 0
	s_cmp_gt_u32 s54, 29
	s_barrier
	s_cbranch_scc0 .LBB0_678
	s_ashr_i32 s1, s48, 4
	v_lshl_add_u32 v174, s48, 8, v179
	v_lshl_or_b32 v172, s49, 8, v157
	s_mul_hi_i32 s7, s1, 0x6000
	s_mulk_i32 s1, 0x6000
	v_ashrrev_i32_e32 v175, 31, v174
	s_add_u32 s12, s23, s1
	v_ashrrev_i32_e32 v173, 31, v172
	v_lshlrev_b64 v[170:171], 11, v[174:175]
	s_addc_u32 s13, s24, s7
	v_lshl_add_u64 v[170:171], v[170:171], 0, v[172:173]
	v_lshl_add_u64 v[72:73], v[172:173], 2, s[12:13]
	v_lshl_add_u64 v[198:199], v[170:171], 2, s[80:81]
	global_load_dwordx4 v[84:87], v[72:73], off offset:16
	global_load_dwordx4 v[88:91], v[72:73], off
	global_load_dwordx4 v[68:71], v[72:73], off offset:528
	s_nop 0
	global_load_dwordx4 v[72:75], v[72:73], off offset:512
	s_mov_b64 s[98:99], 0x0
	v_lshl_add_u64 v[248:249], v[198:199], 0, s[98:99]
	global_load_dwordx4 v[200:203], v[248:249], off offset:16
	global_load_dwordx4 v[204:207], v[248:249], off
	s_mov_b64 s[98:99], 0x0
	v_lshl_add_u64 v[248:249], v[198:199], 0, s[98:99]
	global_load_dwordx4 v[208:211], v[248:249], off offset:528
	global_load_dwordx4 v[212:215], v[248:249], off offset:512
	s_mov_b64 s[98:99], 0x20000
	v_lshl_add_u64 v[248:249], v[198:199], 0, s[98:99]
	global_load_dwordx4 v[216:219], v[248:249], off offset:16
	global_load_dwordx4 v[220:223], v[248:249], off
	s_mov_b64 s[98:99], 0x20000
	v_lshl_add_u64 v[248:249], v[198:199], 0, s[98:99]
	global_load_dwordx4 v[224:227], v[248:249], off offset:528
	global_load_dwordx4 v[228:231], v[248:249], off offset:512
	s_mov_b64 s[98:99], 0x40000
	v_lshl_add_u64 v[248:249], v[198:199], 0, s[98:99]
	global_load_dwordx4 v[232:235], v[248:249], off offset:16
	global_load_dwordx4 v[236:239], v[248:249], off
	s_mov_b64 s[98:99], 0x40000
	v_lshl_add_u64 v[248:249], v[198:199], 0, s[98:99]
	global_load_dwordx4 v[240:243], v[248:249], off offset:528
	global_load_dwordx4 v[244:247], v[248:249], off offset:512
	s_nop 0
	s_nop 1
	s_waitcnt vmcnt(10)
	v_mov_b32_e32 v190, v200
	v_mov_b32_e32 v191, v201
	v_mov_b32_e32 v192, v202
	v_mov_b32_e32 v193, v203
	s_nop 1
	v_mov_b32_e32 v194, v204
	v_mov_b32_e32 v195, v205
	v_mov_b32_e32 v196, v206
	v_mov_b32_e32 v197, v207
	s_mov_b64 s[98:99], 0x60000
	v_lshl_add_u64 v[248:249], v[198:199], 0, s[98:99]
	global_load_dwordx4 v[200:203], v[248:249], off offset:16
	global_load_dwordx4 v[204:207], v[248:249], off
	s_mov_b64 s[12:13], 0x40000
	s_and_b64 vcc, exec, s[4:5]
	s_mov_b32 s49, s0
	s_mov_b32 s48, s6
	s_mov_b64 s[14:15], s[10:11]
	s_nop 0
	v_pk_fma_f32 v[142:143], v[142:143], v[86:87], v[192:193]
	v_pk_fma_f32 v[146:147], v[146:147], v[90:91], v[196:197]
	v_pk_fma_f32 v[144:145], v[144:145], v[88:89], v[194:195]
	v_pk_fma_f32 v[190:191], v[140:141], v[84:85], v[190:191]
	v_cvt_pk_f16_f32 v143, v142, v143
	v_cvt_pk_f16_f32 v141, v146, v147
	v_cvt_pk_f16_f32 v142, v190, v191
	v_cvt_pk_f16_f32 v140, v144, v145
	v_lshl_add_u64 v[190:191], v[170:171], 1, s[16:17]
	global_store_dwordx4 v[190:191], v[140:143], off
	s_nop 1
	s_waitcnt vmcnt(10)
;     __device__ __forceinline__ void operator()(const f32x4 (&acc)[2][2][4][2], const pg8::Unit& u, int wr, int wc, int fr, int fq) const {
;     ...
;         for (int ai = 0; ai < 2; ++ai)
; #pragma unroll
;             for (int m = 0; m < 4; ++m) { const size_t ro = (size_t)(row0 + ai * 128 + m * 16) * DM + col0;
; #pragma unroll
;                 for (int bj = 0; bj < 2; ++bj) {
;                     f32x4 x0, x1;
;                     if (XF32) { x0 = *(const f32x4*)(xin + ro + bj * 128); x1 = *(const f32x4*)(xin + ro + bj * 128 + 4); }
;                     else { const h8 xh = *(const h8*)(H + ro + bj * 128); x0 = (f32x4){(float)xh[0], (float)xh[1], (float)xh[2], (float)xh[3]}; x1 = (f32x4){(float)xh[4], (float)xh[5], (float)xh[6], (float)xh[7]}; }
;                     const f32x4 y0 = x0 + gv[bj][0] * acc[ai][bj][m][0], y1 = x1 + gv[bj][1] * acc[ai][bj][m][1];
;                     h8 o; o[0] = (half_t)y0[0]; o[1] = (half_t)y0[1]; o[2] = (half_t)y0[2]; o[3] = (half_t)y0[3]; o[4] = (half_t)y1[0]; o[5] = (half_t)y1[1]; o[6] = (half_t)y1[2]; o[7] = (half_t)y1[3];
;                     *(h8*)(H + ro + bj * 128) = o; } }
	v_mov_b32_e32 v140, v208
	v_mov_b32_e32 v141, v209
	v_mov_b32_e32 v142, v210
	v_mov_b32_e32 v143, v211
	s_nop 0
	s_nop 1
	v_mov_b32_e32 v144, v212
	v_mov_b32_e32 v145, v213
	v_mov_b32_e32 v146, v214
	v_mov_b32_e32 v147, v215
	s_mov_b64 s[98:99], 0x60000
	v_lshl_add_u64 v[248:249], v[198:199], 0, s[98:99]
	global_load_dwordx4 v[208:211], v[248:249], off offset:528
	global_load_dwordx4 v[212:215], v[248:249], off offset:512
	s_nop 0
	v_pk_fma_f32 v[134:135], v[134:135], v[70:71], v[142:143]
	v_pk_fma_f32 v[138:139], v[138:139], v[74:75], v[146:147]
	v_pk_fma_f32 v[136:137], v[136:137], v[72:73], v[144:145]
	v_pk_fma_f32 v[140:141], v[132:133], v[68:69], v[140:141]
	v_cvt_pk_f16_f32 v135, v134, v135
	v_cvt_pk_f16_f32 v133, v138, v139
	v_cvt_pk_f16_f32 v134, v140, v141
	v_cvt_pk_f16_f32 v132, v136, v137
	global_store_dwordx4 v[190:191], v[132:135], off offset:256
	s_nop 1
	v_or_b32_e32 v132, 16, v174
	v_ashrrev_i32_e32 v133, 31, v132
	v_lshlrev_b64 v[132:133], 11, v[132:133]
	v_lshl_add_u64 v[140:141], v[132:133], 0, v[172:173]
	v_lshl_add_u64 v[142:143], v[140:141], 2, s[80:81]
	s_nop 1
	s_waitcnt vmcnt(10)
	v_mov_b32_e32 v132, v216
	v_mov_b32_e32 v133, v217
	v_mov_b32_e32 v134, v218
	v_mov_b32_e32 v135, v219
	s_nop 1
	v_mov_b32_e32 v136, v220
	v_mov_b32_e32 v137, v221
	v_mov_b32_e32 v138, v222
	v_mov_b32_e32 v139, v223
	s_mov_b64 s[98:99], 0x100000
	v_lshl_add_u64 v[248:249], v[198:199], 0, s[98:99]
	global_load_dwordx4 v[216:219], v[248:249], off offset:16
	global_load_dwordx4 v[220:223], v[248:249], off
	s_nop 0
	v_pk_fma_f32 v[126:127], v[126:127], v[86:87], v[134:135]
	v_pk_fma_f32 v[130:131], v[130:131], v[90:91], v[138:139]
	v_pk_fma_f32 v[128:129], v[128:129], v[88:89], v[136:137]
	v_pk_fma_f32 v[132:133], v[124:125], v[84:85], v[132:133]
	v_cvt_pk_f16_f32 v127, v126, v127
	v_cvt_pk_f16_f32 v125, v130, v131
	v_cvt_pk_f16_f32 v126, v132, v133
	v_cvt_pk_f16_f32 v124, v128, v129
	v_lshl_add_u64 v[132:133], v[140:141], 1, s[16:17]
	global_store_dwordx4 v[132:133], v[124:127], off
	s_nop 1
	s_waitcnt vmcnt(10)
	v_mov_b32_e32 v124, v224
	v_mov_b32_e32 v125, v225
	v_mov_b32_e32 v126, v226
	v_mov_b32_e32 v127, v227
	s_nop 0
	s_nop 1
	v_mov_b32_e32 v128, v228
	v_mov_b32_e32 v129, v229
	v_mov_b32_e32 v130, v230
	v_mov_b32_e32 v131, v231
	s_mov_b64 s[98:99], 0x100000
	v_lshl_add_u64 v[248:249], v[198:199], 0, s[98:99]
	global_load_dwordx4 v[224:227], v[248:249], off offset:528
	global_load_dwordx4 v[228:231], v[248:249], off offset:512
	s_nop 0
	v_pk_fma_f32 v[118:119], v[118:119], v[70:71], v[126:127]
	v_pk_fma_f32 v[122:123], v[122:123], v[74:75], v[130:131]
	v_pk_fma_f32 v[120:121], v[120:121], v[72:73], v[128:129]
	v_pk_fma_f32 v[124:125], v[116:117], v[68:69], v[124:125]
	v_cvt_pk_f16_f32 v119, v118, v119
	v_cvt_pk_f16_f32 v117, v122, v123
	v_cvt_pk_f16_f32 v118, v124, v125
	v_cvt_pk_f16_f32 v116, v120, v121
	global_store_dwordx4 v[132:133], v[116:119], off offset:256
	s_nop 1
	v_or_b32_e32 v116, 32, v174
	v_ashrrev_i32_e32 v117, 31, v116
	v_lshlrev_b64 v[116:117], 11, v[116:117]
	v_lshl_add_u64 v[124:125], v[116:117], 0, v[172:173]
	v_lshl_add_u64 v[126:127], v[124:125], 2, s[80:81]
	s_nop 1
	s_waitcnt vmcnt(10)
	v_mov_b32_e32 v116, v232
	v_mov_b32_e32 v117, v233
	v_mov_b32_e32 v118, v234
	v_mov_b32_e32 v119, v235
	s_nop 1
	v_mov_b32_e32 v120, v236
	v_mov_b32_e32 v121, v237
	v_mov_b32_e32 v122, v238
	v_mov_b32_e32 v123, v239
	s_mov_b64 s[98:99], 0x120000
	v_lshl_add_u64 v[248:249], v[198:199], 0, s[98:99]
	global_load_dwordx4 v[232:235], v[248:249], off offset:16
	global_load_dwordx4 v[236:239], v[248:249], off
	s_nop 0
	v_pk_fma_f32 v[110:111], v[110:111], v[86:87], v[118:119]
	v_pk_fma_f32 v[114:115], v[114:115], v[90:91], v[122:123]
	v_pk_fma_f32 v[112:113], v[112:113], v[88:89], v[120:121]
	v_pk_fma_f32 v[116:117], v[108:109], v[84:85], v[116:117]
	v_cvt_pk_f16_f32 v111, v110, v111
	v_cvt_pk_f16_f32 v109, v114, v115
	v_cvt_pk_f16_f32 v110, v116, v117
	v_cvt_pk_f16_f32 v108, v112, v113
	v_lshl_add_u64 v[116:117], v[124:125], 1, s[16:17]
	global_store_dwordx4 v[116:117], v[108:111], off
	s_nop 1
	s_waitcnt vmcnt(10)
	v_mov_b32_e32 v108, v240
	v_mov_b32_e32 v109, v241
	v_mov_b32_e32 v110, v242
	v_mov_b32_e32 v111, v243
	s_nop 0
	s_nop 1
	v_mov_b32_e32 v112, v244
	v_mov_b32_e32 v113, v245
	v_mov_b32_e32 v114, v246
	v_mov_b32_e32 v115, v247
	s_mov_b64 s[98:99], 0x120000
	v_lshl_add_u64 v[248:249], v[198:199], 0, s[98:99]
	global_load_dwordx4 v[240:243], v[248:249], off offset:528
	global_load_dwordx4 v[244:247], v[248:249], off offset:512
	s_nop 0
	v_pk_fma_f32 v[102:103], v[102:103], v[70:71], v[110:111]
	v_pk_fma_f32 v[106:107], v[106:107], v[74:75], v[114:115]
	v_pk_fma_f32 v[104:105], v[104:105], v[72:73], v[112:113]
	v_pk_fma_f32 v[108:109], v[100:101], v[68:69], v[108:109]
	v_cvt_pk_f16_f32 v103, v102, v103
	v_cvt_pk_f16_f32 v101, v106, v107
	v_cvt_pk_f16_f32 v102, v108, v109
	v_cvt_pk_f16_f32 v100, v104, v105
	global_store_dwordx4 v[116:117], v[100:103], off offset:256
	s_nop 1
	v_or_b32_e32 v100, 48, v174
	v_ashrrev_i32_e32 v101, 31, v100
	v_lshlrev_b64 v[100:101], 11, v[100:101]
	v_lshl_add_u64 v[108:109], v[100:101], 0, v[172:173]
	v_lshl_add_u64 v[110:111], v[108:109], 2, s[80:81]
	s_nop 1
	s_waitcnt vmcnt(10)
;     __device__ __forceinline__ void operator()(const f32x4 (&acc)[2][2][4][2], const pg8::Unit& u, int wr, int wc, int fr, int fq) const {
;     ...
;         for (int ai = 0; ai < 2; ++ai)
; #pragma unroll
;             for (int m = 0; m < 4; ++m) { const size_t ro = (size_t)(row0 + ai * 128 + m * 16) * DM + col0;
; #pragma unroll
;                 for (int bj = 0; bj < 2; ++bj) {
;                     f32x4 x0, x1;
;                     if (XF32) { x0 = *(const f32x4*)(xin + ro + bj * 128); x1 = *(const f32x4*)(xin + ro + bj * 128 + 4); }
;                     else { const h8 xh = *(const h8*)(H + ro + bj * 128); x0 = (f32x4){(float)xh[0], (float)xh[1], (float)xh[2], (float)xh[3]}; x1 = (f32x4){(float)xh[4], (float)xh[5], (float)xh[6], (float)xh[7]}; }
;                     const f32x4 y0 = x0 + gv[bj][0] * acc[ai][bj][m][0], y1 = x1 + gv[bj][1] * acc[ai][bj][m][1];
;                     h8 o; o[0] = (half_t)y0[0]; o[1] = (half_t)y0[1]; o[2] = (half_t)y0[2]; o[3] = (half_t)y0[3]; o[4] = (half_t)y1[0]; o[5] = (half_t)y1[1]; o[6] = (half_t)y1[2]; o[7] = (half_t)y1[3];
;                     *(h8*)(H + ro + bj * 128) = o; } }
	v_mov_b32_e32 v100, v200
	v_mov_b32_e32 v101, v201
	v_mov_b32_e32 v102, v202
	v_mov_b32_e32 v103, v203
	s_nop 1
	v_mov_b32_e32 v104, v204
	v_mov_b32_e32 v105, v205
	v_mov_b32_e32 v106, v206
	v_mov_b32_e32 v107, v207
	s_mov_b64 s[98:99], 0x140000
	v_lshl_add_u64 v[248:249], v[198:199], 0, s[98:99]
	global_load_dwordx4 v[200:203], v[248:249], off offset:16
	global_load_dwordx4 v[204:207], v[248:249], off
	s_nop 0
	v_pk_fma_f32 v[94:95], v[94:95], v[86:87], v[102:103]
	v_pk_fma_f32 v[98:99], v[98:99], v[90:91], v[106:107]
	v_pk_fma_f32 v[96:97], v[96:97], v[88:89], v[104:105]
	v_pk_fma_f32 v[100:101], v[92:93], v[84:85], v[100:101]
	v_cvt_pk_f16_f32 v95, v94, v95
	v_cvt_pk_f16_f32 v93, v98, v99
	v_cvt_pk_f16_f32 v94, v100, v101
	v_cvt_pk_f16_f32 v92, v96, v97
	v_lshl_add_u64 v[100:101], v[108:109], 1, s[16:17]
	global_store_dwordx4 v[100:101], v[92:95], off
	s_nop 1
	s_waitcnt vmcnt(10)
	v_mov_b32_e32 v92, v208
	v_mov_b32_e32 v93, v209
	v_mov_b32_e32 v94, v210
	v_mov_b32_e32 v95, v211
	s_nop 0
	s_nop 1
	v_mov_b32_e32 v96, v212
	v_mov_b32_e32 v97, v213
	v_mov_b32_e32 v98, v214
	v_mov_b32_e32 v99, v215
	s_mov_b64 s[98:99], 0x140000
	v_lshl_add_u64 v[248:249], v[198:199], 0, s[98:99]
	global_load_dwordx4 v[208:211], v[248:249], off offset:528
	global_load_dwordx4 v[212:215], v[248:249], off offset:512
	s_nop 0
	v_pk_fma_f32 v[78:79], v[78:79], v[70:71], v[94:95]
	v_pk_fma_f32 v[82:83], v[82:83], v[74:75], v[98:99]
	v_pk_fma_f32 v[80:81], v[80:81], v[72:73], v[96:97]
	v_pk_fma_f32 v[92:93], v[76:77], v[68:69], v[92:93]
	v_cvt_pk_f16_f32 v79, v78, v79
	v_cvt_pk_f16_f32 v77, v82, v83
	v_cvt_pk_f16_f32 v78, v92, v93
	v_cvt_pk_f16_f32 v76, v80, v81
	v_lshl_add_u64 v[92:93], v[170:171], 0, s[12:13]
	global_store_dwordx4 v[100:101], v[76:79], off offset:256
	v_lshl_add_u64 v[94:95], v[92:93], 2, s[80:81]
	s_nop 1
	s_waitcnt vmcnt(10)
	v_mov_b32_e32 v76, v216
	v_mov_b32_e32 v77, v217
	v_mov_b32_e32 v78, v218
	v_mov_b32_e32 v79, v219
	s_nop 1
	v_mov_b32_e32 v80, v220
	v_mov_b32_e32 v81, v221
	v_mov_b32_e32 v82, v222
	v_mov_b32_e32 v83, v223
	s_mov_b64 s[98:99], 0x160000
	v_lshl_add_u64 v[248:249], v[198:199], 0, s[98:99]
	global_load_dwordx4 v[216:219], v[248:249], off offset:16
	global_load_dwordx4 v[220:223], v[248:249], off
	s_mov_b64 s[12:13], 0x48000
	s_nop 0
	v_pk_fma_f32 v[62:63], v[62:63], v[86:87], v[78:79]
	v_pk_fma_f32 v[66:67], v[66:67], v[90:91], v[82:83]
	v_pk_fma_f32 v[64:65], v[64:65], v[88:89], v[80:81]
	v_pk_fma_f32 v[76:77], v[60:61], v[84:85], v[76:77]
	v_cvt_pk_f16_f32 v63, v62, v63
	v_cvt_pk_f16_f32 v61, v66, v67
	v_cvt_pk_f16_f32 v62, v76, v77
	v_cvt_pk_f16_f32 v60, v64, v65
	v_lshl_add_u64 v[76:77], v[92:93], 1, s[16:17]
	global_store_dwordx4 v[76:77], v[60:63], off
	s_nop 1
	s_waitcnt vmcnt(10)
	v_mov_b32_e32 v60, v224
	v_mov_b32_e32 v61, v225
	v_mov_b32_e32 v62, v226
	v_mov_b32_e32 v63, v227
	s_nop 0
	s_nop 1
	v_mov_b32_e32 v64, v228
	v_mov_b32_e32 v65, v229
	v_mov_b32_e32 v66, v230
	v_mov_b32_e32 v67, v231
	s_mov_b64 s[98:99], 0x160000
	v_lshl_add_u64 v[248:249], v[198:199], 0, s[98:99]
	global_load_dwordx4 v[224:227], v[248:249], off offset:528
	global_load_dwordx4 v[228:231], v[248:249], off offset:512
	s_nop 0
	v_pk_fma_f32 v[54:55], v[54:55], v[70:71], v[62:63]
	v_pk_fma_f32 v[58:59], v[58:59], v[74:75], v[66:67]
	v_pk_fma_f32 v[56:57], v[56:57], v[72:73], v[64:65]
	v_pk_fma_f32 v[60:61], v[52:53], v[68:69], v[60:61]
	v_cvt_pk_f16_f32 v55, v54, v55
	v_cvt_pk_f16_f32 v53, v58, v59
	v_cvt_pk_f16_f32 v54, v60, v61
	v_cvt_pk_f16_f32 v52, v56, v57
	v_lshl_add_u64 v[60:61], v[170:171], 0, s[12:13]
	global_store_dwordx4 v[76:77], v[52:55], off offset:256
	v_lshl_add_u64 v[62:63], v[60:61], 2, s[80:81]
	s_nop 1
	s_waitcnt vmcnt(10)
	v_mov_b32_e32 v52, v232
	v_mov_b32_e32 v53, v233
	v_mov_b32_e32 v54, v234
	v_mov_b32_e32 v55, v235
	s_nop 1
	v_mov_b32_e32 v56, v236
	v_mov_b32_e32 v57, v237
	v_mov_b32_e32 v58, v238
	v_mov_b32_e32 v59, v239
	s_mov_b64 s[12:13], 0x50000
	s_nop 0
	v_pk_fma_f32 v[46:47], v[46:47], v[86:87], v[54:55]
	v_pk_fma_f32 v[50:51], v[50:51], v[90:91], v[58:59]
	v_pk_fma_f32 v[48:49], v[48:49], v[88:89], v[56:57]
	v_pk_fma_f32 v[52:53], v[44:45], v[84:85], v[52:53]
	v_cvt_pk_f16_f32 v47, v46, v47
	v_cvt_pk_f16_f32 v45, v50, v51
	v_cvt_pk_f16_f32 v46, v52, v53
	v_cvt_pk_f16_f32 v44, v48, v49
	v_lshl_add_u64 v[52:53], v[60:61], 1, s[16:17]
	global_store_dwordx4 v[52:53], v[44:47], off
	s_nop 1
	s_waitcnt vmcnt(8)
; #define PG8_WAIT_V(n) asm volatile("s_waitcnt vmcnt(" #n ")" ::: "memory")
; #define PG8_BAR __builtin_amdgcn_s_barrier()
; template <class Epi>
; __device__ __forceinline__ void gemm_phase(LAS unsigned char* lds, const Gemm g, const StaticOrder& S, const Epi& E, const int tid) {
;     ...
;         if (!has_next) break;
; #pragma unroll
;         for (int a = 0; a < 2; ++a)
; #pragma unroll
;             for (int b = 0; b < 2; ++b)
; #pragma unroll
;                 for (int m = 0; m < 4; ++m)
; #pragma unroll
;                     for (int n = 0; n < 2; ++n) acc[a][b][m][n] = (f32x4){0.f, 0.f, 0.f, 0.f};
;         cur = nxt; cA = nA; cB = nB; ++ui;
;     }
;     PG8_WAIT_V(0);
;     if (wr == 0) PG8_BAR;
;     PG8_BAR;
;     __device__ __forceinline__ void operator()(const f32x4 (&acc)[2][2][4][2], const pg8::Unit& u, int wr, int wc, int fr, int fq) const {
;     ...
;         for (int ai = 0; ai < 2; ++ai)
; #pragma unroll
;             for (int m = 0; m < 4; ++m) { const size_t ro = (size_t)(row0 + ai * 128 + m * 16) * DM + col0;
; #pragma unroll
;                 for (int bj = 0; bj < 2; ++bj) {
;                     f32x4 x0, x1;
;                     if (XF32) { x0 = *(const f32x4*)(xin + ro + bj * 128); x1 = *(const f32x4*)(xin + ro + bj * 128 + 4); }
;                     else { const h8 xh = *(const h8*)(H + ro + bj * 128); x0 = (f32x4){(float)xh[0], (float)xh[1], (float)xh[2], (float)xh[3]}; x1 = (f32x4){(float)xh[4], (float)xh[5], (float)xh[6], (float)xh[7]}; }
;                     const f32x4 y0 = x0 + gv[bj][0] * acc[ai][bj][m][0], y1 = x1 + gv[bj][1] * acc[ai][bj][m][1];
;                     h8 o; o[0] = (half_t)y0[0]; o[1] = (half_t)y0[1]; o[2] = (half_t)y0[2]; o[3] = (half_t)y0[3]; o[4] = (half_t)y1[0]; o[5] = (half_t)y1[1]; o[6] = (half_t)y1[2]; o[7] = (half_t)y1[3];
;                     *(h8*)(H + ro + bj * 128) = o; } }
	v_mov_b32_e32 v44, v240
	v_mov_b32_e32 v45, v241
	v_mov_b32_e32 v46, v242
	v_mov_b32_e32 v47, v243
	s_nop 0
	s_nop 1
	v_mov_b32_e32 v48, v244
	v_mov_b32_e32 v49, v245
	v_mov_b32_e32 v50, v246
	v_mov_b32_e32 v51, v247
	s_nop 0
	v_pk_fma_f32 v[38:39], v[38:39], v[70:71], v[46:47]
	v_pk_fma_f32 v[42:43], v[42:43], v[74:75], v[50:51]
	v_pk_fma_f32 v[40:41], v[40:41], v[72:73], v[48:49]
	v_pk_fma_f32 v[44:45], v[36:37], v[68:69], v[44:45]
	v_cvt_pk_f16_f32 v39, v38, v39
	v_cvt_pk_f16_f32 v37, v42, v43
	v_cvt_pk_f16_f32 v38, v44, v45
	v_cvt_pk_f16_f32 v36, v40, v41
	v_lshl_add_u64 v[44:45], v[170:171], 0, s[12:13]
	global_store_dwordx4 v[52:53], v[36:39], off offset:256
	v_lshl_add_u64 v[46:47], v[44:45], 2, s[80:81]
	s_nop 1
	s_waitcnt vmcnt(6)
	v_mov_b32_e32 v36, v200
	v_mov_b32_e32 v37, v201
	v_mov_b32_e32 v38, v202
	v_mov_b32_e32 v39, v203
	s_nop 1
	v_mov_b32_e32 v40, v204
	v_mov_b32_e32 v41, v205
	v_mov_b32_e32 v42, v206
	v_mov_b32_e32 v43, v207
	s_mov_b64 s[12:13], 0x58000
	s_nop 0
	v_pk_fma_f32 v[30:31], v[30:31], v[86:87], v[38:39]
	v_pk_fma_f32 v[34:35], v[34:35], v[90:91], v[42:43]
	v_pk_fma_f32 v[32:33], v[32:33], v[88:89], v[40:41]
	v_pk_fma_f32 v[36:37], v[28:29], v[84:85], v[36:37]
	v_cvt_pk_f16_f32 v31, v30, v31
	v_cvt_pk_f16_f32 v29, v34, v35
	v_cvt_pk_f16_f32 v30, v36, v37
	v_cvt_pk_f16_f32 v28, v32, v33
	v_lshl_add_u64 v[36:37], v[44:45], 1, s[16:17]
	global_store_dwordx4 v[36:37], v[28:31], off
	s_nop 1
	s_waitcnt vmcnt(4)
	v_mov_b32_e32 v28, v208
	v_mov_b32_e32 v29, v209
	v_mov_b32_e32 v30, v210
	v_mov_b32_e32 v31, v211
	s_nop 0
	s_nop 1
	v_mov_b32_e32 v32, v212
	v_mov_b32_e32 v33, v213
	v_mov_b32_e32 v34, v214
	v_mov_b32_e32 v35, v215
	s_nop 0
	v_pk_fma_f32 v[22:23], v[22:23], v[70:71], v[30:31]
	v_pk_fma_f32 v[26:27], v[26:27], v[74:75], v[34:35]
	v_pk_fma_f32 v[24:25], v[24:25], v[72:73], v[32:33]
	v_pk_fma_f32 v[28:29], v[20:21], v[68:69], v[28:29]
	v_cvt_pk_f16_f32 v23, v22, v23
	v_cvt_pk_f16_f32 v21, v26, v27
	v_cvt_pk_f16_f32 v22, v28, v29
	v_cvt_pk_f16_f32 v20, v24, v25
	v_lshl_add_u64 v[28:29], v[170:171], 0, s[12:13]
	global_store_dwordx4 v[36:37], v[20:23], off offset:256
	v_lshl_add_u64 v[30:31], v[28:29], 2, s[80:81]
	s_nop 1
	s_waitcnt vmcnt(2)
	v_mov_b32_e32 v20, v216
	v_mov_b32_e32 v21, v217
	v_mov_b32_e32 v22, v218
	v_mov_b32_e32 v23, v219
	s_nop 1
	v_mov_b32_e32 v24, v220
	v_mov_b32_e32 v25, v221
	v_mov_b32_e32 v26, v222
	v_mov_b32_e32 v27, v223
	s_mov_b64 s[12:13], s[8:9]
	s_nop 0
	v_pk_fma_f32 v[14:15], v[14:15], v[86:87], v[22:23]
	v_pk_fma_f32 v[18:19], v[18:19], v[90:91], v[26:27]
	v_pk_fma_f32 v[16:17], v[16:17], v[88:89], v[24:25]
	v_pk_fma_f32 v[20:21], v[12:13], v[84:85], v[20:21]
	v_cvt_pk_f16_f32 v15, v14, v15
	v_cvt_pk_f16_f32 v13, v18, v19
	v_cvt_pk_f16_f32 v14, v20, v21
	v_cvt_pk_f16_f32 v12, v16, v17
	v_lshl_add_u64 v[20:21], v[28:29], 1, s[16:17]
	global_store_dwordx4 v[20:21], v[12:15], off
	s_nop 1
	s_waitcnt vmcnt(0)
	v_mov_b32_e32 v12, v224
	v_mov_b32_e32 v13, v225
	v_mov_b32_e32 v14, v226
	v_mov_b32_e32 v15, v227
	s_nop 0
	s_nop 1
	v_mov_b32_e32 v16, v228
	v_mov_b32_e32 v17, v229
	v_mov_b32_e32 v18, v230
	v_mov_b32_e32 v19, v231
	s_nop 0
	v_pk_fma_f32 v[6:7], v[6:7], v[70:71], v[14:15]
	v_pk_fma_f32 v[10:11], v[10:11], v[74:75], v[18:19]
	v_pk_fma_f32 v[8:9], v[8:9], v[72:73], v[16:17]
	v_pk_fma_f32 v[12:13], v[4:5], v[68:69], v[12:13]
	v_cvt_pk_f16_f32 v7, v6, v7
	v_cvt_pk_f16_f32 v5, v10, v11
	v_cvt_pk_f16_f32 v6, v12, v13
	v_cvt_pk_f16_f32 v4, v8, v9
	global_store_dwordx4 v[20:21], v[4:7], off offset:256
	s_cbranch_vccz .LBB0_671
	s_waitcnt vmcnt(0)
	v_readlane_b32 s42, v251, 7
	v_readlane_b32 s46, v251, 9
	v_readlane_b32 s48, v251, 13
	s_cmpk_gt_u32 s25, 0xff
	v_readlane_b32 s43, v251, 8
	v_readlane_b32 s47, v251, 10
	v_readlane_b32 s49, v251, 14
	s_cbranch_scc1 .LBB0_682
	s_barrier
